# leading GEMM half runs its epilogue at priority 1 (finishes first; its next-unit header + load segment overlap the trailing half's epilogue), on top of the early closing barrier
# baseline (speedup 1.0000x reference)
.Lmid_gemm0:
	s_add_i32 s18, 0, 0x18000
	s_add_i32 s19, 0, 0x1c000
	v_add_u32_e32 v158, s18, v145
	v_add_u32_e32 v174, s19, v145
	ds_read_b128 v[140:143], v158
	ds_read_b128 v[150:153], v158 offset:1024
	ds_read_b128 v[154:157], v158 offset:2048
	ds_read_b128 v[158:161], v158 offset:3072
	ds_read_b128 v[162:165], v174
	ds_read_b128 v[166:169], v174 offset:1024
	ds_read_b128 v[170:173], v174 offset:2048
	ds_read_b128 v[174:177], v174 offset:3072
	s_add_u32 s48, s48, 0x40000
	s_addc_u32 s49, s49, 0
	s_mov_b32 m0, s57
	v_lshl_add_u64 v[222:223], s[48:49], 0, v[130:131]
	ds_read_b128 v[184:187], v149 offset:32768
	ds_read_b128 v[188:191], v149 offset:33792
	ds_read_b128 v[192:195], v149 offset:34816
	ds_read_b128 v[196:199], v149 offset:35840
	ds_read_b128 v[200:203], v149 offset:36864
	ds_read_b128 v[204:207], v149 offset:37888
	ds_read_b128 v[208:211], v149 offset:38912
	ds_read_b128 v[212:215], v149 offset:39936
	global_load_lds_dwordx4 v[222:223], off
	v_lshl_add_u64 v[222:223], s[48:49], 0, v[128:129]
	s_mov_b32 m0, s58
	s_nop 0
	global_load_lds_dwordx4 v[222:223], off
	s_waitcnt vmcnt(8)
	s_waitcnt lgkmcnt(0)
	s_barrier
	s_waitcnt lgkmcnt(0)
	v_mfma_f32_16x16x32_bf16 v[124:127], v[140:143], v[184:187], v[124:127]
	v_mfma_f32_16x16x32_bf16 v[124:127], v[150:153], v[188:191], v[124:127]
	s_setprio 1
	v_mfma_f32_16x16x32_bf16 v[120:123], v[154:157], v[184:187], v[120:123]
	v_mfma_f32_16x16x32_bf16 v[120:123], v[158:161], v[188:191], v[120:123]
	v_mfma_f32_16x16x32_bf16 v[108:111], v[140:143], v[192:195], v[108:111]
	v_mfma_f32_16x16x32_bf16 v[108:111], v[150:153], v[196:199], v[108:111]
	v_mfma_f32_16x16x32_bf16 v[104:107], v[154:157], v[192:195], v[104:107]
	v_mfma_f32_16x16x32_bf16 v[104:107], v[158:161], v[196:199], v[104:107]
	v_mfma_f32_16x16x32_bf16 v[92:95], v[140:143], v[200:203], v[92:95]
	v_mfma_f32_16x16x32_bf16 v[92:95], v[150:153], v[204:207], v[92:95]
	v_mfma_f32_16x16x32_bf16 v[88:91], v[154:157], v[200:203], v[88:91]
	v_mfma_f32_16x16x32_bf16 v[88:91], v[158:161], v[204:207], v[88:91]
	v_mfma_f32_16x16x32_bf16 v[76:79], v[140:143], v[208:211], v[76:79]
	v_mfma_f32_16x16x32_bf16 v[76:79], v[150:153], v[212:215], v[76:79]
	v_mfma_f32_16x16x32_bf16 v[72:75], v[154:157], v[208:211], v[72:75]
	v_mfma_f32_16x16x32_bf16 v[72:75], v[158:161], v[212:215], v[72:75]
	v_mfma_f32_16x16x32_bf16 v[116:119], v[162:165], v[184:187], v[116:119]
	v_mfma_f32_16x16x32_bf16 v[116:119], v[166:169], v[188:191], v[116:119]
	v_mfma_f32_16x16x32_bf16 v[112:115], v[170:173], v[184:187], v[112:115]
	v_mfma_f32_16x16x32_bf16 v[112:115], v[174:177], v[188:191], v[112:115]
	v_mfma_f32_16x16x32_bf16 v[100:103], v[162:165], v[192:195], v[100:103]
	v_mfma_f32_16x16x32_bf16 v[100:103], v[166:169], v[196:199], v[100:103]
	v_mfma_f32_16x16x32_bf16 v[96:99], v[170:173], v[192:195], v[96:99]
	v_mfma_f32_16x16x32_bf16 v[96:99], v[174:177], v[196:199], v[96:99]
	v_mfma_f32_16x16x32_bf16 v[84:87], v[162:165], v[200:203], v[84:87]
	v_mfma_f32_16x16x32_bf16 v[84:87], v[166:169], v[204:207], v[84:87]
	v_mfma_f32_16x16x32_bf16 v[80:83], v[170:173], v[200:203], v[80:83]
	v_mfma_f32_16x16x32_bf16 v[80:83], v[174:177], v[204:207], v[80:83]
	v_mfma_f32_16x16x32_bf16 v[68:71], v[162:165], v[208:211], v[68:71]
	v_mfma_f32_16x16x32_bf16 v[68:71], v[166:169], v[212:215], v[68:71]
	s_barrier
	v_mfma_f32_16x16x32_bf16 v[64:67], v[170:173], v[208:211], v[64:67]
	v_mfma_f32_16x16x32_bf16 v[64:67], v[174:177], v[212:215], v[64:67]
	s_setprio 0
	s_add_i32 s18, s18, s54
	v_lshl_add_u64 v[178:179], v[178:179], 0, s[6:7]
	s_mov_b32 m0, s18
	ds_read_b128 v[184:187], v149 offset:49152
	ds_read_b128 v[188:191], v149 offset:50176
	ds_read_b128 v[192:195], v149 offset:51200
	ds_read_b128 v[196:199], v149 offset:52224
	ds_read_b128 v[200:203], v149 offset:53248
	ds_read_b128 v[204:207], v149 offset:54272
	ds_read_b128 v[208:211], v149 offset:55296
	ds_read_b128 v[212:215], v149 offset:56320
	global_load_lds_dwordx4 v[178:179], off
	s_add_i32 m0, s18, 0x2000
	s_add_u32 s46, s46, 0x40080
	v_lshl_add_u64 v[178:179], v[216:217], 0, s[6:7]
	s_addc_u32 s47, s47, 0
	s_add_i32 s18, s19, s54
	global_load_lds_dwordx4 v[178:179], off
	v_lshl_add_u64 v[178:179], s[46:47], 0, v[130:131]
	s_mov_b32 m0, s18
	s_nop 0
	global_load_lds_dwordx4 v[178:179], off
	v_lshl_add_u64 v[178:179], s[46:47], 0, v[128:129]
	s_add_i32 m0, s18, 0x2000
	s_nop 0
	global_load_lds_dwordx4 v[178:179], off
	v_lshl_add_u64 v[178:179], v[218:219], 0, s[6:7]
	s_mov_b32 m0, s60
	s_nop 0
	global_load_lds_dwordx4 v[178:179], off
	v_lshl_add_u64 v[178:179], v[220:221], 0, s[6:7]
	s_mov_b32 m0, s61
	s_nop 0
	global_load_lds_dwordx4 v[178:179], off
	s_waitcnt vmcnt(8)
	s_waitcnt lgkmcnt(0)
	s_barrier
	s_waitcnt lgkmcnt(0)
	v_mfma_f32_16x16x32_bf16 v[60:63], v[140:143], v[184:187], v[60:63]
	v_mfma_f32_16x16x32_bf16 v[60:63], v[150:153], v[188:191], v[60:63]
	s_setprio 1
	v_mfma_f32_16x16x32_bf16 v[56:59], v[154:157], v[184:187], v[56:59]
	v_mfma_f32_16x16x32_bf16 v[56:59], v[158:161], v[188:191], v[56:59]
	v_mfma_f32_16x16x32_bf16 v[44:47], v[140:143], v[192:195], v[44:47]
	v_mfma_f32_16x16x32_bf16 v[44:47], v[150:153], v[196:199], v[44:47]
	v_mfma_f32_16x16x32_bf16 v[40:43], v[154:157], v[192:195], v[40:43]
	v_mfma_f32_16x16x32_bf16 v[40:43], v[158:161], v[196:199], v[40:43]
	v_mfma_f32_16x16x32_bf16 v[28:31], v[140:143], v[200:203], v[28:31]
	v_mfma_f32_16x16x32_bf16 v[28:31], v[150:153], v[204:207], v[28:31]
	v_mfma_f32_16x16x32_bf16 v[24:27], v[154:157], v[200:203], v[24:27]
	v_mfma_f32_16x16x32_bf16 v[24:27], v[158:161], v[204:207], v[24:27]
	v_mfma_f32_16x16x32_bf16 v[12:15], v[140:143], v[208:211], v[12:15]
	v_mfma_f32_16x16x32_bf16 v[12:15], v[150:153], v[212:215], v[12:15]
	v_mfma_f32_16x16x32_bf16 v[8:11], v[154:157], v[208:211], v[8:11]
	v_mfma_f32_16x16x32_bf16 v[8:11], v[158:161], v[212:215], v[8:11]
	v_mfma_f32_16x16x32_bf16 v[52:55], v[162:165], v[184:187], v[52:55]
	v_mfma_f32_16x16x32_bf16 v[52:55], v[166:169], v[188:191], v[52:55]
	v_mfma_f32_16x16x32_bf16 v[48:51], v[170:173], v[184:187], v[48:51]
	v_mfma_f32_16x16x32_bf16 v[48:51], v[174:177], v[188:191], v[48:51]
	v_mfma_f32_16x16x32_bf16 v[36:39], v[162:165], v[192:195], v[36:39]
	v_mfma_f32_16x16x32_bf16 v[36:39], v[166:169], v[196:199], v[36:39]
	v_mfma_f32_16x16x32_bf16 v[32:35], v[170:173], v[192:195], v[32:35]
	v_mfma_f32_16x16x32_bf16 v[32:35], v[174:177], v[196:199], v[32:35]
	v_mfma_f32_16x16x32_bf16 v[20:23], v[162:165], v[200:203], v[20:23]
	v_mfma_f32_16x16x32_bf16 v[20:23], v[166:169], v[204:207], v[20:23]
	v_mfma_f32_16x16x32_bf16 v[16:19], v[170:173], v[200:203], v[16:19]
	v_mfma_f32_16x16x32_bf16 v[16:19], v[174:177], v[204:207], v[16:19]
	v_mfma_f32_16x16x32_bf16 v[4:7], v[162:165], v[208:211], v[4:7]
	v_mfma_f32_16x16x32_bf16 v[4:7], v[166:169], v[212:215], v[4:7]
	s_barrier
	v_mfma_f32_16x16x32_bf16 v[0:3], v[170:173], v[208:211], v[0:3]
	v_mfma_f32_16x16x32_bf16 v[0:3], v[174:177], v[212:215], v[0:3]
	s_setprio 0
	s_add_i32 s70, s70, 2
	s_add_u32 s44, s44, 0x100
	s_addc_u32 s45, s45, 0
	s_add_u32 s68, s68, 0x100
	s_addc_u32 s69, s69, 0
	s_cmp_gt_u32 s70, 13
	s_cbranch_scc0 .LBB0_184
	s_and_b64 vcc, exec, s[8:9]
	s_cbranch_vccz .LBB0_187
	s_barrier
	s_setprio 1
.LBB0_187:
	v_mul_f32_e32 v151, 0xbfb8aa3b, v124
	v_exp_f32_e32 v151, v151
	v_mul_f32_e32 v154, 0xbfb8aa3b, v125
	v_exp_f32_e32 v154, v154
	v_lshl_or_b32 v142, s65, 7, v146
	v_add_f32_e32 v151, 1.0, v151
	v_rcp_f32_e32 v151, v151
	v_lshl_add_u32 v150, s36, 8, v144
	v_ashrrev_i32_e32 v143, 31, v142
	v_mov_b64_e32 v[140:141], s[22:23]
	v_mul_f32_e32 v124, v124, v151
	v_mul_f32_e32 v120, v120, v124
	v_add_f32_e32 v124, 1.0, v154
	v_mul_f32_e32 v151, 0xbfb8aa3b, v126
	v_rcp_f32_e32 v124, v124
	v_exp_f32_e32 v151, v151
	v_mul_f32_e32 v154, 0xbfb8aa3b, v127
	v_exp_f32_e32 v154, v154
	v_mul_f32_e32 v124, v125, v124
	v_add_f32_e32 v125, 1.0, v151
	v_rcp_f32_e32 v125, v125
	v_add_f32_e32 v151, 1.0, v154
	v_rcp_f32_e32 v151, v151
	v_mul_f32_e32 v121, v121, v124
	v_mul_f32_e32 v124, v126, v125
	v_mul_f32_e32 v125, 0xbfb8aa3b, v116
	v_exp_f32_e32 v125, v125
	v_mul_f32_e32 v122, v122, v124
	v_mul_f32_e32 v124, v127, v151
	v_mul_f32_e32 v123, v123, v124
	v_cvt_pk_bf16_f32 v120, v120, v121
	v_cvt_pk_bf16_f32 v121, v122, v123
	v_add_f32_e32 v122, 1.0, v125
	v_rcp_f32_e32 v122, v122
	v_mul_f32_e32 v123, 0xbfb8aa3b, v117
	v_exp_f32_e32 v123, v123
	v_mad_i64_i32 v[152:153], s[44:45], v150, s64, v[140:141]
	v_lshlrev_b64 v[142:143], 1, v[142:143]
	v_lshl_add_u64 v[152:153], v[152:153], 0, v[142:143]
	v_mul_f32_e32 v116, v116, v122
	global_store_dwordx2 v[152:153], v[120:121], off
	v_mul_f32_e32 v112, v112, v116
	v_add_f32_e32 v116, 1.0, v123
	v_mul_f32_e32 v120, 0xbfb8aa3b, v118
	v_rcp_f32_e32 v116, v116
	v_exp_f32_e32 v120, v120
	v_mul_f32_e32 v121, 0xbfb8aa3b, v119
	v_exp_f32_e32 v121, v121
	v_mul_f32_e32 v116, v117, v116
	v_add_f32_e32 v117, 1.0, v120
	v_rcp_f32_e32 v117, v117
	v_add_f32_e32 v120, 1.0, v121
	v_rcp_f32_e32 v120, v120
	v_mul_f32_e32 v113, v113, v116
	v_mul_f32_e32 v116, v118, v117
	v_mul_f32_e32 v114, v114, v116
	v_mul_f32_e32 v116, v119, v120
	v_cvt_pk_bf16_f32 v112, v112, v113
	v_mul_f32_e32 v115, v115, v116
	v_cvt_pk_bf16_f32 v113, v114, v115
	global_store_dwordx2 v[152:153], v[112:113], off offset:128
	v_mul_f32_e32 v112, 0xbfb8aa3b, v108
	v_exp_f32_e32 v114, v112
	v_mul_f32_e32 v115, 0xbfb8aa3b, v109
	v_exp_f32_e32 v115, v115
	v_or_b32_e32 v112, 16, v150
	v_add_f32_e32 v114, 1.0, v114
	v_rcp_f32_e32 v114, v114
	v_mad_i64_i32 v[112:113], s[44:45], v112, s64, v[140:141]
	v_lshl_add_u64 v[112:113], v[112:113], 0, v[142:143]
	v_mul_f32_e32 v108, v108, v114
	v_mul_f32_e32 v104, v104, v108
	v_add_f32_e32 v108, 1.0, v115
	v_mul_f32_e32 v114, 0xbfb8aa3b, v110
	v_rcp_f32_e32 v108, v108
	v_exp_f32_e32 v114, v114
	v_mul_f32_e32 v115, 0xbfb8aa3b, v111
	v_exp_f32_e32 v115, v115
	v_mul_f32_e32 v108, v109, v108
	v_add_f32_e32 v109, 1.0, v114
	v_rcp_f32_e32 v109, v109
	v_add_f32_e32 v114, 1.0, v115
	v_rcp_f32_e32 v114, v114
	v_mul_f32_e32 v105, v105, v108
	v_mul_f32_e32 v108, v110, v109
	v_mul_f32_e32 v109, 0xbfb8aa3b, v100
	v_exp_f32_e32 v109, v109
	v_mul_f32_e32 v106, v106, v108
	v_mul_f32_e32 v108, v111, v114
	v_mul_f32_e32 v107, v107, v108
	v_cvt_pk_bf16_f32 v104, v104, v105
	v_cvt_pk_bf16_f32 v105, v106, v107
	v_add_f32_e32 v106, 1.0, v109
	v_rcp_f32_e32 v106, v106
	v_mul_f32_e32 v107, 0xbfb8aa3b, v101
	v_exp_f32_e32 v107, v107
	global_store_dwordx2 v[112:113], v[104:105], off
	v_mul_f32_e32 v100, v100, v106
	v_mul_f32_e32 v96, v96, v100
	v_add_f32_e32 v100, 1.0, v107
	v_mul_f32_e32 v104, 0xbfb8aa3b, v102
	v_rcp_f32_e32 v100, v100
	v_exp_f32_e32 v104, v104
	v_mul_f32_e32 v105, 0xbfb8aa3b, v103
	v_exp_f32_e32 v105, v105
	v_mul_f32_e32 v100, v101, v100
	v_add_f32_e32 v101, 1.0, v104
	v_rcp_f32_e32 v101, v101
	v_add_f32_e32 v104, 1.0, v105
	v_rcp_f32_e32 v104, v104
	v_mul_f32_e32 v97, v97, v100
	v_mul_f32_e32 v100, v102, v101
	v_mul_f32_e32 v98, v98, v100
	v_mul_f32_e32 v100, v103, v104
	v_cvt_pk_bf16_f32 v96, v96, v97
	v_mul_f32_e32 v99, v99, v100
	v_cvt_pk_bf16_f32 v97, v98, v99
	global_store_dwordx2 v[112:113], v[96:97], off offset:128
	v_mul_f32_e32 v96, 0xbfb8aa3b, v92
	v_exp_f32_e32 v98, v96
	v_mul_f32_e32 v99, 0xbfb8aa3b, v93
	v_exp_f32_e32 v99, v99
	v_or_b32_e32 v96, 32, v150
	v_add_f32_e32 v98, 1.0, v98
	v_rcp_f32_e32 v98, v98
	v_mad_i64_i32 v[96:97], s[44:45], v96, s64, v[140:141]
	v_lshl_add_u64 v[96:97], v[96:97], 0, v[142:143]
	v_mul_f32_e32 v92, v92, v98
	v_mul_f32_e32 v88, v88, v92
	v_add_f32_e32 v92, 1.0, v99
	v_mul_f32_e32 v98, 0xbfb8aa3b, v94
	v_rcp_f32_e32 v92, v92
	v_exp_f32_e32 v98, v98
	v_mul_f32_e32 v99, 0xbfb8aa3b, v95
	v_exp_f32_e32 v99, v99
	v_mul_f32_e32 v92, v93, v92
	v_add_f32_e32 v93, 1.0, v98
	v_rcp_f32_e32 v93, v93
	v_add_f32_e32 v98, 1.0, v99
	v_rcp_f32_e32 v98, v98
	v_mul_f32_e32 v89, v89, v92
	v_mul_f32_e32 v92, v94, v93
	v_mul_f32_e32 v93, 0xbfb8aa3b, v84
	v_exp_f32_e32 v93, v93
	v_mul_f32_e32 v90, v90, v92
	v_mul_f32_e32 v92, v95, v98
	v_mul_f32_e32 v91, v91, v92
	v_cvt_pk_bf16_f32 v88, v88, v89
	v_cvt_pk_bf16_f32 v89, v90, v91
	v_add_f32_e32 v90, 1.0, v93
	v_rcp_f32_e32 v90, v90
	v_mul_f32_e32 v91, 0xbfb8aa3b, v85
	v_exp_f32_e32 v91, v91
	global_store_dwordx2 v[96:97], v[88:89], off
	v_mul_f32_e32 v84, v84, v90
	v_mul_f32_e32 v80, v80, v84
	v_add_f32_e32 v84, 1.0, v91
	v_mul_f32_e32 v88, 0xbfb8aa3b, v86
	v_rcp_f32_e32 v84, v84
	v_exp_f32_e32 v88, v88
	v_mul_f32_e32 v89, 0xbfb8aa3b, v87
	v_exp_f32_e32 v89, v89
	v_mul_f32_e32 v84, v85, v84
	v_add_f32_e32 v85, 1.0, v88
	v_rcp_f32_e32 v85, v85
	v_add_f32_e32 v88, 1.0, v89
	v_rcp_f32_e32 v88, v88
	v_mul_f32_e32 v81, v81, v84
	v_mul_f32_e32 v84, v86, v85
	v_mul_f32_e32 v82, v82, v84
	v_mul_f32_e32 v84, v87, v88
	v_cvt_pk_bf16_f32 v80, v80, v81
	v_mul_f32_e32 v83, v83, v84
	v_cvt_pk_bf16_f32 v81, v82, v83
	global_store_dwordx2 v[96:97], v[80:81], off offset:128
	v_mul_f32_e32 v80, 0xbfb8aa3b, v76
	v_exp_f32_e32 v82, v80
	v_mul_f32_e32 v83, 0xbfb8aa3b, v77
	v_exp_f32_e32 v83, v83
	v_or_b32_e32 v80, 48, v150
	v_add_f32_e32 v82, 1.0, v82
	v_rcp_f32_e32 v82, v82
	v_mad_i64_i32 v[80:81], s[44:45], v80, s64, v[140:141]
	v_lshl_add_u64 v[80:81], v[80:81], 0, v[142:143]
	v_mul_f32_e32 v76, v76, v82
	v_mul_f32_e32 v72, v72, v76
	v_add_f32_e32 v76, 1.0, v83
	v_mul_f32_e32 v82, 0xbfb8aa3b, v78
	v_rcp_f32_e32 v76, v76
	v_exp_f32_e32 v82, v82
	v_mul_f32_e32 v83, 0xbfb8aa3b, v79
	v_exp_f32_e32 v83, v83
	v_mul_f32_e32 v76, v77, v76
	v_add_f32_e32 v77, 1.0, v82
	v_rcp_f32_e32 v77, v77
	v_add_f32_e32 v82, 1.0, v83
	v_rcp_f32_e32 v82, v82
	v_mul_f32_e32 v73, v73, v76
	v_mul_f32_e32 v76, v78, v77
	v_mul_f32_e32 v77, 0xbfb8aa3b, v68
	v_exp_f32_e32 v77, v77
	v_mul_f32_e32 v74, v74, v76
	v_mul_f32_e32 v76, v79, v82
	v_mul_f32_e32 v75, v75, v76
	v_cvt_pk_bf16_f32 v72, v72, v73
	v_cvt_pk_bf16_f32 v73, v74, v75
	v_add_f32_e32 v74, 1.0, v77
	v_rcp_f32_e32 v74, v74
	v_mul_f32_e32 v75, 0xbfb8aa3b, v69
	v_exp_f32_e32 v75, v75
	global_store_dwordx2 v[80:81], v[72:73], off
	v_mul_f32_e32 v68, v68, v74
	v_mul_f32_e32 v64, v64, v68
	v_add_f32_e32 v68, 1.0, v75
	v_mul_f32_e32 v72, 0xbfb8aa3b, v70
	v_rcp_f32_e32 v68, v68
	v_exp_f32_e32 v72, v72
	v_mul_f32_e32 v73, 0xbfb8aa3b, v71
	v_exp_f32_e32 v73, v73
	v_mul_f32_e32 v68, v69, v68
	v_add_f32_e32 v69, 1.0, v72
	v_rcp_f32_e32 v69, v69
	v_add_f32_e32 v72, 1.0, v73
	v_rcp_f32_e32 v72, v72
	v_mul_f32_e32 v65, v65, v68
	v_mul_f32_e32 v68, v70, v69
	v_mul_f32_e32 v66, v66, v68
	v_mul_f32_e32 v68, v71, v72
	v_cvt_pk_bf16_f32 v64, v64, v65
	v_mul_f32_e32 v67, v67, v68
	v_cvt_pk_bf16_f32 v65, v66, v67
	global_store_dwordx2 v[80:81], v[64:65], off offset:128
	v_mul_f32_e32 v64, 0xbfb8aa3b, v60
	v_exp_f32_e32 v66, v64
	v_mul_f32_e32 v67, 0xbfb8aa3b, v61
	v_exp_f32_e32 v67, v67
	v_add_u32_e32 v64, 0x80, v150
	v_add_f32_e32 v66, 1.0, v66
	v_rcp_f32_e32 v66, v66
	v_mad_i64_i32 v[64:65], s[44:45], v64, s64, v[140:141]
	v_lshl_add_u64 v[64:65], v[64:65], 0, v[142:143]
	v_mul_f32_e32 v60, v60, v66
	v_mul_f32_e32 v56, v56, v60
	v_add_f32_e32 v60, 1.0, v67
	v_mul_f32_e32 v66, 0xbfb8aa3b, v62
	v_rcp_f32_e32 v60, v60
	v_exp_f32_e32 v66, v66
	v_mul_f32_e32 v67, 0xbfb8aa3b, v63
	v_exp_f32_e32 v67, v67
	v_mul_f32_e32 v60, v61, v60
	v_add_f32_e32 v61, 1.0, v66
	v_rcp_f32_e32 v61, v61
	v_add_f32_e32 v66, 1.0, v67
	v_rcp_f32_e32 v66, v66
	v_mul_f32_e32 v57, v57, v60
	v_mul_f32_e32 v60, v62, v61
	v_mul_f32_e32 v61, 0xbfb8aa3b, v52
	v_exp_f32_e32 v61, v61
	v_mul_f32_e32 v58, v58, v60
	v_mul_f32_e32 v60, v63, v66
	v_mul_f32_e32 v59, v59, v60
	v_cvt_pk_bf16_f32 v56, v56, v57
	v_cvt_pk_bf16_f32 v57, v58, v59
	v_add_f32_e32 v58, 1.0, v61
	v_rcp_f32_e32 v58, v58
	v_mul_f32_e32 v59, 0xbfb8aa3b, v53
	v_exp_f32_e32 v59, v59
	global_store_dwordx2 v[64:65], v[56:57], off
	v_mul_f32_e32 v52, v52, v58
	v_mul_f32_e32 v48, v48, v52
	v_add_f32_e32 v52, 1.0, v59
	v_mul_f32_e32 v56, 0xbfb8aa3b, v54
	v_rcp_f32_e32 v52, v52
	v_exp_f32_e32 v56, v56
	v_mul_f32_e32 v57, 0xbfb8aa3b, v55
	v_exp_f32_e32 v57, v57
	v_mul_f32_e32 v52, v53, v52
	v_add_f32_e32 v53, 1.0, v56
	v_rcp_f32_e32 v53, v53
	v_add_f32_e32 v56, 1.0, v57
	v_rcp_f32_e32 v56, v56
	v_mul_f32_e32 v49, v49, v52
	v_mul_f32_e32 v52, v54, v53
	v_mul_f32_e32 v50, v50, v52
	v_mul_f32_e32 v52, v55, v56
	v_cvt_pk_bf16_f32 v48, v48, v49
	v_mul_f32_e32 v51, v51, v52
	v_cvt_pk_bf16_f32 v49, v50, v51
	global_store_dwordx2 v[64:65], v[48:49], off offset:128
	v_mul_f32_e32 v48, 0xbfb8aa3b, v44
	v_exp_f32_e32 v50, v48
	v_mul_f32_e32 v51, 0xbfb8aa3b, v45
	v_exp_f32_e32 v51, v51
	v_add_u32_e32 v48, 0x90, v150
	v_add_f32_e32 v50, 1.0, v50
	v_rcp_f32_e32 v50, v50
	v_mad_i64_i32 v[48:49], s[44:45], v48, s64, v[140:141]
	v_lshl_add_u64 v[48:49], v[48:49], 0, v[142:143]
	v_mul_f32_e32 v44, v44, v50
	v_mul_f32_e32 v40, v40, v44
	v_add_f32_e32 v44, 1.0, v51
	v_mul_f32_e32 v50, 0xbfb8aa3b, v46
	v_rcp_f32_e32 v44, v44
	v_exp_f32_e32 v50, v50
	v_mul_f32_e32 v51, 0xbfb8aa3b, v47
	v_exp_f32_e32 v51, v51
	v_mul_f32_e32 v44, v45, v44
	v_add_f32_e32 v45, 1.0, v50
	v_rcp_f32_e32 v45, v45
	v_add_f32_e32 v50, 1.0, v51
	v_rcp_f32_e32 v50, v50
	v_mul_f32_e32 v41, v41, v44
	v_mul_f32_e32 v44, v46, v45
	v_mul_f32_e32 v45, 0xbfb8aa3b, v36
	v_exp_f32_e32 v45, v45
	v_mul_f32_e32 v42, v42, v44
	v_mul_f32_e32 v44, v47, v50
	v_mul_f32_e32 v43, v43, v44
	v_cvt_pk_bf16_f32 v40, v40, v41
	v_cvt_pk_bf16_f32 v41, v42, v43
	v_add_f32_e32 v42, 1.0, v45
	v_rcp_f32_e32 v42, v42
	v_mul_f32_e32 v43, 0xbfb8aa3b, v37
	v_exp_f32_e32 v43, v43
	global_store_dwordx2 v[48:49], v[40:41], off
	v_mul_f32_e32 v36, v36, v42
	v_mul_f32_e32 v32, v32, v36
	v_add_f32_e32 v36, 1.0, v43
	v_mul_f32_e32 v40, 0xbfb8aa3b, v38
	v_rcp_f32_e32 v36, v36
	v_exp_f32_e32 v40, v40
	v_mul_f32_e32 v41, 0xbfb8aa3b, v39
	v_exp_f32_e32 v41, v41
	v_mul_f32_e32 v36, v37, v36
	v_add_f32_e32 v37, 1.0, v40
	v_rcp_f32_e32 v37, v37
	v_add_f32_e32 v40, 1.0, v41
	v_rcp_f32_e32 v40, v40
	v_mul_f32_e32 v33, v33, v36
	v_mul_f32_e32 v36, v38, v37
	v_mul_f32_e32 v34, v34, v36
	v_mul_f32_e32 v36, v39, v40
	v_cvt_pk_bf16_f32 v32, v32, v33
	v_mul_f32_e32 v35, v35, v36
	v_cvt_pk_bf16_f32 v33, v34, v35
	global_store_dwordx2 v[48:49], v[32:33], off offset:128
	v_mul_f32_e32 v32, 0xbfb8aa3b, v28
	v_exp_f32_e32 v34, v32
	v_mul_f32_e32 v35, 0xbfb8aa3b, v29
	v_exp_f32_e32 v35, v35
	v_add_u32_e32 v32, 0xa0, v150
	v_add_f32_e32 v34, 1.0, v34
	v_rcp_f32_e32 v34, v34
	v_mad_i64_i32 v[32:33], s[44:45], v32, s64, v[140:141]
	v_lshl_add_u64 v[32:33], v[32:33], 0, v[142:143]
	v_mul_f32_e32 v28, v28, v34
	v_mul_f32_e32 v24, v24, v28
	v_add_f32_e32 v28, 1.0, v35
	v_mul_f32_e32 v34, 0xbfb8aa3b, v30
	v_rcp_f32_e32 v28, v28
	v_exp_f32_e32 v34, v34
	v_mul_f32_e32 v35, 0xbfb8aa3b, v31
	v_exp_f32_e32 v35, v35
	v_mul_f32_e32 v28, v29, v28
	v_add_f32_e32 v29, 1.0, v34
	v_rcp_f32_e32 v29, v29
	v_add_f32_e32 v34, 1.0, v35
	v_rcp_f32_e32 v34, v34
	v_mul_f32_e32 v25, v25, v28
	v_mul_f32_e32 v28, v30, v29
	v_mul_f32_e32 v29, 0xbfb8aa3b, v20
	v_exp_f32_e32 v29, v29
	v_mul_f32_e32 v26, v26, v28
	v_mul_f32_e32 v28, v31, v34
	v_mul_f32_e32 v27, v27, v28
	v_cvt_pk_bf16_f32 v24, v24, v25
	v_cvt_pk_bf16_f32 v25, v26, v27
	v_add_f32_e32 v26, 1.0, v29
	v_rcp_f32_e32 v26, v26
	v_mul_f32_e32 v27, 0xbfb8aa3b, v21
	v_exp_f32_e32 v27, v27
	global_store_dwordx2 v[32:33], v[24:25], off
	v_mul_f32_e32 v20, v20, v26
	v_mul_f32_e32 v16, v16, v20
	v_add_f32_e32 v20, 1.0, v27
	v_mul_f32_e32 v24, 0xbfb8aa3b, v22
	v_rcp_f32_e32 v20, v20
	v_exp_f32_e32 v24, v24
	v_mul_f32_e32 v25, 0xbfb8aa3b, v23
	v_exp_f32_e32 v25, v25
	v_mul_f32_e32 v20, v21, v20
	v_add_f32_e32 v21, 1.0, v24
	v_rcp_f32_e32 v21, v21
	v_add_f32_e32 v24, 1.0, v25
	v_rcp_f32_e32 v24, v24
	v_mul_f32_e32 v17, v17, v20
	v_mul_f32_e32 v20, v22, v21
	v_mul_f32_e32 v18, v18, v20
	v_mul_f32_e32 v20, v23, v24
	v_cvt_pk_bf16_f32 v16, v16, v17
	v_mul_f32_e32 v19, v19, v20
	v_cvt_pk_bf16_f32 v17, v18, v19
	global_store_dwordx2 v[32:33], v[16:17], off offset:128
	v_mul_f32_e32 v16, 0xbfb8aa3b, v12
	v_exp_f32_e32 v18, v16
	v_mul_f32_e32 v19, 0xbfb8aa3b, v13
	v_exp_f32_e32 v19, v19
	v_add_u32_e32 v16, 0xb0, v150
	v_add_f32_e32 v18, 1.0, v18
	v_rcp_f32_e32 v18, v18
	v_mad_i64_i32 v[16:17], s[44:45], v16, s64, v[140:141]
	v_lshl_add_u64 v[16:17], v[16:17], 0, v[142:143]
	v_mul_f32_e32 v12, v12, v18
	v_mul_f32_e32 v8, v8, v12
	v_add_f32_e32 v12, 1.0, v19
	v_mul_f32_e32 v18, 0xbfb8aa3b, v14
	v_rcp_f32_e32 v12, v12
	v_exp_f32_e32 v18, v18
	v_mul_f32_e32 v19, 0xbfb8aa3b, v15
	v_exp_f32_e32 v19, v19
	v_mul_f32_e32 v12, v13, v12
	v_add_f32_e32 v13, 1.0, v18
	v_rcp_f32_e32 v13, v13
	v_add_f32_e32 v18, 1.0, v19
	v_rcp_f32_e32 v18, v18
	v_mul_f32_e32 v9, v9, v12
	v_mul_f32_e32 v12, v14, v13
	v_mul_f32_e32 v13, 0xbfb8aa3b, v4
	v_exp_f32_e32 v13, v13
	v_mul_f32_e32 v10, v10, v12
	v_mul_f32_e32 v12, v15, v18
	v_mul_f32_e32 v11, v11, v12
	v_cvt_pk_bf16_f32 v8, v8, v9
	v_cvt_pk_bf16_f32 v9, v10, v11
	v_add_f32_e32 v10, 1.0, v13
	v_rcp_f32_e32 v10, v10
	v_mul_f32_e32 v11, 0xbfb8aa3b, v5
	v_exp_f32_e32 v11, v11
	global_store_dwordx2 v[16:17], v[8:9], off
	v_mul_f32_e32 v4, v4, v10
	v_mul_f32_e32 v0, v0, v4
	v_add_f32_e32 v4, 1.0, v11
	v_mul_f32_e32 v8, 0xbfb8aa3b, v6
	v_rcp_f32_e32 v4, v4
	v_exp_f32_e32 v8, v8
	v_mul_f32_e32 v9, 0xbfb8aa3b, v7
	v_exp_f32_e32 v9, v9
	v_mul_f32_e32 v4, v5, v4
	v_add_f32_e32 v5, 1.0, v8
	v_rcp_f32_e32 v5, v5
	v_add_f32_e32 v8, 1.0, v9
	v_rcp_f32_e32 v8, v8
	v_mul_f32_e32 v1, v1, v4
	v_mul_f32_e32 v4, v6, v5
	v_mul_f32_e32 v2, v2, v4
	v_mul_f32_e32 v4, v7, v8
	s_andn2_b64 vcc, exec, s[4:5]
	s_mov_b64 s[4:5], -1
	v_mul_f32_e32 v3, v3, v4
	v_cvt_pk_bf16_f32 v0, v0, v1
	v_cvt_pk_bf16_f32 v1, v2, v3
	global_store_dwordx2 v[16:17], v[0:1], off offset:128
	s_setprio 0
	s_cbranch_vccnz .LBB0_180
	s_andn2_b64 vcc, exec, s[0:1]
	s_cbranch_vccnz .LBB0_179
	s_barrier
	s_branch .LBB0_179

.Lmid_gemm1:
	s_add_i32 s18, 0, 0x18000
	s_add_i32 s19, 0, 0x1c000
	v_add_u32_e32 v164, s18, v147
	v_add_u32_e32 v181, s19, v147
	ds_read_b128 v[152:155], v164
	ds_read_b128 v[156:159], v164 offset:1024
	ds_read_b128 v[160:163], v164 offset:2048
	ds_read_b128 v[164:167], v164 offset:3072
	ds_read_b128 v[168:171], v181
	ds_read_b128 v[172:175], v181 offset:1024
	ds_read_b128 v[176:179], v181 offset:2048
	ds_read_b128 v[184:187], v181 offset:3072
	s_add_u32 s52, s58, 0xb0000
	s_addc_u32 s53, s59, 0
	s_mov_b32 m0, s65
	v_lshl_add_u64 v[226:227], s[52:53], 0, v[128:129]
	ds_read_b128 v[188:191], v151 offset:32768
	ds_read_b128 v[192:195], v151 offset:33792
	ds_read_b128 v[196:199], v151 offset:34816
	ds_read_b128 v[200:203], v151 offset:35840
	ds_read_b128 v[204:207], v151 offset:36864
	ds_read_b128 v[208:211], v151 offset:37888
	ds_read_b128 v[212:215], v151 offset:38912
	ds_read_b128 v[216:219], v151 offset:39936
	global_load_lds_dwordx4 v[226:227], off
	v_lshl_add_u64 v[226:227], s[52:53], 0, v[132:133]
	s_mov_b32 m0, s66
	s_nop 0
	global_load_lds_dwordx4 v[226:227], off
	s_waitcnt vmcnt(8)
	s_waitcnt lgkmcnt(0)
	s_barrier
	s_waitcnt lgkmcnt(0)
	v_mfma_f32_16x16x32_bf16 v[124:127], v[152:155], v[188:191], v[124:127]
	v_mfma_f32_16x16x32_bf16 v[124:127], v[156:159], v[192:195], v[124:127]
	s_setprio 1
	v_mfma_f32_16x16x32_bf16 v[120:123], v[160:163], v[188:191], v[120:123]
	v_mfma_f32_16x16x32_bf16 v[120:123], v[164:167], v[192:195], v[120:123]
	v_mfma_f32_16x16x32_bf16 v[116:119], v[152:155], v[196:199], v[116:119]
	v_mfma_f32_16x16x32_bf16 v[116:119], v[156:159], v[200:203], v[116:119]
	v_mfma_f32_16x16x32_bf16 v[108:111], v[160:163], v[196:199], v[108:111]
	v_mfma_f32_16x16x32_bf16 v[108:111], v[164:167], v[200:203], v[108:111]
	v_mfma_f32_16x16x32_bf16 v[100:103], v[152:155], v[204:207], v[100:103]
	v_mfma_f32_16x16x32_bf16 v[100:103], v[156:159], v[208:211], v[100:103]
	v_mfma_f32_16x16x32_bf16 v[92:95], v[160:163], v[204:207], v[92:95]
	v_mfma_f32_16x16x32_bf16 v[92:95], v[164:167], v[208:211], v[92:95]
	v_mfma_f32_16x16x32_bf16 v[84:87], v[152:155], v[212:215], v[84:87]
	v_mfma_f32_16x16x32_bf16 v[84:87], v[156:159], v[216:219], v[84:87]
	v_mfma_f32_16x16x32_bf16 v[76:79], v[160:163], v[212:215], v[76:79]
	v_mfma_f32_16x16x32_bf16 v[76:79], v[164:167], v[216:219], v[76:79]
	v_mfma_f32_16x16x32_bf16 v[112:115], v[168:171], v[188:191], v[112:115]
	v_mfma_f32_16x16x32_bf16 v[112:115], v[172:175], v[192:195], v[112:115]
	v_mfma_f32_16x16x32_bf16 v[104:107], v[176:179], v[188:191], v[104:107]
	v_mfma_f32_16x16x32_bf16 v[104:107], v[184:187], v[192:195], v[104:107]
	v_mfma_f32_16x16x32_bf16 v[96:99], v[168:171], v[196:199], v[96:99]
	v_mfma_f32_16x16x32_bf16 v[96:99], v[172:175], v[200:203], v[96:99]
	v_mfma_f32_16x16x32_bf16 v[88:91], v[176:179], v[196:199], v[88:91]
	v_mfma_f32_16x16x32_bf16 v[88:91], v[184:187], v[200:203], v[88:91]
	v_mfma_f32_16x16x32_bf16 v[80:83], v[168:171], v[204:207], v[80:83]
	v_mfma_f32_16x16x32_bf16 v[80:83], v[172:175], v[208:211], v[80:83]
	v_mfma_f32_16x16x32_bf16 v[72:75], v[176:179], v[204:207], v[72:75]
	v_mfma_f32_16x16x32_bf16 v[72:75], v[184:187], v[208:211], v[72:75]
	v_mfma_f32_16x16x32_bf16 v[68:71], v[168:171], v[212:215], v[68:71]
	v_mfma_f32_16x16x32_bf16 v[68:71], v[172:175], v[216:219], v[68:71]
	s_barrier
	v_mfma_f32_16x16x32_bf16 v[64:67], v[176:179], v[212:215], v[64:67]
	v_mfma_f32_16x16x32_bf16 v[64:67], v[184:187], v[216:219], v[64:67]
	s_setprio 0
	s_add_i32 s18, s18, s62
	v_lshl_add_u64 v[144:145], v[144:145], 0, s[8:9]
	s_mov_b32 m0, s18
	ds_read_b128 v[188:191], v151 offset:49152
	ds_read_b128 v[192:195], v151 offset:50176
	ds_read_b128 v[196:199], v151 offset:51200
	ds_read_b128 v[200:203], v151 offset:52224
	ds_read_b128 v[204:207], v151 offset:53248
	ds_read_b128 v[208:211], v151 offset:54272
	ds_read_b128 v[212:215], v151 offset:55296
	ds_read_b128 v[216:219], v151 offset:56320
	global_load_lds_dwordx4 v[144:145], off
	s_add_i32 m0, s18, 0x2000
	s_add_u32 s52, s56, 0xb0080
	v_lshl_add_u64 v[144:145], v[220:221], 0, s[8:9]
	s_addc_u32 s53, s57, 0
	s_add_i32 s18, s19, s62
	global_load_lds_dwordx4 v[144:145], off
	v_lshl_add_u64 v[144:145], s[52:53], 0, v[130:131]
	s_mov_b32 m0, s18
	s_nop 0
	global_load_lds_dwordx4 v[144:145], off
	v_lshl_add_u64 v[144:145], s[52:53], 0, v[134:135]
	s_add_i32 m0, s18, 0x2000
	s_nop 0
	global_load_lds_dwordx4 v[144:145], off
	v_lshl_add_u64 v[144:145], v[222:223], 0, s[8:9]
	s_mov_b32 m0, s68
	s_nop 0
	global_load_lds_dwordx4 v[144:145], off
	v_lshl_add_u64 v[144:145], v[224:225], 0, s[8:9]
	s_mov_b32 m0, s69
	s_nop 0
	global_load_lds_dwordx4 v[144:145], off
	s_waitcnt vmcnt(8)
	s_waitcnt lgkmcnt(0)
	s_barrier
	s_waitcnt lgkmcnt(0)
	v_mfma_f32_16x16x32_bf16 v[60:63], v[152:155], v[188:191], v[60:63]
	v_mfma_f32_16x16x32_bf16 v[60:63], v[156:159], v[192:195], v[60:63]
	s_setprio 1
	v_mfma_f32_16x16x32_bf16 v[56:59], v[160:163], v[188:191], v[56:59]
	v_mfma_f32_16x16x32_bf16 v[56:59], v[164:167], v[192:195], v[56:59]
	v_mfma_f32_16x16x32_bf16 v[52:55], v[152:155], v[196:199], v[52:55]
	v_mfma_f32_16x16x32_bf16 v[52:55], v[156:159], v[200:203], v[52:55]
	v_mfma_f32_16x16x32_bf16 v[44:47], v[160:163], v[196:199], v[44:47]
	v_mfma_f32_16x16x32_bf16 v[44:47], v[164:167], v[200:203], v[44:47]
	v_mfma_f32_16x16x32_bf16 v[36:39], v[152:155], v[204:207], v[36:39]
	v_mfma_f32_16x16x32_bf16 v[36:39], v[156:159], v[208:211], v[36:39]
	v_mfma_f32_16x16x32_bf16 v[28:31], v[160:163], v[204:207], v[28:31]
	v_mfma_f32_16x16x32_bf16 v[28:31], v[164:167], v[208:211], v[28:31]
	v_mfma_f32_16x16x32_bf16 v[20:23], v[152:155], v[212:215], v[20:23]
	v_mfma_f32_16x16x32_bf16 v[20:23], v[156:159], v[216:219], v[20:23]
	v_mfma_f32_16x16x32_bf16 v[12:15], v[160:163], v[212:215], v[12:15]
	v_mfma_f32_16x16x32_bf16 v[12:15], v[164:167], v[216:219], v[12:15]
	v_mfma_f32_16x16x32_bf16 v[48:51], v[168:171], v[188:191], v[48:51]
	v_mfma_f32_16x16x32_bf16 v[48:51], v[172:175], v[192:195], v[48:51]
	v_mfma_f32_16x16x32_bf16 v[40:43], v[176:179], v[188:191], v[40:43]
	v_mfma_f32_16x16x32_bf16 v[40:43], v[184:187], v[192:195], v[40:43]
	v_mfma_f32_16x16x32_bf16 v[32:35], v[168:171], v[196:199], v[32:35]
	v_mfma_f32_16x16x32_bf16 v[32:35], v[172:175], v[200:203], v[32:35]
	v_mfma_f32_16x16x32_bf16 v[24:27], v[176:179], v[196:199], v[24:27]
	v_mfma_f32_16x16x32_bf16 v[24:27], v[184:187], v[200:203], v[24:27]
	v_mfma_f32_16x16x32_bf16 v[16:19], v[168:171], v[204:207], v[16:19]
	v_mfma_f32_16x16x32_bf16 v[16:19], v[172:175], v[208:211], v[16:19]
	v_mfma_f32_16x16x32_bf16 v[8:11], v[176:179], v[204:207], v[8:11]
	v_mfma_f32_16x16x32_bf16 v[8:11], v[184:187], v[208:211], v[8:11]
	v_mfma_f32_16x16x32_bf16 v[4:7], v[168:171], v[212:215], v[4:7]
	v_mfma_f32_16x16x32_bf16 v[4:7], v[172:175], v[216:219], v[4:7]
	s_barrier
	v_mfma_f32_16x16x32_bf16 v[0:3], v[176:179], v[212:215], v[0:3]
	v_mfma_f32_16x16x32_bf16 v[0:3], v[184:187], v[216:219], v[0:3]
	s_setprio 0
	s_add_i32 s86, s86, 2
	s_add_u32 s84, s84, 0x100
	s_addc_u32 s85, s85, 0
	s_cmp_gt_u32 s86, 41
	s_mov_b64 s[52:53], s[54:55]
	s_cbranch_scc0 .LBB0_264
	s_and_b64 vcc, exec, s[10:11]
	s_cbranch_vccz .LBB0_267
	s_barrier
	s_setprio 1
.LBB0_267:
	v_lshl_add_u32 v152, s82, 8, v146
	v_lshl_or_b32 v144, s83, 8, v148
	v_ashrrev_i32_e32 v145, 31, v144
	v_ashrrev_i32_e32 v153, 31, v152
	v_lshl_add_u64 v[154:155], v[144:145], 1, s[24:25]
	v_lshlrev_b64 v[144:145], 11, v[152:153]
	v_lshl_add_u64 v[144:145], v[154:155], 0, v[144:145]
	s_nop 15
	s_nop 7
	v_cvt_pk_bf16_f32 v124, v124, v125
	v_cvt_pk_bf16_f32 v125, v126, v127
	v_cvt_pk_bf16_f32 v126, v120, v121
	v_cvt_pk_bf16_f32 v127, v122, v123
	global_store_dwordx4 v[144:145], v[124:127], off
	v_cvt_pk_bf16_f32 v112, v112, v113
	v_cvt_pk_bf16_f32 v113, v114, v115
	v_cvt_pk_bf16_f32 v114, v104, v105
	v_or_b32_e32 v104, 16, v152
	v_ashrrev_i32_e32 v105, 31, v104
	v_lshlrev_b64 v[104:105], 11, v[104:105]
	v_cvt_pk_bf16_f32 v115, v106, v107
	global_store_dwordx4 v[144:145], v[112:115], off offset:256
	s_nop 1
	v_lshl_add_u64 v[112:113], v[154:155], 0, v[104:105]
	v_cvt_pk_bf16_f32 v104, v116, v117
	v_cvt_pk_bf16_f32 v105, v118, v119
	v_cvt_pk_bf16_f32 v106, v108, v109
	v_cvt_pk_bf16_f32 v107, v110, v111
	global_store_dwordx4 v[112:113], v[104:107], off
	v_cvt_pk_bf16_f32 v96, v96, v97
	v_cvt_pk_bf16_f32 v97, v98, v99
	v_cvt_pk_bf16_f32 v98, v88, v89
	v_or_b32_e32 v88, 32, v152
	v_ashrrev_i32_e32 v89, 31, v88
	v_lshlrev_b64 v[88:89], 11, v[88:89]
	v_cvt_pk_bf16_f32 v99, v90, v91
	global_store_dwordx4 v[112:113], v[96:99], off offset:256
	s_nop 1
	v_lshl_add_u64 v[96:97], v[154:155], 0, v[88:89]
	v_cvt_pk_bf16_f32 v88, v100, v101
	v_cvt_pk_bf16_f32 v89, v102, v103
	v_cvt_pk_bf16_f32 v90, v92, v93
	v_cvt_pk_bf16_f32 v91, v94, v95
	global_store_dwordx4 v[96:97], v[88:91], off
	v_cvt_pk_bf16_f32 v80, v80, v81
	v_cvt_pk_bf16_f32 v81, v82, v83
	v_cvt_pk_bf16_f32 v82, v72, v73
	v_or_b32_e32 v72, 48, v152
	v_ashrrev_i32_e32 v73, 31, v72
	v_lshlrev_b64 v[72:73], 11, v[72:73]
	v_cvt_pk_bf16_f32 v83, v74, v75
	global_store_dwordx4 v[96:97], v[80:83], off offset:256
	s_nop 1
	v_lshl_add_u64 v[80:81], v[154:155], 0, v[72:73]
	v_cvt_pk_bf16_f32 v72, v84, v85
	v_cvt_pk_bf16_f32 v73, v86, v87
	v_cvt_pk_bf16_f32 v74, v76, v77
	v_cvt_pk_bf16_f32 v75, v78, v79
	global_store_dwordx4 v[80:81], v[72:75], off
	v_cvt_pk_bf16_f32 v68, v68, v69
	v_cvt_pk_bf16_f32 v69, v70, v71
	v_cvt_pk_bf16_f32 v70, v64, v65
	v_cvt_pk_bf16_f32 v71, v66, v67
	global_store_dwordx4 v[80:81], v[68:71], off offset:256
	v_cvt_pk_bf16_f32 v60, v60, v61
	v_cvt_pk_bf16_f32 v61, v62, v63
	v_cvt_pk_bf16_f32 v62, v56, v57
	v_add_co_u32_e32 v56, vcc, s72, v144
	v_lshl_add_u64 v[64:65], v[144:145], 0, s[30:31]
	s_nop 0
	v_addc_co_u32_e32 v57, vcc, 0, v145, vcc
	v_cvt_pk_bf16_f32 v63, v58, v59
	global_store_dwordx4 v[56:57], v[60:63], off
	v_cvt_pk_bf16_f32 v48, v48, v49
	v_cvt_pk_bf16_f32 v49, v50, v51
	v_cvt_pk_bf16_f32 v50, v40, v41
	v_cvt_pk_bf16_f32 v51, v42, v43
	global_store_dwordx4 v[64:65], v[48:51], off offset:256
	v_cvt_pk_bf16_f32 v40, v52, v53
	v_cvt_pk_bf16_f32 v41, v54, v55
	v_cvt_pk_bf16_f32 v42, v44, v45
	v_add_co_u32_e32 v44, vcc, s73, v144
	s_nop 0
	v_lshl_add_u64 v[48:49], v[144:145], 0, s[36:37]
	v_addc_co_u32_e32 v45, vcc, 0, v145, vcc
	v_cvt_pk_bf16_f32 v43, v46, v47
	global_store_dwordx4 v[44:45], v[40:43], off
	v_cvt_pk_bf16_f32 v32, v32, v33
	v_cvt_pk_bf16_f32 v33, v34, v35
	v_cvt_pk_bf16_f32 v34, v24, v25
	v_cvt_pk_bf16_f32 v35, v26, v27
	global_store_dwordx4 v[48:49], v[32:35], off offset:256
	v_cvt_pk_bf16_f32 v24, v36, v37
	v_cvt_pk_bf16_f32 v25, v38, v39
	v_cvt_pk_bf16_f32 v26, v28, v29
	v_add_co_u32_e32 v28, vcc, s74, v144
	s_nop 0
	v_lshl_add_u64 v[32:33], v[144:145], 0, s[44:45]
	v_addc_co_u32_e32 v29, vcc, 0, v145, vcc
	v_cvt_pk_bf16_f32 v27, v30, v31
	global_store_dwordx4 v[28:29], v[24:27], off
	v_cvt_pk_bf16_f32 v16, v16, v17
	v_cvt_pk_bf16_f32 v17, v18, v19
	v_cvt_pk_bf16_f32 v18, v8, v9
	v_cvt_pk_bf16_f32 v19, v10, v11
	global_store_dwordx4 v[32:33], v[16:19], off offset:256
	v_cvt_pk_bf16_f32 v8, v20, v21
	v_cvt_pk_bf16_f32 v9, v22, v23
	v_cvt_pk_bf16_f32 v10, v12, v13
	v_add_co_u32_e32 v12, vcc, s75, v144
	s_nop 0
	v_lshl_add_u64 v[16:17], v[144:145], 0, s[46:47]
	v_addc_co_u32_e32 v13, vcc, 0, v145, vcc
	s_and_b64 vcc, exec, s[4:5]
	s_mov_b64 s[4:5], -1
	v_cvt_pk_bf16_f32 v11, v14, v15
	global_store_dwordx4 v[12:13], v[8:11], off
	v_cvt_pk_bf16_f32 v4, v4, v5
	v_cvt_pk_bf16_f32 v5, v6, v7
	v_cvt_pk_bf16_f32 v6, v0, v1
	v_cvt_pk_bf16_f32 v7, v2, v3
	global_store_dwordx4 v[16:17], v[4:7], off offset:256
	s_setprio 0
	s_cbranch_vccnz .LBB0_252
	s_andn2_b64 vcc, exec, s[0:1]
	s_cbranch_vccnz .LBB0_251
	s_barrier
	s_branch .LBB0_251

.Lmid_gemm2:
	s_add_i32 s18, 0, 0x18000
	s_add_i32 s19, 0, 0x1c000
	v_add_u32_e32 v164, s18, v147
	v_add_u32_e32 v181, s19, v147
	ds_read_b128 v[152:155], v164
	ds_read_b128 v[156:159], v164 offset:1024
	ds_read_b128 v[160:163], v164 offset:2048
	ds_read_b128 v[164:167], v164 offset:3072
	ds_read_b128 v[168:171], v181
	ds_read_b128 v[172:175], v181 offset:1024
	ds_read_b128 v[176:179], v181 offset:2048
	ds_read_b128 v[184:187], v181 offset:3072
	s_add_u32 s62, s62, 0x40000
	s_addc_u32 s63, s63, 0
	s_mov_b32 m0, s70
	v_lshl_add_u64 v[228:229], s[62:63], 0, v[134:135]
	ds_read_b128 v[188:191], v150 offset:32768
	ds_read_b128 v[192:195], v150 offset:33792
	ds_read_b128 v[196:199], v150 offset:34816
	ds_read_b128 v[200:203], v150 offset:35840
	ds_read_b128 v[204:207], v150 offset:36864
	ds_read_b128 v[208:211], v150 offset:37888
	ds_read_b128 v[212:215], v150 offset:38912
	ds_read_b128 v[216:219], v150 offset:39936
	global_load_lds_dwordx4 v[228:229], off
	v_lshl_add_u64 v[228:229], s[62:63], 0, v[130:131]
	s_mov_b32 m0, s71
	s_nop 0
	global_load_lds_dwordx4 v[228:229], off
	s_waitcnt vmcnt(8)
	s_waitcnt lgkmcnt(0)
	s_barrier
	s_waitcnt lgkmcnt(0)
	v_mfma_f32_16x16x32_bf16 v[124:127], v[152:155], v[188:191], v[124:127]
	v_mfma_f32_16x16x32_bf16 v[124:127], v[156:159], v[192:195], v[124:127]
	s_setprio 1
	v_mfma_f32_16x16x32_bf16 v[120:123], v[160:163], v[188:191], v[120:123]
	v_mfma_f32_16x16x32_bf16 v[120:123], v[164:167], v[192:195], v[120:123]
	v_mfma_f32_16x16x32_bf16 v[116:119], v[152:155], v[196:199], v[116:119]
	v_mfma_f32_16x16x32_bf16 v[116:119], v[156:159], v[200:203], v[116:119]
	v_mfma_f32_16x16x32_bf16 v[112:115], v[160:163], v[196:199], v[112:115]
	v_mfma_f32_16x16x32_bf16 v[112:115], v[164:167], v[200:203], v[112:115]
	v_mfma_f32_16x16x32_bf16 v[108:111], v[152:155], v[204:207], v[108:111]
	v_mfma_f32_16x16x32_bf16 v[108:111], v[156:159], v[208:211], v[108:111]
	v_mfma_f32_16x16x32_bf16 v[104:107], v[160:163], v[204:207], v[104:107]
	v_mfma_f32_16x16x32_bf16 v[104:107], v[164:167], v[208:211], v[104:107]
	v_mfma_f32_16x16x32_bf16 v[100:103], v[152:155], v[212:215], v[100:103]
	v_mfma_f32_16x16x32_bf16 v[100:103], v[156:159], v[216:219], v[100:103]
	v_mfma_f32_16x16x32_bf16 v[96:99], v[160:163], v[212:215], v[96:99]
	v_mfma_f32_16x16x32_bf16 v[96:99], v[164:167], v[216:219], v[96:99]
	v_mfma_f32_16x16x32_bf16 v[68:71], v[168:171], v[188:191], v[68:71]
	v_mfma_f32_16x16x32_bf16 v[68:71], v[172:175], v[192:195], v[68:71]
	v_mfma_f32_16x16x32_bf16 v[64:67], v[176:179], v[188:191], v[64:67]
	v_mfma_f32_16x16x32_bf16 v[64:67], v[184:187], v[192:195], v[64:67]
	v_mfma_f32_16x16x32_bf16 v[52:55], v[168:171], v[196:199], v[52:55]
	v_mfma_f32_16x16x32_bf16 v[52:55], v[172:175], v[200:203], v[52:55]
	v_mfma_f32_16x16x32_bf16 v[48:51], v[176:179], v[196:199], v[48:51]
	v_mfma_f32_16x16x32_bf16 v[48:51], v[184:187], v[200:203], v[48:51]
	v_mfma_f32_16x16x32_bf16 v[44:47], v[168:171], v[204:207], v[44:47]
	v_mfma_f32_16x16x32_bf16 v[44:47], v[172:175], v[208:211], v[44:47]
	v_mfma_f32_16x16x32_bf16 v[40:43], v[176:179], v[204:207], v[40:43]
	v_mfma_f32_16x16x32_bf16 v[40:43], v[184:187], v[208:211], v[40:43]
	v_mfma_f32_16x16x32_bf16 v[36:39], v[168:171], v[212:215], v[36:39]
	v_mfma_f32_16x16x32_bf16 v[36:39], v[172:175], v[216:219], v[36:39]
	s_barrier
	v_mfma_f32_16x16x32_bf16 v[32:35], v[176:179], v[212:215], v[32:35]
	v_mfma_f32_16x16x32_bf16 v[32:35], v[184:187], v[216:219], v[32:35]
	s_setprio 0
	s_add_i32 s18, s18, s66
	v_lshl_add_u64 v[220:221], v[220:221], 0, s[6:7]
	s_mov_b32 m0, s18
	ds_read_b128 v[188:191], v150 offset:49152
	ds_read_b128 v[192:195], v150 offset:50176
	ds_read_b128 v[196:199], v150 offset:51200
	ds_read_b128 v[200:203], v150 offset:52224
	ds_read_b128 v[204:207], v150 offset:53248
	ds_read_b128 v[208:211], v150 offset:54272
	ds_read_b128 v[212:215], v150 offset:55296
	ds_read_b128 v[216:219], v150 offset:56320
	global_load_lds_dwordx4 v[220:221], off
	s_add_i32 m0, s18, 0x2000
	s_add_u32 s60, s60, 0x40080
	v_lshl_add_u64 v[220:221], v[222:223], 0, s[6:7]
	s_addc_u32 s61, s61, 0
	s_add_i32 s18, s19, s66
	global_load_lds_dwordx4 v[220:221], off
	v_lshl_add_u64 v[220:221], s[60:61], 0, v[132:133]
	s_mov_b32 m0, s18
	s_nop 0
	global_load_lds_dwordx4 v[220:221], off
	v_lshl_add_u64 v[220:221], s[60:61], 0, v[128:129]
	s_add_i32 m0, s18, 0x2000
	s_nop 0
	global_load_lds_dwordx4 v[220:221], off
	v_lshl_add_u64 v[220:221], v[224:225], 0, s[6:7]
	s_mov_b32 m0, s74
	s_nop 0
	global_load_lds_dwordx4 v[220:221], off
	v_lshl_add_u64 v[220:221], v[226:227], 0, s[6:7]
	s_mov_b32 m0, s75
	s_nop 0
	global_load_lds_dwordx4 v[220:221], off
	s_waitcnt vmcnt(8)
	s_waitcnt lgkmcnt(0)
	s_barrier
	s_waitcnt lgkmcnt(0)
	v_mfma_f32_16x16x32_bf16 v[92:95], v[152:155], v[188:191], v[92:95]
	v_mfma_f32_16x16x32_bf16 v[92:95], v[156:159], v[192:195], v[92:95]
	s_setprio 1
	v_mfma_f32_16x16x32_bf16 v[88:91], v[160:163], v[188:191], v[88:91]
	v_mfma_f32_16x16x32_bf16 v[88:91], v[164:167], v[192:195], v[88:91]
	v_mfma_f32_16x16x32_bf16 v[84:87], v[152:155], v[196:199], v[84:87]
	v_mfma_f32_16x16x32_bf16 v[84:87], v[156:159], v[200:203], v[84:87]
	v_mfma_f32_16x16x32_bf16 v[80:83], v[160:163], v[196:199], v[80:83]
	v_mfma_f32_16x16x32_bf16 v[80:83], v[164:167], v[200:203], v[80:83]
	v_mfma_f32_16x16x32_bf16 v[76:79], v[152:155], v[204:207], v[76:79]
	v_mfma_f32_16x16x32_bf16 v[76:79], v[156:159], v[208:211], v[76:79]
	v_mfma_f32_16x16x32_bf16 v[72:75], v[160:163], v[204:207], v[72:75]
	v_mfma_f32_16x16x32_bf16 v[72:75], v[164:167], v[208:211], v[72:75]
	v_mfma_f32_16x16x32_bf16 v[60:63], v[152:155], v[212:215], v[60:63]
	v_mfma_f32_16x16x32_bf16 v[60:63], v[156:159], v[216:219], v[60:63]
	v_mfma_f32_16x16x32_bf16 v[56:59], v[160:163], v[212:215], v[56:59]
	v_mfma_f32_16x16x32_bf16 v[56:59], v[164:167], v[216:219], v[56:59]
	v_mfma_f32_16x16x32_bf16 v[28:31], v[168:171], v[188:191], v[28:31]
	v_mfma_f32_16x16x32_bf16 v[28:31], v[172:175], v[192:195], v[28:31]
	v_mfma_f32_16x16x32_bf16 v[24:27], v[176:179], v[188:191], v[24:27]
	v_mfma_f32_16x16x32_bf16 v[24:27], v[184:187], v[192:195], v[24:27]
	v_mfma_f32_16x16x32_bf16 v[20:23], v[168:171], v[196:199], v[20:23]
	v_mfma_f32_16x16x32_bf16 v[20:23], v[172:175], v[200:203], v[20:23]
	v_mfma_f32_16x16x32_bf16 v[16:19], v[176:179], v[196:199], v[16:19]
	v_mfma_f32_16x16x32_bf16 v[16:19], v[184:187], v[200:203], v[16:19]
	v_mfma_f32_16x16x32_bf16 v[12:15], v[168:171], v[204:207], v[12:15]
	v_mfma_f32_16x16x32_bf16 v[12:15], v[172:175], v[208:211], v[12:15]
	v_mfma_f32_16x16x32_bf16 v[8:11], v[176:179], v[204:207], v[8:11]
	v_mfma_f32_16x16x32_bf16 v[8:11], v[184:187], v[208:211], v[8:11]
	v_mfma_f32_16x16x32_bf16 v[4:7], v[168:171], v[212:215], v[4:7]
	v_mfma_f32_16x16x32_bf16 v[4:7], v[172:175], v[216:219], v[4:7]
	s_barrier
	v_mfma_f32_16x16x32_bf16 v[0:3], v[176:179], v[212:215], v[0:3]
	v_mfma_f32_16x16x32_bf16 v[0:3], v[184:187], v[216:219], v[0:3]
	s_setprio 0
	s_add_i32 s86, s86, 2
	s_add_u32 s58, s58, 0x100
	s_addc_u32 s59, s59, 0
	s_add_u32 s84, s84, 0x100
	s_addc_u32 s85, s85, 0
	s_cmp_gt_u32 s86, 13
	s_cbranch_scc0 .LBB0_387
	s_and_b64 vcc, exec, s[8:9]
	s_cbranch_vccz .LBB0_390
	s_barrier
	s_setprio 1
.LBB0_390:
	s_lshl_b32 s18, s57, 8
	s_or_b32 s18, s18, s73
	v_lshl_add_u32 v152, s56, 8, v146
	s_ashr_i32 s56, s18, 6
	s_ashr_i32 s57, s56, 31
	s_lshl_b64 s[58:59], s[56:57], 22
	s_cmp_lt_i32 s56, 16
	s_cselect_b64 vcc, -1, 0
	v_cndmask_b32_e32 v156, 1.0, v151, vcc
	v_pk_mul_f32 v[124:125], v[156:157], v[124:125] op_sel_hi:[0,1]
	v_ashrrev_i32_e32 v153, 31, v152
	v_lshl_add_u64 v[154:155], v[136:137], 0, s[58:59]
	v_pk_mul_f32 v[126:127], v[156:157], v[126:127] op_sel_hi:[0,1]
	v_pk_mul_f32 v[158:159], v[156:157], v[122:123] op_sel_hi:[0,1]
	v_pk_mul_f32 v[122:123], v[156:157], v[120:121] op_sel_hi:[0,1]
	v_cvt_pk_bf16_f32 v120, v124, v125
	v_lshlrev_b64 v[124:125], 7, v[152:153]
	v_cvt_pk_bf16_f32 v121, v126, v127
	v_lshl_add_u64 v[126:127], v[154:155], 0, v[124:125]
	v_pk_mul_f32 v[116:117], v[156:157], v[116:117] op_sel_hi:[0,1]
	v_cvt_pk_bf16_f32 v122, v122, v123
	v_cvt_pk_bf16_f32 v123, v158, v159
	global_store_dwordx4 v[126:127], v[120:123], off
	v_pk_mul_f32 v[118:119], v[156:157], v[118:119] op_sel_hi:[0,1]
	v_pk_mul_f32 v[108:109], v[156:157], v[108:109] op_sel_hi:[0,1]
	v_pk_mul_f32 v[120:121], v[156:157], v[114:115] op_sel_hi:[0,1]
	v_pk_mul_f32 v[114:115], v[156:157], v[112:113] op_sel_hi:[0,1]
	v_cvt_pk_bf16_f32 v112, v116, v117
	v_or_b32_e32 v116, 16, v152
	v_ashrrev_i32_e32 v117, 31, v116
	v_lshlrev_b64 v[116:117], 7, v[116:117]
	v_cvt_pk_bf16_f32 v113, v118, v119
	v_lshl_add_u64 v[118:119], v[154:155], 0, v[116:117]
	v_cvt_pk_bf16_f32 v114, v114, v115
	v_cvt_pk_bf16_f32 v115, v120, v121
	global_store_dwordx4 v[118:119], v[112:115], off
	v_pk_mul_f32 v[110:111], v[156:157], v[110:111] op_sel_hi:[0,1]
	v_pk_mul_f32 v[100:101], v[156:157], v[100:101] op_sel_hi:[0,1]
	v_pk_mul_f32 v[112:113], v[156:157], v[106:107] op_sel_hi:[0,1]
	v_pk_mul_f32 v[106:107], v[156:157], v[104:105] op_sel_hi:[0,1]
	v_cvt_pk_bf16_f32 v104, v108, v109
	v_or_b32_e32 v108, 32, v152
	v_ashrrev_i32_e32 v109, 31, v108
	v_lshlrev_b64 v[108:109], 7, v[108:109]
	v_cvt_pk_bf16_f32 v105, v110, v111
	v_lshl_add_u64 v[110:111], v[154:155], 0, v[108:109]
	v_cvt_pk_bf16_f32 v106, v106, v107
	v_cvt_pk_bf16_f32 v107, v112, v113
	global_store_dwordx4 v[110:111], v[104:107], off
	v_pk_mul_f32 v[102:103], v[156:157], v[102:103] op_sel_hi:[0,1]
	v_pk_mul_f32 v[92:93], v[156:157], v[92:93] op_sel_hi:[0,1]
	v_pk_mul_f32 v[104:105], v[156:157], v[98:99] op_sel_hi:[0,1]
	v_pk_mul_f32 v[98:99], v[156:157], v[96:97] op_sel_hi:[0,1]
	v_cvt_pk_bf16_f32 v96, v100, v101
	v_or_b32_e32 v100, 48, v152
	v_ashrrev_i32_e32 v101, 31, v100
	v_lshlrev_b64 v[100:101], 7, v[100:101]
	v_cvt_pk_bf16_f32 v97, v102, v103
	v_lshl_add_u64 v[102:103], v[154:155], 0, v[100:101]
	v_cvt_pk_bf16_f32 v98, v98, v99
	v_cvt_pk_bf16_f32 v99, v104, v105
	global_store_dwordx4 v[102:103], v[96:99], off
	v_pk_mul_f32 v[94:95], v[156:157], v[94:95] op_sel_hi:[0,1]
	v_pk_mul_f32 v[84:85], v[156:157], v[84:85] op_sel_hi:[0,1]
	v_pk_mul_f32 v[96:97], v[156:157], v[90:91] op_sel_hi:[0,1]
	v_pk_mul_f32 v[90:91], v[156:157], v[88:89] op_sel_hi:[0,1]
	v_cvt_pk_bf16_f32 v88, v92, v93
	v_lshl_add_u64 v[92:93], v[124:125], 0, s[10:11]
	v_cvt_pk_bf16_f32 v89, v94, v95
	v_lshl_add_u64 v[94:95], v[154:155], 0, v[92:93]
	v_cvt_pk_bf16_f32 v90, v90, v91
	v_cvt_pk_bf16_f32 v91, v96, v97
	global_store_dwordx4 v[94:95], v[88:91], off
	v_pk_mul_f32 v[86:87], v[156:157], v[86:87] op_sel_hi:[0,1]
	s_or_b32 s56, s56, 2
	v_pk_mul_f32 v[88:89], v[156:157], v[82:83] op_sel_hi:[0,1]
	v_pk_mul_f32 v[82:83], v[156:157], v[80:81] op_sel_hi:[0,1]
	v_cvt_pk_bf16_f32 v80, v84, v85
	v_lshl_add_u64 v[84:85], v[124:125], 0, s[16:17]
	v_cvt_pk_bf16_f32 v81, v86, v87
	v_lshl_add_u64 v[86:87], v[154:155], 0, v[84:85]
	v_pk_mul_f32 v[76:77], v[156:157], v[76:77] op_sel_hi:[0,1]
	s_ashr_i32 s57, s56, 31
	v_cvt_pk_bf16_f32 v82, v82, v83
	v_cvt_pk_bf16_f32 v83, v88, v89
	global_store_dwordx4 v[86:87], v[80:83], off
	v_pk_mul_f32 v[78:79], v[156:157], v[78:79] op_sel_hi:[0,1]
	s_lshl_b64 s[58:59], s[56:57], 22
	v_pk_mul_f32 v[80:81], v[156:157], v[74:75] op_sel_hi:[0,1]
	v_pk_mul_f32 v[74:75], v[156:157], v[72:73] op_sel_hi:[0,1]
	v_cvt_pk_bf16_f32 v72, v76, v77
	v_lshl_add_u64 v[76:77], v[124:125], 0, s[36:37]
	v_cvt_pk_bf16_f32 v73, v78, v79
	v_lshl_add_u64 v[78:79], v[154:155], 0, v[76:77]
	v_pk_mul_f32 v[60:61], v[156:157], v[60:61] op_sel_hi:[0,1]
	s_cmp_lt_i32 s56, 16
	v_cvt_pk_bf16_f32 v74, v74, v75
	v_cvt_pk_bf16_f32 v75, v80, v81
	global_store_dwordx4 v[78:79], v[72:75], off
	v_pk_mul_f32 v[62:63], v[156:157], v[62:63] op_sel_hi:[0,1]
	s_cselect_b64 vcc, -1, 0
	v_pk_mul_f32 v[72:73], v[156:157], v[58:59] op_sel_hi:[0,1]
	v_pk_mul_f32 v[58:59], v[156:157], v[56:57] op_sel_hi:[0,1]
	v_cvt_pk_bf16_f32 v56, v60, v61
	v_lshl_add_u64 v[60:61], v[124:125], 0, s[44:45]
	v_cvt_pk_bf16_f32 v57, v62, v63
	v_cvt_pk_bf16_f32 v58, v58, v59
	v_cvt_pk_bf16_f32 v59, v72, v73
	v_lshl_add_u64 v[62:63], v[154:155], 0, v[60:61]
	v_cndmask_b32_e32 v72, 1.0, v151, vcc
	global_store_dwordx4 v[62:63], v[56:59], off
	v_lshl_add_u64 v[62:63], v[136:137], 0, s[58:59]
	v_pk_mul_f32 v[64:65], v[72:73], v[64:65] op_sel_hi:[0,1]
	v_pk_mul_f32 v[58:59], v[72:73], v[70:71] op_sel_hi:[0,1]
	v_pk_mul_f32 v[56:57], v[72:73], v[68:69] op_sel_hi:[0,1]
	v_cvt_pk_bf16_f32 v56, v56, v57
	v_cvt_pk_bf16_f32 v57, v58, v59
	v_cvt_pk_bf16_f32 v58, v64, v65
	v_lshl_add_u64 v[64:65], v[62:63], 0, v[124:125]
	v_pk_mul_f32 v[52:53], v[72:73], v[52:53] op_sel_hi:[0,1]
	v_pk_mul_f32 v[66:67], v[72:73], v[66:67] op_sel_hi:[0,1]
	v_cvt_pk_bf16_f32 v59, v66, v67
	global_store_dwordx4 v[64:65], v[56:59], off
	v_pk_mul_f32 v[54:55], v[72:73], v[54:55] op_sel_hi:[0,1]
	v_pk_mul_f32 v[44:45], v[72:73], v[44:45] op_sel_hi:[0,1]
	v_pk_mul_f32 v[56:57], v[72:73], v[50:51] op_sel_hi:[0,1]
	v_pk_mul_f32 v[50:51], v[72:73], v[48:49] op_sel_hi:[0,1]
	v_cvt_pk_bf16_f32 v48, v52, v53
	v_cvt_pk_bf16_f32 v49, v54, v55
	v_lshl_add_u64 v[52:53], v[62:63], 0, v[116:117]
	v_cvt_pk_bf16_f32 v50, v50, v51
	v_cvt_pk_bf16_f32 v51, v56, v57
	global_store_dwordx4 v[52:53], v[48:51], off
	v_pk_mul_f32 v[46:47], v[72:73], v[46:47] op_sel_hi:[0,1]
	v_pk_mul_f32 v[36:37], v[72:73], v[36:37] op_sel_hi:[0,1]
	v_pk_mul_f32 v[48:49], v[72:73], v[42:43] op_sel_hi:[0,1]
	v_pk_mul_f32 v[42:43], v[72:73], v[40:41] op_sel_hi:[0,1]
	v_cvt_pk_bf16_f32 v40, v44, v45
	v_cvt_pk_bf16_f32 v41, v46, v47
	v_lshl_add_u64 v[44:45], v[62:63], 0, v[108:109]
	v_cvt_pk_bf16_f32 v42, v42, v43
	v_cvt_pk_bf16_f32 v43, v48, v49
	global_store_dwordx4 v[44:45], v[40:43], off
	v_pk_mul_f32 v[38:39], v[72:73], v[38:39] op_sel_hi:[0,1]
	v_pk_mul_f32 v[28:29], v[72:73], v[28:29] op_sel_hi:[0,1]
	v_pk_mul_f32 v[40:41], v[72:73], v[34:35] op_sel_hi:[0,1]
	v_pk_mul_f32 v[34:35], v[72:73], v[32:33] op_sel_hi:[0,1]
	v_cvt_pk_bf16_f32 v32, v36, v37
	v_cvt_pk_bf16_f32 v33, v38, v39
	v_lshl_add_u64 v[36:37], v[62:63], 0, v[100:101]
	v_cvt_pk_bf16_f32 v34, v34, v35
	v_cvt_pk_bf16_f32 v35, v40, v41
	global_store_dwordx4 v[36:37], v[32:35], off
	v_pk_mul_f32 v[30:31], v[72:73], v[30:31] op_sel_hi:[0,1]
	v_pk_mul_f32 v[20:21], v[72:73], v[20:21] op_sel_hi:[0,1]
	v_pk_mul_f32 v[32:33], v[72:73], v[26:27] op_sel_hi:[0,1]
	v_pk_mul_f32 v[26:27], v[72:73], v[24:25] op_sel_hi:[0,1]
	v_cvt_pk_bf16_f32 v24, v28, v29
	v_cvt_pk_bf16_f32 v25, v30, v31
	v_lshl_add_u64 v[28:29], v[62:63], 0, v[92:93]
	v_cvt_pk_bf16_f32 v26, v26, v27
	v_cvt_pk_bf16_f32 v27, v32, v33
	global_store_dwordx4 v[28:29], v[24:27], off
	v_pk_mul_f32 v[22:23], v[72:73], v[22:23] op_sel_hi:[0,1]
	v_pk_mul_f32 v[12:13], v[72:73], v[12:13] op_sel_hi:[0,1]
	v_pk_mul_f32 v[24:25], v[72:73], v[18:19] op_sel_hi:[0,1]
	v_pk_mul_f32 v[18:19], v[72:73], v[16:17] op_sel_hi:[0,1]
	v_cvt_pk_bf16_f32 v16, v20, v21
	v_cvt_pk_bf16_f32 v17, v22, v23
	v_lshl_add_u64 v[20:21], v[62:63], 0, v[84:85]
	v_cvt_pk_bf16_f32 v18, v18, v19
	v_cvt_pk_bf16_f32 v19, v24, v25
	global_store_dwordx4 v[20:21], v[16:19], off
	v_pk_mul_f32 v[14:15], v[72:73], v[14:15] op_sel_hi:[0,1]
	v_pk_mul_f32 v[4:5], v[72:73], v[4:5] op_sel_hi:[0,1]
	v_pk_mul_f32 v[16:17], v[72:73], v[10:11] op_sel_hi:[0,1]
	v_pk_mul_f32 v[10:11], v[72:73], v[8:9] op_sel_hi:[0,1]
	v_cvt_pk_bf16_f32 v8, v12, v13
	v_cvt_pk_bf16_f32 v9, v14, v15
	v_lshl_add_u64 v[12:13], v[62:63], 0, v[76:77]
	v_cvt_pk_bf16_f32 v10, v10, v11
	v_cvt_pk_bf16_f32 v11, v16, v17
	global_store_dwordx4 v[12:13], v[8:11], off
	s_andn2_b64 vcc, exec, s[4:5]
	s_mov_b64 s[4:5], -1
	v_pk_mul_f32 v[8:9], v[72:73], v[2:3] op_sel_hi:[0,1]
	v_pk_mul_f32 v[2:3], v[72:73], v[0:1] op_sel_hi:[0,1]
	v_cvt_pk_bf16_f32 v0, v4, v5
	v_lshl_add_u64 v[4:5], v[62:63], 0, v[60:61]
	v_pk_mul_f32 v[6:7], v[72:73], v[6:7] op_sel_hi:[0,1]
	v_cvt_pk_bf16_f32 v1, v6, v7
	v_cvt_pk_bf16_f32 v2, v2, v3
	v_cvt_pk_bf16_f32 v3, v8, v9
	global_store_dwordx4 v[4:5], v[0:3], off
	s_setprio 0
	s_cbranch_vccnz .LBB0_383
	s_andn2_b64 vcc, exec, s[0:1]
	s_cbranch_vccnz .LBB0_382
	s_barrier
	s_branch .LBB0_382

.Lmid_gemm3:
	s_add_i32 s79, 0, 0x18000
	s_add_i32 s89, 0, 0x1c000
	v_add_u32_e32 v164, s79, v147
	v_add_u32_e32 v181, s89, v147
	ds_read_b128 v[152:155], v164
	ds_read_b128 v[156:159], v164 offset:1024
	ds_read_b128 v[160:163], v164 offset:2048
	ds_read_b128 v[164:167], v164 offset:3072
	ds_read_b128 v[168:171], v181
	ds_read_b128 v[172:175], v181 offset:1024
	ds_read_b128 v[176:179], v181 offset:2048
	ds_read_b128 v[184:187], v181 offset:3072
	s_add_u32 s18, s62, 0x40000
	s_addc_u32 s19, s63, 0
	s_mov_b32 m0, s68
	v_lshl_add_u64 v[226:227], s[18:19], 0, v[128:129]
	ds_read_b128 v[188:191], v151 offset:32768
	ds_read_b128 v[192:195], v151 offset:33792
	ds_read_b128 v[196:199], v151 offset:34816
	ds_read_b128 v[200:203], v151 offset:35840
	ds_read_b128 v[204:207], v151 offset:36864
	ds_read_b128 v[208:211], v151 offset:37888
	ds_read_b128 v[212:215], v151 offset:38912
	ds_read_b128 v[216:219], v151 offset:39936
	global_load_lds_dwordx4 v[226:227], off
	v_lshl_add_u64 v[226:227], s[18:19], 0, v[132:133]
	s_mov_b32 m0, s69
	s_nop 0
	global_load_lds_dwordx4 v[226:227], off
	s_waitcnt vmcnt(8)
	s_waitcnt lgkmcnt(0)
	s_barrier
	s_waitcnt lgkmcnt(0)
	v_mfma_f32_16x16x32_bf16 v[124:127], v[152:155], v[188:191], v[124:127]
	v_mfma_f32_16x16x32_bf16 v[124:127], v[156:159], v[192:195], v[124:127]
	s_setprio 1
	v_mfma_f32_16x16x32_bf16 v[120:123], v[160:163], v[188:191], v[120:123]
	v_mfma_f32_16x16x32_bf16 v[120:123], v[164:167], v[192:195], v[120:123]
	v_mfma_f32_16x16x32_bf16 v[116:119], v[152:155], v[196:199], v[116:119]
	v_mfma_f32_16x16x32_bf16 v[116:119], v[156:159], v[200:203], v[116:119]
	v_mfma_f32_16x16x32_bf16 v[108:111], v[160:163], v[196:199], v[108:111]
	v_mfma_f32_16x16x32_bf16 v[108:111], v[164:167], v[200:203], v[108:111]
	v_mfma_f32_16x16x32_bf16 v[100:103], v[152:155], v[204:207], v[100:103]
	v_mfma_f32_16x16x32_bf16 v[100:103], v[156:159], v[208:211], v[100:103]
	v_mfma_f32_16x16x32_bf16 v[92:95], v[160:163], v[204:207], v[92:95]
	v_mfma_f32_16x16x32_bf16 v[92:95], v[164:167], v[208:211], v[92:95]
	v_mfma_f32_16x16x32_bf16 v[84:87], v[152:155], v[212:215], v[84:87]
	v_mfma_f32_16x16x32_bf16 v[84:87], v[156:159], v[216:219], v[84:87]
	v_mfma_f32_16x16x32_bf16 v[76:79], v[160:163], v[212:215], v[76:79]
	v_mfma_f32_16x16x32_bf16 v[76:79], v[164:167], v[216:219], v[76:79]
	v_mfma_f32_16x16x32_bf16 v[112:115], v[168:171], v[188:191], v[112:115]
	v_mfma_f32_16x16x32_bf16 v[112:115], v[172:175], v[192:195], v[112:115]
	v_mfma_f32_16x16x32_bf16 v[104:107], v[176:179], v[188:191], v[104:107]
	v_mfma_f32_16x16x32_bf16 v[104:107], v[184:187], v[192:195], v[104:107]
	v_mfma_f32_16x16x32_bf16 v[96:99], v[168:171], v[196:199], v[96:99]
	v_mfma_f32_16x16x32_bf16 v[96:99], v[172:175], v[200:203], v[96:99]
	v_mfma_f32_16x16x32_bf16 v[88:91], v[176:179], v[196:199], v[88:91]
	v_mfma_f32_16x16x32_bf16 v[88:91], v[184:187], v[200:203], v[88:91]
	v_mfma_f32_16x16x32_bf16 v[80:83], v[168:171], v[204:207], v[80:83]
	v_mfma_f32_16x16x32_bf16 v[80:83], v[172:175], v[208:211], v[80:83]
	v_mfma_f32_16x16x32_bf16 v[72:75], v[176:179], v[204:207], v[72:75]
	v_mfma_f32_16x16x32_bf16 v[72:75], v[184:187], v[208:211], v[72:75]
	v_mfma_f32_16x16x32_bf16 v[68:71], v[168:171], v[212:215], v[68:71]
	v_mfma_f32_16x16x32_bf16 v[68:71], v[172:175], v[216:219], v[68:71]
	s_barrier
	v_mfma_f32_16x16x32_bf16 v[64:67], v[176:179], v[212:215], v[64:67]
	v_mfma_f32_16x16x32_bf16 v[64:67], v[184:187], v[216:219], v[64:67]
	s_setprio 0
	s_add_i32 s18, s79, s66
	v_lshl_add_u64 v[144:145], v[144:145], 0, s[10:11]
	s_mov_b32 m0, s18
	ds_read_b128 v[188:191], v151 offset:49152
	ds_read_b128 v[192:195], v151 offset:50176
	ds_read_b128 v[196:199], v151 offset:51200
	ds_read_b128 v[200:203], v151 offset:52224
	ds_read_b128 v[204:207], v151 offset:53248
	ds_read_b128 v[208:211], v151 offset:54272
	ds_read_b128 v[212:215], v151 offset:55296
	ds_read_b128 v[216:219], v151 offset:56320
	global_load_lds_dwordx4 v[144:145], off
	s_add_i32 m0, s18, 0x2000
	s_add_u32 s18, s60, 0x40080
	v_lshl_add_u64 v[144:145], v[220:221], 0, s[10:11]
	s_addc_u32 s19, s61, 0
	s_add_i32 s60, s89, s66
	global_load_lds_dwordx4 v[144:145], off
	v_lshl_add_u64 v[144:145], s[18:19], 0, v[130:131]
	s_mov_b32 m0, s60
	s_nop 0
	global_load_lds_dwordx4 v[144:145], off
	v_lshl_add_u64 v[144:145], s[18:19], 0, v[134:135]
	s_add_i32 m0, s60, 0x2000
	s_nop 0
	global_load_lds_dwordx4 v[144:145], off
	v_lshl_add_u64 v[144:145], v[222:223], 0, s[10:11]
	s_mov_b32 m0, s71
	s_nop 0
	global_load_lds_dwordx4 v[144:145], off
	v_lshl_add_u64 v[144:145], v[224:225], 0, s[10:11]
	s_mov_b32 m0, s72
	s_nop 0
	global_load_lds_dwordx4 v[144:145], off
	s_waitcnt vmcnt(8)
	s_waitcnt lgkmcnt(0)
	s_barrier
	s_waitcnt lgkmcnt(0)
	v_mfma_f32_16x16x32_bf16 v[60:63], v[152:155], v[188:191], v[60:63]
	v_mfma_f32_16x16x32_bf16 v[60:63], v[156:159], v[192:195], v[60:63]
	s_setprio 1
	v_mfma_f32_16x16x32_bf16 v[56:59], v[160:163], v[188:191], v[56:59]
	v_mfma_f32_16x16x32_bf16 v[56:59], v[164:167], v[192:195], v[56:59]
	v_mfma_f32_16x16x32_bf16 v[52:55], v[152:155], v[196:199], v[52:55]
	v_mfma_f32_16x16x32_bf16 v[52:55], v[156:159], v[200:203], v[52:55]
	v_mfma_f32_16x16x32_bf16 v[44:47], v[160:163], v[196:199], v[44:47]
	v_mfma_f32_16x16x32_bf16 v[44:47], v[164:167], v[200:203], v[44:47]
	v_mfma_f32_16x16x32_bf16 v[36:39], v[152:155], v[204:207], v[36:39]
	v_mfma_f32_16x16x32_bf16 v[36:39], v[156:159], v[208:211], v[36:39]
	v_mfma_f32_16x16x32_bf16 v[28:31], v[160:163], v[204:207], v[28:31]
	v_mfma_f32_16x16x32_bf16 v[28:31], v[164:167], v[208:211], v[28:31]
	v_mfma_f32_16x16x32_bf16 v[20:23], v[152:155], v[212:215], v[20:23]
	v_mfma_f32_16x16x32_bf16 v[20:23], v[156:159], v[216:219], v[20:23]
	v_mfma_f32_16x16x32_bf16 v[12:15], v[160:163], v[212:215], v[12:15]
	v_mfma_f32_16x16x32_bf16 v[12:15], v[164:167], v[216:219], v[12:15]
	v_mfma_f32_16x16x32_bf16 v[48:51], v[168:171], v[188:191], v[48:51]
	v_mfma_f32_16x16x32_bf16 v[48:51], v[172:175], v[192:195], v[48:51]
	v_mfma_f32_16x16x32_bf16 v[40:43], v[176:179], v[188:191], v[40:43]
	v_mfma_f32_16x16x32_bf16 v[40:43], v[184:187], v[192:195], v[40:43]
	v_mfma_f32_16x16x32_bf16 v[32:35], v[168:171], v[196:199], v[32:35]
	v_mfma_f32_16x16x32_bf16 v[32:35], v[172:175], v[200:203], v[32:35]
	v_mfma_f32_16x16x32_bf16 v[24:27], v[176:179], v[196:199], v[24:27]
	v_mfma_f32_16x16x32_bf16 v[24:27], v[184:187], v[200:203], v[24:27]
	v_mfma_f32_16x16x32_bf16 v[16:19], v[168:171], v[204:207], v[16:19]
	v_mfma_f32_16x16x32_bf16 v[16:19], v[172:175], v[208:211], v[16:19]
	v_mfma_f32_16x16x32_bf16 v[8:11], v[176:179], v[204:207], v[8:11]
	v_mfma_f32_16x16x32_bf16 v[8:11], v[184:187], v[208:211], v[8:11]
	v_mfma_f32_16x16x32_bf16 v[4:7], v[168:171], v[212:215], v[4:7]
	v_mfma_f32_16x16x32_bf16 v[4:7], v[172:175], v[216:219], v[4:7]
	s_barrier
	v_mfma_f32_16x16x32_bf16 v[0:3], v[176:179], v[212:215], v[0:3]
	v_mfma_f32_16x16x32_bf16 v[0:3], v[184:187], v[216:219], v[0:3]
	s_setprio 0
	s_add_i32 s88, s88, 2
	s_add_u32 s58, s58, 0x100
	s_addc_u32 s59, s59, 0
	s_add_u32 s86, s86, 0x100
	s_addc_u32 s87, s87, 0
	s_cmp_gt_u32 s88, 13
	s_cbranch_scc0 .LBB0_601
	s_and_b64 vcc, exec, s[12:13]
	s_cbranch_vccz .LBB0_604
	s_barrier
	s_setprio 1
.LBB0_604:
	v_lshl_add_u32 v152, s56, 8, v146
	v_lshl_or_b32 v144, s83, 8, v148
	v_ashrrev_i32_e32 v145, 31, v144
	v_ashrrev_i32_e32 v153, 31, v152
	v_lshl_add_u64 v[154:155], v[144:145], 1, s[24:25]
	v_lshlrev_b64 v[144:145], 11, v[152:153]
	v_lshl_add_u64 v[144:145], v[154:155], 0, v[144:145]
	s_nop 15
	s_nop 7
	v_cvt_pk_bf16_f32 v124, v124, v125
	v_cvt_pk_bf16_f32 v125, v126, v127
	v_cvt_pk_bf16_f32 v126, v120, v121
	v_cvt_pk_bf16_f32 v127, v122, v123
	global_store_dwordx4 v[144:145], v[124:127], off
	v_cvt_pk_bf16_f32 v112, v112, v113
	v_cvt_pk_bf16_f32 v113, v114, v115
	v_cvt_pk_bf16_f32 v114, v104, v105
	v_or_b32_e32 v104, 16, v152
	v_ashrrev_i32_e32 v105, 31, v104
	v_lshlrev_b64 v[104:105], 11, v[104:105]
	v_cvt_pk_bf16_f32 v115, v106, v107
	global_store_dwordx4 v[144:145], v[112:115], off offset:256
	s_nop 1
	v_lshl_add_u64 v[112:113], v[154:155], 0, v[104:105]
	v_cvt_pk_bf16_f32 v104, v116, v117
	v_cvt_pk_bf16_f32 v105, v118, v119
	v_cvt_pk_bf16_f32 v106, v108, v109
	v_cvt_pk_bf16_f32 v107, v110, v111
	global_store_dwordx4 v[112:113], v[104:107], off
	v_cvt_pk_bf16_f32 v96, v96, v97
	v_cvt_pk_bf16_f32 v97, v98, v99
	v_cvt_pk_bf16_f32 v98, v88, v89
	v_or_b32_e32 v88, 32, v152
	v_ashrrev_i32_e32 v89, 31, v88
	v_lshlrev_b64 v[88:89], 11, v[88:89]
	v_cvt_pk_bf16_f32 v99, v90, v91
	global_store_dwordx4 v[112:113], v[96:99], off offset:256
	s_nop 1
	v_lshl_add_u64 v[96:97], v[154:155], 0, v[88:89]
	v_cvt_pk_bf16_f32 v88, v100, v101
	v_cvt_pk_bf16_f32 v89, v102, v103
	v_cvt_pk_bf16_f32 v90, v92, v93
	v_cvt_pk_bf16_f32 v91, v94, v95
	global_store_dwordx4 v[96:97], v[88:91], off
	v_cvt_pk_bf16_f32 v80, v80, v81
	v_cvt_pk_bf16_f32 v81, v82, v83
	v_cvt_pk_bf16_f32 v82, v72, v73
	v_or_b32_e32 v72, 48, v152
	v_ashrrev_i32_e32 v73, 31, v72
	v_lshlrev_b64 v[72:73], 11, v[72:73]
	v_cvt_pk_bf16_f32 v83, v74, v75
	global_store_dwordx4 v[96:97], v[80:83], off offset:256
	s_nop 1
	v_lshl_add_u64 v[80:81], v[154:155], 0, v[72:73]
	v_cvt_pk_bf16_f32 v72, v84, v85
	v_cvt_pk_bf16_f32 v73, v86, v87
	v_cvt_pk_bf16_f32 v74, v76, v77
	v_cvt_pk_bf16_f32 v75, v78, v79
	global_store_dwordx4 v[80:81], v[72:75], off
	v_cvt_pk_bf16_f32 v68, v68, v69
	v_cvt_pk_bf16_f32 v69, v70, v71
	v_cvt_pk_bf16_f32 v70, v64, v65
	v_cvt_pk_bf16_f32 v71, v66, v67
	global_store_dwordx4 v[80:81], v[68:71], off offset:256
	v_cvt_pk_bf16_f32 v60, v60, v61
	v_cvt_pk_bf16_f32 v61, v62, v63
	v_cvt_pk_bf16_f32 v62, v56, v57
	v_add_co_u32_e32 v56, vcc, s75, v144
	v_lshl_add_u64 v[64:65], v[144:145], 0, s[0:1]
	s_nop 0
	v_addc_co_u32_e32 v57, vcc, 0, v145, vcc
	v_cvt_pk_bf16_f32 v63, v58, v59
	global_store_dwordx4 v[56:57], v[60:63], off
	v_cvt_pk_bf16_f32 v48, v48, v49
	v_cvt_pk_bf16_f32 v49, v50, v51
	v_cvt_pk_bf16_f32 v50, v40, v41
	v_cvt_pk_bf16_f32 v51, v42, v43
	global_store_dwordx4 v[64:65], v[48:51], off offset:256
	v_cvt_pk_bf16_f32 v40, v52, v53
	v_cvt_pk_bf16_f32 v41, v54, v55
	v_cvt_pk_bf16_f32 v42, v44, v45
	v_add_co_u32_e32 v44, vcc, s76, v144
	s_nop 0
	v_lshl_add_u64 v[48:49], v[144:145], 0, s[16:17]
	v_addc_co_u32_e32 v45, vcc, 0, v145, vcc
	v_cvt_pk_bf16_f32 v43, v46, v47
	global_store_dwordx4 v[44:45], v[40:43], off
	v_cvt_pk_bf16_f32 v32, v32, v33
	v_cvt_pk_bf16_f32 v33, v34, v35
	v_cvt_pk_bf16_f32 v34, v24, v25
	v_cvt_pk_bf16_f32 v35, v26, v27
	global_store_dwordx4 v[48:49], v[32:35], off offset:256
	v_cvt_pk_bf16_f32 v24, v36, v37
	v_cvt_pk_bf16_f32 v25, v38, v39
	v_cvt_pk_bf16_f32 v26, v28, v29
	v_add_co_u32_e32 v28, vcc, s77, v144
	s_nop 0
	v_lshl_add_u64 v[32:33], v[144:145], 0, s[36:37]
	v_addc_co_u32_e32 v29, vcc, 0, v145, vcc
	v_cvt_pk_bf16_f32 v27, v30, v31
	global_store_dwordx4 v[28:29], v[24:27], off
	v_cvt_pk_bf16_f32 v16, v16, v17
	v_cvt_pk_bf16_f32 v17, v18, v19
	v_cvt_pk_bf16_f32 v18, v8, v9
	v_cvt_pk_bf16_f32 v19, v10, v11
	global_store_dwordx4 v[32:33], v[16:19], off offset:256
	v_cvt_pk_bf16_f32 v8, v20, v21
	v_cvt_pk_bf16_f32 v9, v22, v23
	v_cvt_pk_bf16_f32 v10, v12, v13
	v_add_co_u32_e32 v12, vcc, s82, v144
	s_nop 0
	v_lshl_add_u64 v[16:17], v[144:145], 0, s[44:45]
	v_addc_co_u32_e32 v13, vcc, 0, v145, vcc
	s_andn2_b64 vcc, exec, s[4:5]
	s_mov_b64 s[4:5], -1
	v_cvt_pk_bf16_f32 v11, v14, v15
	global_store_dwordx4 v[12:13], v[8:11], off
	v_cvt_pk_bf16_f32 v4, v4, v5
	v_cvt_pk_bf16_f32 v5, v6, v7
	v_cvt_pk_bf16_f32 v6, v0, v1
	v_cvt_pk_bf16_f32 v7, v2, v3
	global_store_dwordx4 v[16:17], v[4:7], off offset:256
	s_setprio 0
	s_cbranch_vccnz .LBB0_593
	s_andn2_b64 vcc, exec, s[8:9]
	s_cbranch_vccnz .LBB0_592
	s_barrier
	s_branch .LBB0_592

.Lmid_gemm4:
	s_add_i32 s75, 0, 0x18000
	s_add_i32 s76, 0, 0x1c000
	v_add_u32_e32 v158, s75, v145
	v_add_u32_e32 v174, s76, v145
	ds_read_b128 v[140:143], v158
	ds_read_b128 v[150:153], v158 offset:1024
	ds_read_b128 v[154:157], v158 offset:2048
	ds_read_b128 v[158:161], v158 offset:3072
	ds_read_b128 v[162:165], v174
	ds_read_b128 v[166:169], v174 offset:1024
	ds_read_b128 v[170:173], v174 offset:2048
	ds_read_b128 v[174:177], v174 offset:3072
	s_add_u32 s54, s54, 0x40000
	s_addc_u32 s55, s55, 0
	s_mov_b32 m0, s61
	v_lshl_add_u64 v[222:223], s[54:55], 0, v[130:131]
	ds_read_b128 v[184:187], v149 offset:32768
	ds_read_b128 v[188:191], v149 offset:33792
	ds_read_b128 v[192:195], v149 offset:34816
	ds_read_b128 v[196:199], v149 offset:35840
	ds_read_b128 v[200:203], v149 offset:36864
	ds_read_b128 v[204:207], v149 offset:37888
	ds_read_b128 v[208:211], v149 offset:38912
	ds_read_b128 v[212:215], v149 offset:39936
	global_load_lds_dwordx4 v[222:223], off
	v_lshl_add_u64 v[222:223], s[54:55], 0, v[128:129]
	s_mov_b32 m0, s62
	s_nop 0
	global_load_lds_dwordx4 v[222:223], off
	s_waitcnt vmcnt(8)
	s_waitcnt lgkmcnt(0)
	s_barrier
	s_waitcnt lgkmcnt(0)
	v_mfma_f32_16x16x32_bf16 v[124:127], v[140:143], v[184:187], v[124:127]
	v_mfma_f32_16x16x32_bf16 v[124:127], v[150:153], v[188:191], v[124:127]
	s_setprio 1
	v_mfma_f32_16x16x32_bf16 v[120:123], v[154:157], v[184:187], v[120:123]
	v_mfma_f32_16x16x32_bf16 v[120:123], v[158:161], v[188:191], v[120:123]
	v_mfma_f32_16x16x32_bf16 v[108:111], v[140:143], v[192:195], v[108:111]
	v_mfma_f32_16x16x32_bf16 v[108:111], v[150:153], v[196:199], v[108:111]
	v_mfma_f32_16x16x32_bf16 v[104:107], v[154:157], v[192:195], v[104:107]
	v_mfma_f32_16x16x32_bf16 v[104:107], v[158:161], v[196:199], v[104:107]
	v_mfma_f32_16x16x32_bf16 v[92:95], v[140:143], v[200:203], v[92:95]
	v_mfma_f32_16x16x32_bf16 v[92:95], v[150:153], v[204:207], v[92:95]
	v_mfma_f32_16x16x32_bf16 v[88:91], v[154:157], v[200:203], v[88:91]
	v_mfma_f32_16x16x32_bf16 v[88:91], v[158:161], v[204:207], v[88:91]
	v_mfma_f32_16x16x32_bf16 v[76:79], v[140:143], v[208:211], v[76:79]
	v_mfma_f32_16x16x32_bf16 v[76:79], v[150:153], v[212:215], v[76:79]
	v_mfma_f32_16x16x32_bf16 v[72:75], v[154:157], v[208:211], v[72:75]
	v_mfma_f32_16x16x32_bf16 v[72:75], v[158:161], v[212:215], v[72:75]
	v_mfma_f32_16x16x32_bf16 v[116:119], v[162:165], v[184:187], v[116:119]
	v_mfma_f32_16x16x32_bf16 v[116:119], v[166:169], v[188:191], v[116:119]
	v_mfma_f32_16x16x32_bf16 v[112:115], v[170:173], v[184:187], v[112:115]
	v_mfma_f32_16x16x32_bf16 v[112:115], v[174:177], v[188:191], v[112:115]
	v_mfma_f32_16x16x32_bf16 v[100:103], v[162:165], v[192:195], v[100:103]
	v_mfma_f32_16x16x32_bf16 v[100:103], v[166:169], v[196:199], v[100:103]
	v_mfma_f32_16x16x32_bf16 v[96:99], v[170:173], v[192:195], v[96:99]
	v_mfma_f32_16x16x32_bf16 v[96:99], v[174:177], v[196:199], v[96:99]
	v_mfma_f32_16x16x32_bf16 v[84:87], v[162:165], v[200:203], v[84:87]
	v_mfma_f32_16x16x32_bf16 v[84:87], v[166:169], v[204:207], v[84:87]
	v_mfma_f32_16x16x32_bf16 v[80:83], v[170:173], v[200:203], v[80:83]
	v_mfma_f32_16x16x32_bf16 v[80:83], v[174:177], v[204:207], v[80:83]
	v_mfma_f32_16x16x32_bf16 v[68:71], v[162:165], v[208:211], v[68:71]
	v_mfma_f32_16x16x32_bf16 v[68:71], v[166:169], v[212:215], v[68:71]
	s_barrier
	v_mfma_f32_16x16x32_bf16 v[64:67], v[170:173], v[208:211], v[64:67]
	v_mfma_f32_16x16x32_bf16 v[64:67], v[174:177], v[212:215], v[64:67]
	s_setprio 0
	s_add_i32 s54, s75, s58
	v_lshl_add_u64 v[178:179], v[178:179], 0, s[12:13]
	s_mov_b32 m0, s54
	ds_read_b128 v[184:187], v149 offset:49152
	ds_read_b128 v[188:191], v149 offset:50176
	ds_read_b128 v[192:195], v149 offset:51200
	ds_read_b128 v[196:199], v149 offset:52224
	ds_read_b128 v[200:203], v149 offset:53248
	ds_read_b128 v[204:207], v149 offset:54272
	ds_read_b128 v[208:211], v149 offset:55296
	ds_read_b128 v[212:215], v149 offset:56320
	global_load_lds_dwordx4 v[178:179], off
	s_add_i32 m0, s54, 0x2000
	s_add_u32 s52, s52, 0x40080
	v_lshl_add_u64 v[178:179], v[216:217], 0, s[12:13]
	s_addc_u32 s53, s53, 0
	s_add_i32 s54, s76, s58
	global_load_lds_dwordx4 v[178:179], off
	v_lshl_add_u64 v[178:179], s[52:53], 0, v[130:131]
	s_mov_b32 m0, s54
	s_nop 0
	global_load_lds_dwordx4 v[178:179], off
	v_lshl_add_u64 v[178:179], s[52:53], 0, v[128:129]
	s_add_i32 m0, s54, 0x2000
	s_nop 0
	global_load_lds_dwordx4 v[178:179], off
	v_lshl_add_u64 v[178:179], v[218:219], 0, s[12:13]
	s_mov_b32 m0, s64
	s_nop 0
	global_load_lds_dwordx4 v[178:179], off
	v_lshl_add_u64 v[178:179], v[220:221], 0, s[12:13]
	s_mov_b32 m0, s65
	s_nop 0
	global_load_lds_dwordx4 v[178:179], off
	s_waitcnt vmcnt(8)
	s_waitcnt lgkmcnt(0)
	s_barrier
	s_waitcnt lgkmcnt(0)
	v_mfma_f32_16x16x32_bf16 v[60:63], v[140:143], v[184:187], v[60:63]
	v_mfma_f32_16x16x32_bf16 v[60:63], v[150:153], v[188:191], v[60:63]
	s_setprio 1
	v_mfma_f32_16x16x32_bf16 v[56:59], v[154:157], v[184:187], v[56:59]
	v_mfma_f32_16x16x32_bf16 v[56:59], v[158:161], v[188:191], v[56:59]
	v_mfma_f32_16x16x32_bf16 v[44:47], v[140:143], v[192:195], v[44:47]
	v_mfma_f32_16x16x32_bf16 v[44:47], v[150:153], v[196:199], v[44:47]
	v_mfma_f32_16x16x32_bf16 v[40:43], v[154:157], v[192:195], v[40:43]
	v_mfma_f32_16x16x32_bf16 v[40:43], v[158:161], v[196:199], v[40:43]
	v_mfma_f32_16x16x32_bf16 v[28:31], v[140:143], v[200:203], v[28:31]
	v_mfma_f32_16x16x32_bf16 v[28:31], v[150:153], v[204:207], v[28:31]
	v_mfma_f32_16x16x32_bf16 v[24:27], v[154:157], v[200:203], v[24:27]
	v_mfma_f32_16x16x32_bf16 v[24:27], v[158:161], v[204:207], v[24:27]
	v_mfma_f32_16x16x32_bf16 v[12:15], v[140:143], v[208:211], v[12:15]
	v_mfma_f32_16x16x32_bf16 v[12:15], v[150:153], v[212:215], v[12:15]
	v_mfma_f32_16x16x32_bf16 v[8:11], v[154:157], v[208:211], v[8:11]
	v_mfma_f32_16x16x32_bf16 v[8:11], v[158:161], v[212:215], v[8:11]
	v_mfma_f32_16x16x32_bf16 v[52:55], v[162:165], v[184:187], v[52:55]
	v_mfma_f32_16x16x32_bf16 v[52:55], v[166:169], v[188:191], v[52:55]
	v_mfma_f32_16x16x32_bf16 v[48:51], v[170:173], v[184:187], v[48:51]
	v_mfma_f32_16x16x32_bf16 v[48:51], v[174:177], v[188:191], v[48:51]
	v_mfma_f32_16x16x32_bf16 v[36:39], v[162:165], v[192:195], v[36:39]
	v_mfma_f32_16x16x32_bf16 v[36:39], v[166:169], v[196:199], v[36:39]
	v_mfma_f32_16x16x32_bf16 v[32:35], v[170:173], v[192:195], v[32:35]
	v_mfma_f32_16x16x32_bf16 v[32:35], v[174:177], v[196:199], v[32:35]
	v_mfma_f32_16x16x32_bf16 v[20:23], v[162:165], v[200:203], v[20:23]
	v_mfma_f32_16x16x32_bf16 v[20:23], v[166:169], v[204:207], v[20:23]
	v_mfma_f32_16x16x32_bf16 v[16:19], v[170:173], v[200:203], v[16:19]
	v_mfma_f32_16x16x32_bf16 v[16:19], v[174:177], v[204:207], v[16:19]
	v_mfma_f32_16x16x32_bf16 v[4:7], v[162:165], v[208:211], v[4:7]
	v_mfma_f32_16x16x32_bf16 v[4:7], v[166:169], v[212:215], v[4:7]
	s_barrier
	v_mfma_f32_16x16x32_bf16 v[0:3], v[170:173], v[208:211], v[0:3]
	v_mfma_f32_16x16x32_bf16 v[0:3], v[174:177], v[212:215], v[0:3]
	s_setprio 0
	s_add_i32 s74, s74, 2
	s_add_u32 s48, s48, 0x100
	s_addc_u32 s49, s49, 0
	s_add_u32 s72, s72, 0x100
	s_addc_u32 s73, s73, 0
	s_cmp_gt_u32 s74, 13
	s_cbranch_scc0 .LBB0_724
	s_and_b64 vcc, exec, s[16:17]
	s_cbranch_vccz .LBB0_727
	s_barrier
	s_setprio 1
.LBB0_727:
	v_mul_f32_e32 v151, 0xbfb8aa3b, v124
	v_exp_f32_e32 v151, v151
	v_mul_f32_e32 v154, 0xbfb8aa3b, v125
	v_exp_f32_e32 v154, v154
	v_lshl_or_b32 v142, s69, 7, v146
	v_add_f32_e32 v151, 1.0, v151
	v_rcp_f32_e32 v151, v151
	v_lshl_add_u32 v150, s46, 8, v144
	v_ashrrev_i32_e32 v143, 31, v142
	v_mov_b64_e32 v[140:141], s[22:23]
	v_mul_f32_e32 v124, v124, v151
	v_mul_f32_e32 v120, v120, v124
	v_add_f32_e32 v124, 1.0, v154
	v_mul_f32_e32 v151, 0xbfb8aa3b, v126
	v_rcp_f32_e32 v124, v124
	v_exp_f32_e32 v151, v151
	v_mul_f32_e32 v154, 0xbfb8aa3b, v127
	v_exp_f32_e32 v154, v154
	v_mul_f32_e32 v124, v125, v124
	v_add_f32_e32 v125, 1.0, v151
	v_rcp_f32_e32 v125, v125
	v_add_f32_e32 v151, 1.0, v154
	v_rcp_f32_e32 v151, v151
	v_mul_f32_e32 v121, v121, v124
	v_mul_f32_e32 v124, v126, v125
	v_mul_f32_e32 v125, 0xbfb8aa3b, v116
	v_exp_f32_e32 v125, v125
	v_mul_f32_e32 v122, v122, v124
	v_mul_f32_e32 v124, v127, v151
	v_mul_f32_e32 v123, v123, v124
	v_cvt_pk_bf16_f32 v120, v120, v121
	v_cvt_pk_bf16_f32 v121, v122, v123
	v_add_f32_e32 v122, 1.0, v125
	v_rcp_f32_e32 v122, v122
	v_mul_f32_e32 v123, 0xbfb8aa3b, v117
	v_exp_f32_e32 v123, v123
	v_mad_i64_i32 v[152:153], s[48:49], v150, s68, v[140:141]
	v_lshlrev_b64 v[142:143], 1, v[142:143]
	v_lshl_add_u64 v[152:153], v[152:153], 0, v[142:143]
	v_mul_f32_e32 v116, v116, v122
	global_store_dwordx2 v[152:153], v[120:121], off
	v_mul_f32_e32 v112, v112, v116
	v_add_f32_e32 v116, 1.0, v123
	v_mul_f32_e32 v120, 0xbfb8aa3b, v118
	v_rcp_f32_e32 v116, v116
	v_exp_f32_e32 v120, v120
	v_mul_f32_e32 v121, 0xbfb8aa3b, v119
	v_exp_f32_e32 v121, v121
	v_mul_f32_e32 v116, v117, v116
	v_add_f32_e32 v117, 1.0, v120
	v_rcp_f32_e32 v117, v117
	v_add_f32_e32 v120, 1.0, v121
	v_rcp_f32_e32 v120, v120
	v_mul_f32_e32 v113, v113, v116
	v_mul_f32_e32 v116, v118, v117
	v_mul_f32_e32 v114, v114, v116
	v_mul_f32_e32 v116, v119, v120
	v_cvt_pk_bf16_f32 v112, v112, v113
	v_mul_f32_e32 v115, v115, v116
	v_cvt_pk_bf16_f32 v113, v114, v115
	global_store_dwordx2 v[152:153], v[112:113], off offset:128
	v_mul_f32_e32 v112, 0xbfb8aa3b, v108
	v_exp_f32_e32 v114, v112
	v_mul_f32_e32 v115, 0xbfb8aa3b, v109
	v_exp_f32_e32 v115, v115
	v_or_b32_e32 v112, 16, v150
	v_add_f32_e32 v114, 1.0, v114
	v_rcp_f32_e32 v114, v114
	v_mad_i64_i32 v[112:113], s[48:49], v112, s68, v[140:141]
	v_lshl_add_u64 v[112:113], v[112:113], 0, v[142:143]
	v_mul_f32_e32 v108, v108, v114
	v_mul_f32_e32 v104, v104, v108
	v_add_f32_e32 v108, 1.0, v115
	v_mul_f32_e32 v114, 0xbfb8aa3b, v110
	v_rcp_f32_e32 v108, v108
	v_exp_f32_e32 v114, v114
	v_mul_f32_e32 v115, 0xbfb8aa3b, v111
	v_exp_f32_e32 v115, v115
	v_mul_f32_e32 v108, v109, v108
	v_add_f32_e32 v109, 1.0, v114
	v_rcp_f32_e32 v109, v109
	v_add_f32_e32 v114, 1.0, v115
	v_rcp_f32_e32 v114, v114
	v_mul_f32_e32 v105, v105, v108
	v_mul_f32_e32 v108, v110, v109
	v_mul_f32_e32 v109, 0xbfb8aa3b, v100
	v_exp_f32_e32 v109, v109
	v_mul_f32_e32 v106, v106, v108
	v_mul_f32_e32 v108, v111, v114
	v_mul_f32_e32 v107, v107, v108
	v_cvt_pk_bf16_f32 v104, v104, v105
	v_cvt_pk_bf16_f32 v105, v106, v107
	v_add_f32_e32 v106, 1.0, v109
	v_rcp_f32_e32 v106, v106
	v_mul_f32_e32 v107, 0xbfb8aa3b, v101
	v_exp_f32_e32 v107, v107
	global_store_dwordx2 v[112:113], v[104:105], off
	v_mul_f32_e32 v100, v100, v106
	v_mul_f32_e32 v96, v96, v100
	v_add_f32_e32 v100, 1.0, v107
	v_mul_f32_e32 v104, 0xbfb8aa3b, v102
	v_rcp_f32_e32 v100, v100
	v_exp_f32_e32 v104, v104
	v_mul_f32_e32 v105, 0xbfb8aa3b, v103
	v_exp_f32_e32 v105, v105
	v_mul_f32_e32 v100, v101, v100
	v_add_f32_e32 v101, 1.0, v104
	v_rcp_f32_e32 v101, v101
	v_add_f32_e32 v104, 1.0, v105
	v_rcp_f32_e32 v104, v104
	v_mul_f32_e32 v97, v97, v100
	v_mul_f32_e32 v100, v102, v101
	v_mul_f32_e32 v98, v98, v100
	v_mul_f32_e32 v100, v103, v104
	v_cvt_pk_bf16_f32 v96, v96, v97
	v_mul_f32_e32 v99, v99, v100
	v_cvt_pk_bf16_f32 v97, v98, v99
	global_store_dwordx2 v[112:113], v[96:97], off offset:128
	v_mul_f32_e32 v96, 0xbfb8aa3b, v92
	v_exp_f32_e32 v98, v96
	v_mul_f32_e32 v99, 0xbfb8aa3b, v93
	v_exp_f32_e32 v99, v99
	v_or_b32_e32 v96, 32, v150
	v_add_f32_e32 v98, 1.0, v98
	v_rcp_f32_e32 v98, v98
	v_mad_i64_i32 v[96:97], s[48:49], v96, s68, v[140:141]
	v_lshl_add_u64 v[96:97], v[96:97], 0, v[142:143]
	v_mul_f32_e32 v92, v92, v98
	v_mul_f32_e32 v88, v88, v92
	v_add_f32_e32 v92, 1.0, v99
	v_mul_f32_e32 v98, 0xbfb8aa3b, v94
	v_rcp_f32_e32 v92, v92
	v_exp_f32_e32 v98, v98
	v_mul_f32_e32 v99, 0xbfb8aa3b, v95
	v_exp_f32_e32 v99, v99
	v_mul_f32_e32 v92, v93, v92
	v_add_f32_e32 v93, 1.0, v98
	v_rcp_f32_e32 v93, v93
	v_add_f32_e32 v98, 1.0, v99
	v_rcp_f32_e32 v98, v98
	v_mul_f32_e32 v89, v89, v92
	v_mul_f32_e32 v92, v94, v93
	v_mul_f32_e32 v93, 0xbfb8aa3b, v84
	v_exp_f32_e32 v93, v93
	v_mul_f32_e32 v90, v90, v92
	v_mul_f32_e32 v92, v95, v98
	v_mul_f32_e32 v91, v91, v92
	v_cvt_pk_bf16_f32 v88, v88, v89
	v_cvt_pk_bf16_f32 v89, v90, v91
	v_add_f32_e32 v90, 1.0, v93
	v_rcp_f32_e32 v90, v90
	v_mul_f32_e32 v91, 0xbfb8aa3b, v85
	v_exp_f32_e32 v91, v91
	global_store_dwordx2 v[96:97], v[88:89], off
	v_mul_f32_e32 v84, v84, v90
	v_mul_f32_e32 v80, v80, v84
	v_add_f32_e32 v84, 1.0, v91
	v_mul_f32_e32 v88, 0xbfb8aa3b, v86
	v_rcp_f32_e32 v84, v84
	v_exp_f32_e32 v88, v88
	v_mul_f32_e32 v89, 0xbfb8aa3b, v87
	v_exp_f32_e32 v89, v89
	v_mul_f32_e32 v84, v85, v84
	v_add_f32_e32 v85, 1.0, v88
	v_rcp_f32_e32 v85, v85
	v_add_f32_e32 v88, 1.0, v89
	v_rcp_f32_e32 v88, v88
	v_mul_f32_e32 v81, v81, v84
	v_mul_f32_e32 v84, v86, v85
	v_mul_f32_e32 v82, v82, v84
	v_mul_f32_e32 v84, v87, v88
	v_cvt_pk_bf16_f32 v80, v80, v81
	v_mul_f32_e32 v83, v83, v84
	v_cvt_pk_bf16_f32 v81, v82, v83
	global_store_dwordx2 v[96:97], v[80:81], off offset:128
	v_mul_f32_e32 v80, 0xbfb8aa3b, v76
	v_exp_f32_e32 v82, v80
	v_mul_f32_e32 v83, 0xbfb8aa3b, v77
	v_exp_f32_e32 v83, v83
	v_or_b32_e32 v80, 48, v150
	v_add_f32_e32 v82, 1.0, v82
	v_rcp_f32_e32 v82, v82
	v_mad_i64_i32 v[80:81], s[48:49], v80, s68, v[140:141]
	v_lshl_add_u64 v[80:81], v[80:81], 0, v[142:143]
	v_mul_f32_e32 v76, v76, v82
	v_mul_f32_e32 v72, v72, v76
	v_add_f32_e32 v76, 1.0, v83
	v_mul_f32_e32 v82, 0xbfb8aa3b, v78
	v_rcp_f32_e32 v76, v76
	v_exp_f32_e32 v82, v82
	v_mul_f32_e32 v83, 0xbfb8aa3b, v79
	v_exp_f32_e32 v83, v83
	v_mul_f32_e32 v76, v77, v76
	v_add_f32_e32 v77, 1.0, v82
	v_rcp_f32_e32 v77, v77
	v_add_f32_e32 v82, 1.0, v83
	v_rcp_f32_e32 v82, v82
	v_mul_f32_e32 v73, v73, v76
	v_mul_f32_e32 v76, v78, v77
	v_mul_f32_e32 v77, 0xbfb8aa3b, v68
	v_exp_f32_e32 v77, v77
	v_mul_f32_e32 v74, v74, v76
	v_mul_f32_e32 v76, v79, v82
	v_mul_f32_e32 v75, v75, v76
	v_cvt_pk_bf16_f32 v72, v72, v73
	v_cvt_pk_bf16_f32 v73, v74, v75
	v_add_f32_e32 v74, 1.0, v77
	v_rcp_f32_e32 v74, v74
	v_mul_f32_e32 v75, 0xbfb8aa3b, v69
	v_exp_f32_e32 v75, v75
	global_store_dwordx2 v[80:81], v[72:73], off
	v_mul_f32_e32 v68, v68, v74
	v_mul_f32_e32 v64, v64, v68
	v_add_f32_e32 v68, 1.0, v75
	v_mul_f32_e32 v72, 0xbfb8aa3b, v70
	v_rcp_f32_e32 v68, v68
	v_exp_f32_e32 v72, v72
	v_mul_f32_e32 v73, 0xbfb8aa3b, v71
	v_exp_f32_e32 v73, v73
	v_mul_f32_e32 v68, v69, v68
	v_add_f32_e32 v69, 1.0, v72
	v_rcp_f32_e32 v69, v69
	v_add_f32_e32 v72, 1.0, v73
	v_rcp_f32_e32 v72, v72
	v_mul_f32_e32 v65, v65, v68
	v_mul_f32_e32 v68, v70, v69
	v_mul_f32_e32 v66, v66, v68
	v_mul_f32_e32 v68, v71, v72
	v_cvt_pk_bf16_f32 v64, v64, v65
	v_mul_f32_e32 v67, v67, v68
	v_cvt_pk_bf16_f32 v65, v66, v67
	global_store_dwordx2 v[80:81], v[64:65], off offset:128
	v_mul_f32_e32 v64, 0xbfb8aa3b, v60
	v_exp_f32_e32 v66, v64
	v_mul_f32_e32 v67, 0xbfb8aa3b, v61
	v_exp_f32_e32 v67, v67
	v_add_u32_e32 v64, 0x80, v150
	v_add_f32_e32 v66, 1.0, v66
	v_rcp_f32_e32 v66, v66
	v_mad_i64_i32 v[64:65], s[48:49], v64, s68, v[140:141]
	v_lshl_add_u64 v[64:65], v[64:65], 0, v[142:143]
	v_mul_f32_e32 v60, v60, v66
	v_mul_f32_e32 v56, v56, v60
	v_add_f32_e32 v60, 1.0, v67
	v_mul_f32_e32 v66, 0xbfb8aa3b, v62
	v_rcp_f32_e32 v60, v60
	v_exp_f32_e32 v66, v66
	v_mul_f32_e32 v67, 0xbfb8aa3b, v63
	v_exp_f32_e32 v67, v67
	v_mul_f32_e32 v60, v61, v60
	v_add_f32_e32 v61, 1.0, v66
	v_rcp_f32_e32 v61, v61
	v_add_f32_e32 v66, 1.0, v67
	v_rcp_f32_e32 v66, v66
	v_mul_f32_e32 v57, v57, v60
	v_mul_f32_e32 v60, v62, v61
	v_mul_f32_e32 v61, 0xbfb8aa3b, v52
	v_exp_f32_e32 v61, v61
	v_mul_f32_e32 v58, v58, v60
	v_mul_f32_e32 v60, v63, v66
	v_mul_f32_e32 v59, v59, v60
	v_cvt_pk_bf16_f32 v56, v56, v57
	v_cvt_pk_bf16_f32 v57, v58, v59
	v_add_f32_e32 v58, 1.0, v61
	v_rcp_f32_e32 v58, v58
	v_mul_f32_e32 v59, 0xbfb8aa3b, v53
	v_exp_f32_e32 v59, v59
	global_store_dwordx2 v[64:65], v[56:57], off
	v_mul_f32_e32 v52, v52, v58
	v_mul_f32_e32 v48, v48, v52
	v_add_f32_e32 v52, 1.0, v59
	v_mul_f32_e32 v56, 0xbfb8aa3b, v54
	v_rcp_f32_e32 v52, v52
	v_exp_f32_e32 v56, v56
	v_mul_f32_e32 v57, 0xbfb8aa3b, v55
	v_exp_f32_e32 v57, v57
	v_mul_f32_e32 v52, v53, v52
	v_add_f32_e32 v53, 1.0, v56
	v_rcp_f32_e32 v53, v53
	v_add_f32_e32 v56, 1.0, v57
	v_rcp_f32_e32 v56, v56
	v_mul_f32_e32 v49, v49, v52
	v_mul_f32_e32 v52, v54, v53
	v_mul_f32_e32 v50, v50, v52
	v_mul_f32_e32 v52, v55, v56
	v_cvt_pk_bf16_f32 v48, v48, v49
	v_mul_f32_e32 v51, v51, v52
	v_cvt_pk_bf16_f32 v49, v50, v51
	global_store_dwordx2 v[64:65], v[48:49], off offset:128
	v_mul_f32_e32 v48, 0xbfb8aa3b, v44
	v_exp_f32_e32 v50, v48
	v_mul_f32_e32 v51, 0xbfb8aa3b, v45
	v_exp_f32_e32 v51, v51
	v_add_u32_e32 v48, 0x90, v150
	v_add_f32_e32 v50, 1.0, v50
	v_rcp_f32_e32 v50, v50
	v_mad_i64_i32 v[48:49], s[48:49], v48, s68, v[140:141]
	v_lshl_add_u64 v[48:49], v[48:49], 0, v[142:143]
	v_mul_f32_e32 v44, v44, v50
	v_mul_f32_e32 v40, v40, v44
	v_add_f32_e32 v44, 1.0, v51
	v_mul_f32_e32 v50, 0xbfb8aa3b, v46
	v_rcp_f32_e32 v44, v44
	v_exp_f32_e32 v50, v50
	v_mul_f32_e32 v51, 0xbfb8aa3b, v47
	v_exp_f32_e32 v51, v51
	v_mul_f32_e32 v44, v45, v44
	v_add_f32_e32 v45, 1.0, v50
	v_rcp_f32_e32 v45, v45
	v_add_f32_e32 v50, 1.0, v51
	v_rcp_f32_e32 v50, v50
	v_mul_f32_e32 v41, v41, v44
	v_mul_f32_e32 v44, v46, v45
	v_mul_f32_e32 v45, 0xbfb8aa3b, v36
	v_exp_f32_e32 v45, v45
	v_mul_f32_e32 v42, v42, v44
	v_mul_f32_e32 v44, v47, v50
	v_mul_f32_e32 v43, v43, v44
	v_cvt_pk_bf16_f32 v40, v40, v41
	v_cvt_pk_bf16_f32 v41, v42, v43
	v_add_f32_e32 v42, 1.0, v45
	v_rcp_f32_e32 v42, v42
	v_mul_f32_e32 v43, 0xbfb8aa3b, v37
	v_exp_f32_e32 v43, v43
	global_store_dwordx2 v[48:49], v[40:41], off
	v_mul_f32_e32 v36, v36, v42
	v_mul_f32_e32 v32, v32, v36
	v_add_f32_e32 v36, 1.0, v43
	v_mul_f32_e32 v40, 0xbfb8aa3b, v38
	v_rcp_f32_e32 v36, v36
	v_exp_f32_e32 v40, v40
	v_mul_f32_e32 v41, 0xbfb8aa3b, v39
	v_exp_f32_e32 v41, v41
	v_mul_f32_e32 v36, v37, v36
	v_add_f32_e32 v37, 1.0, v40
	v_rcp_f32_e32 v37, v37
	v_add_f32_e32 v40, 1.0, v41
	v_rcp_f32_e32 v40, v40
	v_mul_f32_e32 v33, v33, v36
	v_mul_f32_e32 v36, v38, v37
	v_mul_f32_e32 v34, v34, v36
	v_mul_f32_e32 v36, v39, v40
	v_cvt_pk_bf16_f32 v32, v32, v33
	v_mul_f32_e32 v35, v35, v36
	v_cvt_pk_bf16_f32 v33, v34, v35
	global_store_dwordx2 v[48:49], v[32:33], off offset:128
	v_mul_f32_e32 v32, 0xbfb8aa3b, v28
	v_exp_f32_e32 v34, v32
	v_mul_f32_e32 v35, 0xbfb8aa3b, v29
	v_exp_f32_e32 v35, v35
	v_add_u32_e32 v32, 0xa0, v150
	v_add_f32_e32 v34, 1.0, v34
	v_rcp_f32_e32 v34, v34
	v_mad_i64_i32 v[32:33], s[48:49], v32, s68, v[140:141]
	v_lshl_add_u64 v[32:33], v[32:33], 0, v[142:143]
	v_mul_f32_e32 v28, v28, v34
	v_mul_f32_e32 v24, v24, v28
	v_add_f32_e32 v28, 1.0, v35
	v_mul_f32_e32 v34, 0xbfb8aa3b, v30
	v_rcp_f32_e32 v28, v28
	v_exp_f32_e32 v34, v34
	v_mul_f32_e32 v35, 0xbfb8aa3b, v31
	v_exp_f32_e32 v35, v35
	v_mul_f32_e32 v28, v29, v28
	v_add_f32_e32 v29, 1.0, v34
	v_rcp_f32_e32 v29, v29
	v_add_f32_e32 v34, 1.0, v35
	v_rcp_f32_e32 v34, v34
	v_mul_f32_e32 v25, v25, v28
	v_mul_f32_e32 v28, v30, v29
	v_mul_f32_e32 v29, 0xbfb8aa3b, v20
	v_exp_f32_e32 v29, v29
	v_mul_f32_e32 v26, v26, v28
	v_mul_f32_e32 v28, v31, v34
	v_mul_f32_e32 v27, v27, v28
	v_cvt_pk_bf16_f32 v24, v24, v25
	v_cvt_pk_bf16_f32 v25, v26, v27
	v_add_f32_e32 v26, 1.0, v29
	v_rcp_f32_e32 v26, v26
	v_mul_f32_e32 v27, 0xbfb8aa3b, v21
	v_exp_f32_e32 v27, v27
	global_store_dwordx2 v[32:33], v[24:25], off
	v_mul_f32_e32 v20, v20, v26
	v_mul_f32_e32 v16, v16, v20
	v_add_f32_e32 v20, 1.0, v27
	v_mul_f32_e32 v24, 0xbfb8aa3b, v22
	v_rcp_f32_e32 v20, v20
	v_exp_f32_e32 v24, v24
	v_mul_f32_e32 v25, 0xbfb8aa3b, v23
	v_exp_f32_e32 v25, v25
	v_mul_f32_e32 v20, v21, v20
	v_add_f32_e32 v21, 1.0, v24
	v_rcp_f32_e32 v21, v21
	v_add_f32_e32 v24, 1.0, v25
	v_rcp_f32_e32 v24, v24
	v_mul_f32_e32 v17, v17, v20
	v_mul_f32_e32 v20, v22, v21
	v_mul_f32_e32 v18, v18, v20
	v_mul_f32_e32 v20, v23, v24
	v_cvt_pk_bf16_f32 v16, v16, v17
	v_mul_f32_e32 v19, v19, v20
	v_cvt_pk_bf16_f32 v17, v18, v19
	global_store_dwordx2 v[32:33], v[16:17], off offset:128
	v_mul_f32_e32 v16, 0xbfb8aa3b, v12
	v_exp_f32_e32 v18, v16
	v_mul_f32_e32 v19, 0xbfb8aa3b, v13
	v_exp_f32_e32 v19, v19
	v_add_u32_e32 v16, 0xb0, v150
	v_add_f32_e32 v18, 1.0, v18
	v_rcp_f32_e32 v18, v18
	v_mad_i64_i32 v[16:17], s[48:49], v16, s68, v[140:141]
	v_lshl_add_u64 v[16:17], v[16:17], 0, v[142:143]
	v_mul_f32_e32 v12, v12, v18
	v_mul_f32_e32 v8, v8, v12
	v_add_f32_e32 v12, 1.0, v19
	v_mul_f32_e32 v18, 0xbfb8aa3b, v14
	v_rcp_f32_e32 v12, v12
	v_exp_f32_e32 v18, v18
	v_mul_f32_e32 v19, 0xbfb8aa3b, v15
	v_exp_f32_e32 v19, v19
	v_mul_f32_e32 v12, v13, v12
	v_add_f32_e32 v13, 1.0, v18
	v_rcp_f32_e32 v13, v13
	v_add_f32_e32 v18, 1.0, v19
	v_rcp_f32_e32 v18, v18
	v_mul_f32_e32 v9, v9, v12
	v_mul_f32_e32 v12, v14, v13
	v_mul_f32_e32 v13, 0xbfb8aa3b, v4
	v_exp_f32_e32 v13, v13
	v_mul_f32_e32 v10, v10, v12
	v_mul_f32_e32 v12, v15, v18
	v_mul_f32_e32 v11, v11, v12
	v_cvt_pk_bf16_f32 v8, v8, v9
	v_cvt_pk_bf16_f32 v9, v10, v11
	v_add_f32_e32 v10, 1.0, v13
	v_rcp_f32_e32 v10, v10
	v_mul_f32_e32 v11, 0xbfb8aa3b, v5
	v_exp_f32_e32 v11, v11
	global_store_dwordx2 v[16:17], v[8:9], off
	v_mul_f32_e32 v4, v4, v10
	v_mul_f32_e32 v0, v0, v4
	v_add_f32_e32 v4, 1.0, v11
	v_mul_f32_e32 v8, 0xbfb8aa3b, v6
	v_rcp_f32_e32 v4, v4
	v_exp_f32_e32 v8, v8
	v_mul_f32_e32 v9, 0xbfb8aa3b, v7
	v_exp_f32_e32 v9, v9
	v_mul_f32_e32 v4, v5, v4
	v_add_f32_e32 v5, 1.0, v8
	v_rcp_f32_e32 v5, v5
	v_add_f32_e32 v8, 1.0, v9
	v_rcp_f32_e32 v8, v8
	v_mul_f32_e32 v1, v1, v4
	v_mul_f32_e32 v4, v6, v5
	v_mul_f32_e32 v2, v2, v4
	v_mul_f32_e32 v4, v7, v8
	s_andn2_b64 vcc, exec, s[10:11]
	s_mov_b64 s[10:11], -1
	v_mul_f32_e32 v3, v3, v4
	v_cvt_pk_bf16_f32 v0, v0, v1
	v_cvt_pk_bf16_f32 v1, v2, v3
	global_store_dwordx2 v[16:17], v[0:1], off offset:128
	s_setprio 0
	s_cbranch_vccnz .LBB0_720
	s_andn2_b64 vcc, exec, s[0:1]
	s_cbranch_vccnz .LBB0_719
	s_barrier
	s_branch .LBB0_719

.Lmid_gemm5:
	s_add_i32 s79, 0, 0x18000
	s_add_i32 s87, 0, 0x1c000
	v_add_u32_e32 v164, s79, v147
	v_add_u32_e32 v181, s87, v147
	ds_read_b128 v[152:155], v164
	ds_read_b128 v[156:159], v164 offset:1024
	ds_read_b128 v[160:163], v164 offset:2048
	ds_read_b128 v[164:167], v164 offset:3072
	ds_read_b128 v[168:171], v181
	ds_read_b128 v[172:175], v181 offset:1024
	ds_read_b128 v[176:179], v181 offset:2048
	ds_read_b128 v[184:187], v181 offset:3072
	s_add_u32 s52, s58, 0xb0000
	s_addc_u32 s53, s59, 0
	s_mov_b32 m0, s65
	v_lshl_add_u64 v[226:227], s[52:53], 0, v[128:129]
	ds_read_b128 v[188:191], v151 offset:32768
	ds_read_b128 v[192:195], v151 offset:33792
	ds_read_b128 v[196:199], v151 offset:34816
	ds_read_b128 v[200:203], v151 offset:35840
	ds_read_b128 v[204:207], v151 offset:36864
	ds_read_b128 v[208:211], v151 offset:37888
	ds_read_b128 v[212:215], v151 offset:38912
	ds_read_b128 v[216:219], v151 offset:39936
	global_load_lds_dwordx4 v[226:227], off
	v_lshl_add_u64 v[226:227], s[52:53], 0, v[132:133]
	s_mov_b32 m0, s66
	s_nop 0
	global_load_lds_dwordx4 v[226:227], off
	s_waitcnt vmcnt(8)
	s_waitcnt lgkmcnt(0)
	s_barrier
	s_waitcnt lgkmcnt(0)
	v_mfma_f32_16x16x32_bf16 v[124:127], v[152:155], v[188:191], v[124:127]
	v_mfma_f32_16x16x32_bf16 v[124:127], v[156:159], v[192:195], v[124:127]
	s_setprio 1
	v_mfma_f32_16x16x32_bf16 v[120:123], v[160:163], v[188:191], v[120:123]
	v_mfma_f32_16x16x32_bf16 v[120:123], v[164:167], v[192:195], v[120:123]
	v_mfma_f32_16x16x32_bf16 v[116:119], v[152:155], v[196:199], v[116:119]
	v_mfma_f32_16x16x32_bf16 v[116:119], v[156:159], v[200:203], v[116:119]
	v_mfma_f32_16x16x32_bf16 v[108:111], v[160:163], v[196:199], v[108:111]
	v_mfma_f32_16x16x32_bf16 v[108:111], v[164:167], v[200:203], v[108:111]
	v_mfma_f32_16x16x32_bf16 v[100:103], v[152:155], v[204:207], v[100:103]
	v_mfma_f32_16x16x32_bf16 v[100:103], v[156:159], v[208:211], v[100:103]
	v_mfma_f32_16x16x32_bf16 v[92:95], v[160:163], v[204:207], v[92:95]
	v_mfma_f32_16x16x32_bf16 v[92:95], v[164:167], v[208:211], v[92:95]
	v_mfma_f32_16x16x32_bf16 v[84:87], v[152:155], v[212:215], v[84:87]
	v_mfma_f32_16x16x32_bf16 v[84:87], v[156:159], v[216:219], v[84:87]
	v_mfma_f32_16x16x32_bf16 v[76:79], v[160:163], v[212:215], v[76:79]
	v_mfma_f32_16x16x32_bf16 v[76:79], v[164:167], v[216:219], v[76:79]
	v_mfma_f32_16x16x32_bf16 v[112:115], v[168:171], v[188:191], v[112:115]
	v_mfma_f32_16x16x32_bf16 v[112:115], v[172:175], v[192:195], v[112:115]
	v_mfma_f32_16x16x32_bf16 v[104:107], v[176:179], v[188:191], v[104:107]
	v_mfma_f32_16x16x32_bf16 v[104:107], v[184:187], v[192:195], v[104:107]
	v_mfma_f32_16x16x32_bf16 v[96:99], v[168:171], v[196:199], v[96:99]
	v_mfma_f32_16x16x32_bf16 v[96:99], v[172:175], v[200:203], v[96:99]
	v_mfma_f32_16x16x32_bf16 v[88:91], v[176:179], v[196:199], v[88:91]
	v_mfma_f32_16x16x32_bf16 v[88:91], v[184:187], v[200:203], v[88:91]
	v_mfma_f32_16x16x32_bf16 v[80:83], v[168:171], v[204:207], v[80:83]
	v_mfma_f32_16x16x32_bf16 v[80:83], v[172:175], v[208:211], v[80:83]
	v_mfma_f32_16x16x32_bf16 v[72:75], v[176:179], v[204:207], v[72:75]
	v_mfma_f32_16x16x32_bf16 v[72:75], v[184:187], v[208:211], v[72:75]
	v_mfma_f32_16x16x32_bf16 v[68:71], v[168:171], v[212:215], v[68:71]
	v_mfma_f32_16x16x32_bf16 v[68:71], v[172:175], v[216:219], v[68:71]
	s_barrier
	v_mfma_f32_16x16x32_bf16 v[64:67], v[176:179], v[212:215], v[64:67]
	v_mfma_f32_16x16x32_bf16 v[64:67], v[184:187], v[216:219], v[64:67]
	s_setprio 0
	s_add_i32 s52, s79, s62
	v_lshl_add_u64 v[144:145], v[144:145], 0, s[16:17]
	s_mov_b32 m0, s52
	ds_read_b128 v[188:191], v151 offset:49152
	ds_read_b128 v[192:195], v151 offset:50176
	ds_read_b128 v[196:199], v151 offset:51200
	ds_read_b128 v[200:203], v151 offset:52224
	ds_read_b128 v[204:207], v151 offset:53248
	ds_read_b128 v[208:211], v151 offset:54272
	ds_read_b128 v[212:215], v151 offset:55296
	ds_read_b128 v[216:219], v151 offset:56320
	global_load_lds_dwordx4 v[144:145], off
	s_add_i32 m0, s52, 0x2000
	s_add_u32 s52, s56, 0xb0080
	v_lshl_add_u64 v[144:145], v[220:221], 0, s[16:17]
	s_addc_u32 s53, s57, 0
	s_add_i32 s56, s87, s62
	global_load_lds_dwordx4 v[144:145], off
	v_lshl_add_u64 v[144:145], s[52:53], 0, v[130:131]
	s_mov_b32 m0, s56
	s_nop 0
	global_load_lds_dwordx4 v[144:145], off
	v_lshl_add_u64 v[144:145], s[52:53], 0, v[134:135]
	s_add_i32 m0, s56, 0x2000
	s_nop 0
	global_load_lds_dwordx4 v[144:145], off
	v_lshl_add_u64 v[144:145], v[222:223], 0, s[16:17]
	s_mov_b32 m0, s68
	s_nop 0
	global_load_lds_dwordx4 v[144:145], off
	v_lshl_add_u64 v[144:145], v[224:225], 0, s[16:17]
	s_mov_b32 m0, s69
	s_nop 0
	global_load_lds_dwordx4 v[144:145], off
	s_waitcnt vmcnt(8)
	s_waitcnt lgkmcnt(0)
	s_barrier
	s_waitcnt lgkmcnt(0)
	v_mfma_f32_16x16x32_bf16 v[60:63], v[152:155], v[188:191], v[60:63]
	v_mfma_f32_16x16x32_bf16 v[60:63], v[156:159], v[192:195], v[60:63]
	s_setprio 1
	v_mfma_f32_16x16x32_bf16 v[56:59], v[160:163], v[188:191], v[56:59]
	v_mfma_f32_16x16x32_bf16 v[56:59], v[164:167], v[192:195], v[56:59]
	v_mfma_f32_16x16x32_bf16 v[52:55], v[152:155], v[196:199], v[52:55]
	v_mfma_f32_16x16x32_bf16 v[52:55], v[156:159], v[200:203], v[52:55]
	v_mfma_f32_16x16x32_bf16 v[44:47], v[160:163], v[196:199], v[44:47]
	v_mfma_f32_16x16x32_bf16 v[44:47], v[164:167], v[200:203], v[44:47]
	v_mfma_f32_16x16x32_bf16 v[36:39], v[152:155], v[204:207], v[36:39]
	v_mfma_f32_16x16x32_bf16 v[36:39], v[156:159], v[208:211], v[36:39]
	v_mfma_f32_16x16x32_bf16 v[28:31], v[160:163], v[204:207], v[28:31]
	v_mfma_f32_16x16x32_bf16 v[28:31], v[164:167], v[208:211], v[28:31]
	v_mfma_f32_16x16x32_bf16 v[20:23], v[152:155], v[212:215], v[20:23]
	v_mfma_f32_16x16x32_bf16 v[20:23], v[156:159], v[216:219], v[20:23]
	v_mfma_f32_16x16x32_bf16 v[12:15], v[160:163], v[212:215], v[12:15]
	v_mfma_f32_16x16x32_bf16 v[12:15], v[164:167], v[216:219], v[12:15]
	v_mfma_f32_16x16x32_bf16 v[48:51], v[168:171], v[188:191], v[48:51]
	v_mfma_f32_16x16x32_bf16 v[48:51], v[172:175], v[192:195], v[48:51]
	v_mfma_f32_16x16x32_bf16 v[40:43], v[176:179], v[188:191], v[40:43]
	v_mfma_f32_16x16x32_bf16 v[40:43], v[184:187], v[192:195], v[40:43]
	v_mfma_f32_16x16x32_bf16 v[32:35], v[168:171], v[196:199], v[32:35]
	v_mfma_f32_16x16x32_bf16 v[32:35], v[172:175], v[200:203], v[32:35]
	v_mfma_f32_16x16x32_bf16 v[24:27], v[176:179], v[196:199], v[24:27]
	v_mfma_f32_16x16x32_bf16 v[24:27], v[184:187], v[200:203], v[24:27]
	v_mfma_f32_16x16x32_bf16 v[16:19], v[168:171], v[204:207], v[16:19]
	v_mfma_f32_16x16x32_bf16 v[16:19], v[172:175], v[208:211], v[16:19]
	v_mfma_f32_16x16x32_bf16 v[8:11], v[176:179], v[204:207], v[8:11]
	v_mfma_f32_16x16x32_bf16 v[8:11], v[184:187], v[208:211], v[8:11]
	v_mfma_f32_16x16x32_bf16 v[4:7], v[168:171], v[212:215], v[4:7]
	v_mfma_f32_16x16x32_bf16 v[4:7], v[172:175], v[216:219], v[4:7]
	s_barrier
	v_mfma_f32_16x16x32_bf16 v[0:3], v[176:179], v[212:215], v[0:3]
	v_mfma_f32_16x16x32_bf16 v[0:3], v[184:187], v[216:219], v[0:3]
	s_setprio 0
	s_add_i32 s86, s86, 2
	s_add_u32 s84, s84, 0x100
	s_addc_u32 s85, s85, 0
	s_cmp_gt_u32 s86, 41
	s_mov_b64 s[52:53], s[54:55]
	s_cbranch_scc0 .LBB0_804
	s_and_b64 vcc, exec, s[18:19]
	s_cbranch_vccz .LBB0_807
	s_barrier
	s_setprio 1
.LBB0_807:
	v_lshl_add_u32 v152, s82, 8, v146
	v_lshl_or_b32 v144, s83, 8, v148
	v_ashrrev_i32_e32 v145, 31, v144
	v_ashrrev_i32_e32 v153, 31, v152
	v_lshl_add_u64 v[154:155], v[144:145], 1, s[24:25]
	v_lshlrev_b64 v[144:145], 11, v[152:153]
	v_lshl_add_u64 v[144:145], v[154:155], 0, v[144:145]
	s_nop 15
	s_nop 7
	v_cvt_pk_bf16_f32 v124, v124, v125
	v_cvt_pk_bf16_f32 v125, v126, v127
	v_cvt_pk_bf16_f32 v126, v120, v121
	v_cvt_pk_bf16_f32 v127, v122, v123
	global_store_dwordx4 v[144:145], v[124:127], off
	v_cvt_pk_bf16_f32 v112, v112, v113
	v_cvt_pk_bf16_f32 v113, v114, v115
	v_cvt_pk_bf16_f32 v114, v104, v105
	v_or_b32_e32 v104, 16, v152
	v_ashrrev_i32_e32 v105, 31, v104
	v_lshlrev_b64 v[104:105], 11, v[104:105]
	v_cvt_pk_bf16_f32 v115, v106, v107
	global_store_dwordx4 v[144:145], v[112:115], off offset:256
	s_nop 1
	v_lshl_add_u64 v[112:113], v[154:155], 0, v[104:105]
	v_cvt_pk_bf16_f32 v104, v116, v117
	v_cvt_pk_bf16_f32 v105, v118, v119
	v_cvt_pk_bf16_f32 v106, v108, v109
	v_cvt_pk_bf16_f32 v107, v110, v111
	global_store_dwordx4 v[112:113], v[104:107], off
	v_cvt_pk_bf16_f32 v96, v96, v97
	v_cvt_pk_bf16_f32 v97, v98, v99
	v_cvt_pk_bf16_f32 v98, v88, v89
	v_or_b32_e32 v88, 32, v152
	v_ashrrev_i32_e32 v89, 31, v88
	v_lshlrev_b64 v[88:89], 11, v[88:89]
	v_cvt_pk_bf16_f32 v99, v90, v91
	global_store_dwordx4 v[112:113], v[96:99], off offset:256
	s_nop 1
	v_lshl_add_u64 v[96:97], v[154:155], 0, v[88:89]
	v_cvt_pk_bf16_f32 v88, v100, v101
	v_cvt_pk_bf16_f32 v89, v102, v103
	v_cvt_pk_bf16_f32 v90, v92, v93
	v_cvt_pk_bf16_f32 v91, v94, v95
	global_store_dwordx4 v[96:97], v[88:91], off
	v_cvt_pk_bf16_f32 v80, v80, v81
	v_cvt_pk_bf16_f32 v81, v82, v83
	v_cvt_pk_bf16_f32 v82, v72, v73
	v_or_b32_e32 v72, 48, v152
	v_ashrrev_i32_e32 v73, 31, v72
	v_lshlrev_b64 v[72:73], 11, v[72:73]
	v_cvt_pk_bf16_f32 v83, v74, v75
	global_store_dwordx4 v[96:97], v[80:83], off offset:256
	s_nop 1
	v_lshl_add_u64 v[80:81], v[154:155], 0, v[72:73]
	v_cvt_pk_bf16_f32 v72, v84, v85
	v_cvt_pk_bf16_f32 v73, v86, v87
	v_cvt_pk_bf16_f32 v74, v76, v77
	v_cvt_pk_bf16_f32 v75, v78, v79
	global_store_dwordx4 v[80:81], v[72:75], off
	v_cvt_pk_bf16_f32 v68, v68, v69
	v_cvt_pk_bf16_f32 v69, v70, v71
	v_cvt_pk_bf16_f32 v70, v64, v65
	v_cvt_pk_bf16_f32 v71, v66, v67
	global_store_dwordx4 v[80:81], v[68:71], off offset:256
	v_cvt_pk_bf16_f32 v60, v60, v61
	v_cvt_pk_bf16_f32 v61, v62, v63
	v_cvt_pk_bf16_f32 v62, v56, v57
	v_add_co_u32_e32 v56, vcc, s72, v144
	v_lshl_add_u64 v[64:65], v[144:145], 0, s[30:31]
	s_nop 0
	v_addc_co_u32_e32 v57, vcc, 0, v145, vcc
	v_cvt_pk_bf16_f32 v63, v58, v59
	global_store_dwordx4 v[56:57], v[60:63], off
	v_cvt_pk_bf16_f32 v48, v48, v49
	v_cvt_pk_bf16_f32 v49, v50, v51
	v_cvt_pk_bf16_f32 v50, v40, v41
	v_cvt_pk_bf16_f32 v51, v42, v43
	global_store_dwordx4 v[64:65], v[48:51], off offset:256
	v_cvt_pk_bf16_f32 v40, v52, v53
	v_cvt_pk_bf16_f32 v41, v54, v55
	v_cvt_pk_bf16_f32 v42, v44, v45
	v_add_co_u32_e32 v44, vcc, s73, v144
	s_nop 0
	v_lshl_add_u64 v[48:49], v[144:145], 0, s[36:37]
	v_addc_co_u32_e32 v45, vcc, 0, v145, vcc
	v_cvt_pk_bf16_f32 v43, v46, v47
	global_store_dwordx4 v[44:45], v[40:43], off
	v_cvt_pk_bf16_f32 v32, v32, v33
	v_cvt_pk_bf16_f32 v33, v34, v35
	v_cvt_pk_bf16_f32 v34, v24, v25
	v_cvt_pk_bf16_f32 v35, v26, v27
	global_store_dwordx4 v[48:49], v[32:35], off offset:256
	v_cvt_pk_bf16_f32 v24, v36, v37
	v_cvt_pk_bf16_f32 v25, v38, v39
	v_cvt_pk_bf16_f32 v26, v28, v29
	v_add_co_u32_e32 v28, vcc, s74, v144
	s_nop 0
	v_lshl_add_u64 v[32:33], v[144:145], 0, s[44:45]
	v_addc_co_u32_e32 v29, vcc, 0, v145, vcc
	v_cvt_pk_bf16_f32 v27, v30, v31
	global_store_dwordx4 v[28:29], v[24:27], off
	v_cvt_pk_bf16_f32 v16, v16, v17
	v_cvt_pk_bf16_f32 v17, v18, v19
	v_cvt_pk_bf16_f32 v18, v8, v9
	v_cvt_pk_bf16_f32 v19, v10, v11
	global_store_dwordx4 v[32:33], v[16:19], off offset:256
	v_cvt_pk_bf16_f32 v8, v20, v21
	v_cvt_pk_bf16_f32 v9, v22, v23
	v_cvt_pk_bf16_f32 v10, v12, v13
	v_add_co_u32_e32 v12, vcc, s75, v144
	s_nop 0
	v_lshl_add_u64 v[16:17], v[144:145], 0, s[46:47]
	v_addc_co_u32_e32 v13, vcc, 0, v145, vcc
	s_and_b64 vcc, exec, s[10:11]
	s_mov_b64 s[10:11], -1
	v_cvt_pk_bf16_f32 v11, v14, v15
	global_store_dwordx4 v[12:13], v[8:11], off
	v_cvt_pk_bf16_f32 v4, v4, v5
	v_cvt_pk_bf16_f32 v5, v6, v7
	v_cvt_pk_bf16_f32 v6, v0, v1
	v_cvt_pk_bf16_f32 v7, v2, v3
	global_store_dwordx4 v[16:17], v[4:7], off offset:256
	s_setprio 0
	s_cbranch_vccnz .LBB0_792
	s_andn2_b64 vcc, exec, s[0:1]
	s_cbranch_vccnz .LBB0_791
	s_barrier
	s_branch .LBB0_791

.Lmid_gemm6:
	s_add_i32 s79, 0, 0x18000
	v_add_u32_e32 v151, s79, v147
	s_add_i32 s88, 0, 0x1c000
	ds_read_b128 v[152:155], v151
	ds_read_b128 v[156:159], v151 offset:1024
	ds_read_b128 v[160:163], v151 offset:2048
	ds_read_b128 v[164:167], v151 offset:3072
	v_add_u32_e32 v151, s88, v147
	ds_read_b128 v[168:171], v151
	ds_read_b128 v[172:175], v151 offset:1024
	ds_read_b128 v[176:179], v151 offset:2048
	ds_read_b128 v[184:187], v151 offset:3072
	s_add_u32 s64, s64, 0x40000
	s_addc_u32 s65, s65, 0
	s_mov_b32 m0, s71
	v_lshl_add_u64 v[228:229], s[64:65], 0, v[128:129]
	ds_read_b128 v[188:191], v150 offset:32768
	ds_read_b128 v[192:195], v150 offset:33792
	ds_read_b128 v[196:199], v150 offset:34816
	ds_read_b128 v[200:203], v150 offset:35840
	ds_read_b128 v[204:207], v150 offset:36864
	ds_read_b128 v[208:211], v150 offset:37888
	ds_read_b128 v[212:215], v150 offset:38912
	ds_read_b128 v[216:219], v150 offset:39936
	global_load_lds_dwordx4 v[228:229], off
	v_lshl_add_u64 v[228:229], s[64:65], 0, v[132:133]
	s_mov_b32 m0, s72
	s_nop 0
	global_load_lds_dwordx4 v[228:229], off
	s_waitcnt vmcnt(8)
	s_waitcnt lgkmcnt(0)
	s_barrier
	s_waitcnt lgkmcnt(0)
	v_mfma_f32_16x16x32_bf16 v[124:127], v[152:155], v[188:191], v[124:127]
	v_mfma_f32_16x16x32_bf16 v[124:127], v[156:159], v[192:195], v[124:127]
	s_setprio 1
	v_mfma_f32_16x16x32_bf16 v[120:123], v[160:163], v[188:191], v[120:123]
	v_mfma_f32_16x16x32_bf16 v[120:123], v[164:167], v[192:195], v[120:123]
	v_mfma_f32_16x16x32_bf16 v[116:119], v[152:155], v[196:199], v[116:119]
	v_mfma_f32_16x16x32_bf16 v[116:119], v[156:159], v[200:203], v[116:119]
	v_mfma_f32_16x16x32_bf16 v[112:115], v[160:163], v[196:199], v[112:115]
	v_mfma_f32_16x16x32_bf16 v[112:115], v[164:167], v[200:203], v[112:115]
	v_mfma_f32_16x16x32_bf16 v[108:111], v[152:155], v[204:207], v[108:111]
	v_mfma_f32_16x16x32_bf16 v[108:111], v[156:159], v[208:211], v[108:111]
	v_mfma_f32_16x16x32_bf16 v[104:107], v[160:163], v[204:207], v[104:107]
	v_mfma_f32_16x16x32_bf16 v[104:107], v[164:167], v[208:211], v[104:107]
	v_mfma_f32_16x16x32_bf16 v[100:103], v[152:155], v[212:215], v[100:103]
	v_mfma_f32_16x16x32_bf16 v[100:103], v[156:159], v[216:219], v[100:103]
	v_mfma_f32_16x16x32_bf16 v[96:99], v[160:163], v[212:215], v[96:99]
	v_mfma_f32_16x16x32_bf16 v[96:99], v[164:167], v[216:219], v[96:99]
	v_mfma_f32_16x16x32_bf16 v[76:79], v[168:171], v[188:191], v[76:79]
	v_mfma_f32_16x16x32_bf16 v[76:79], v[172:175], v[192:195], v[76:79]
	v_mfma_f32_16x16x32_bf16 v[68:71], v[176:179], v[188:191], v[68:71]
	v_mfma_f32_16x16x32_bf16 v[68:71], v[184:187], v[192:195], v[68:71]
	v_mfma_f32_16x16x32_bf16 v[60:63], v[168:171], v[196:199], v[60:63]
	v_mfma_f32_16x16x32_bf16 v[60:63], v[172:175], v[200:203], v[60:63]
	v_mfma_f32_16x16x32_bf16 v[52:55], v[176:179], v[196:199], v[52:55]
	v_mfma_f32_16x16x32_bf16 v[52:55], v[184:187], v[200:203], v[52:55]
	v_mfma_f32_16x16x32_bf16 v[44:47], v[168:171], v[204:207], v[44:47]
	v_mfma_f32_16x16x32_bf16 v[44:47], v[172:175], v[208:211], v[44:47]
	v_mfma_f32_16x16x32_bf16 v[40:43], v[176:179], v[204:207], v[40:43]
	v_mfma_f32_16x16x32_bf16 v[40:43], v[184:187], v[208:211], v[40:43]
	v_mfma_f32_16x16x32_bf16 v[36:39], v[168:171], v[212:215], v[36:39]
	v_mfma_f32_16x16x32_bf16 v[36:39], v[172:175], v[216:219], v[36:39]
	s_barrier
	v_mfma_f32_16x16x32_bf16 v[32:35], v[176:179], v[212:215], v[32:35]
	v_mfma_f32_16x16x32_bf16 v[32:35], v[184:187], v[216:219], v[32:35]
	s_setprio 0
	s_add_i32 s64, s79, s68
	v_lshl_add_u64 v[220:221], v[220:221], 0, s[12:13]
	s_mov_b32 m0, s64
	ds_read_b128 v[188:191], v150 offset:49152
	ds_read_b128 v[192:195], v150 offset:50176
	ds_read_b128 v[196:199], v150 offset:51200
	ds_read_b128 v[200:203], v150 offset:52224
	ds_read_b128 v[204:207], v150 offset:53248
	ds_read_b128 v[208:211], v150 offset:54272
	ds_read_b128 v[212:215], v150 offset:55296
	ds_read_b128 v[216:219], v150 offset:56320
	global_load_lds_dwordx4 v[220:221], off
	s_add_i32 m0, s64, 0x2000
	s_add_u32 s62, s62, 0x40080
	v_lshl_add_u64 v[220:221], v[222:223], 0, s[12:13]
	s_addc_u32 s63, s63, 0
	s_add_i32 s64, s88, s68
	global_load_lds_dwordx4 v[220:221], off
	v_lshl_add_u64 v[220:221], s[62:63], 0, v[130:131]
	s_mov_b32 m0, s64
	s_nop 0
	global_load_lds_dwordx4 v[220:221], off
	v_lshl_add_u64 v[220:221], s[62:63], 0, v[134:135]
	s_add_i32 m0, s64, 0x2000
	s_nop 0
	global_load_lds_dwordx4 v[220:221], off
	v_lshl_add_u64 v[220:221], v[224:225], 0, s[12:13]
	s_mov_b32 m0, s75
	s_nop 0
	global_load_lds_dwordx4 v[220:221], off
	v_lshl_add_u64 v[220:221], v[226:227], 0, s[12:13]
	s_mov_b32 m0, s76
	s_nop 0
	global_load_lds_dwordx4 v[220:221], off
	s_waitcnt vmcnt(8)
	s_waitcnt lgkmcnt(0)
	s_barrier
	s_waitcnt lgkmcnt(0)
	v_mfma_f32_16x16x32_bf16 v[92:95], v[152:155], v[188:191], v[92:95]
	v_mfma_f32_16x16x32_bf16 v[92:95], v[156:159], v[192:195], v[92:95]
	s_setprio 1
	v_mfma_f32_16x16x32_bf16 v[88:91], v[160:163], v[188:191], v[88:91]
	v_mfma_f32_16x16x32_bf16 v[88:91], v[164:167], v[192:195], v[88:91]
	v_mfma_f32_16x16x32_bf16 v[84:87], v[152:155], v[196:199], v[84:87]
	v_mfma_f32_16x16x32_bf16 v[84:87], v[156:159], v[200:203], v[84:87]
	v_mfma_f32_16x16x32_bf16 v[80:83], v[160:163], v[196:199], v[80:83]
	v_mfma_f32_16x16x32_bf16 v[80:83], v[164:167], v[200:203], v[80:83]
	v_mfma_f32_16x16x32_bf16 v[72:75], v[152:155], v[204:207], v[72:75]
	v_mfma_f32_16x16x32_bf16 v[72:75], v[156:159], v[208:211], v[72:75]
	v_mfma_f32_16x16x32_bf16 v[64:67], v[160:163], v[204:207], v[64:67]
	v_mfma_f32_16x16x32_bf16 v[64:67], v[164:167], v[208:211], v[64:67]
	v_mfma_f32_16x16x32_bf16 v[56:59], v[152:155], v[212:215], v[56:59]
	v_mfma_f32_16x16x32_bf16 v[56:59], v[156:159], v[216:219], v[56:59]
	v_mfma_f32_16x16x32_bf16 v[48:51], v[160:163], v[212:215], v[48:51]
	v_mfma_f32_16x16x32_bf16 v[48:51], v[164:167], v[216:219], v[48:51]
	v_mfma_f32_16x16x32_bf16 v[28:31], v[168:171], v[188:191], v[28:31]
	v_mfma_f32_16x16x32_bf16 v[28:31], v[172:175], v[192:195], v[28:31]
	v_mfma_f32_16x16x32_bf16 v[24:27], v[176:179], v[188:191], v[24:27]
	v_mfma_f32_16x16x32_bf16 v[24:27], v[184:187], v[192:195], v[24:27]
	v_mfma_f32_16x16x32_bf16 v[20:23], v[168:171], v[196:199], v[20:23]
	v_mfma_f32_16x16x32_bf16 v[20:23], v[172:175], v[200:203], v[20:23]
	v_mfma_f32_16x16x32_bf16 v[16:19], v[176:179], v[196:199], v[16:19]
	v_mfma_f32_16x16x32_bf16 v[16:19], v[184:187], v[200:203], v[16:19]
	v_mfma_f32_16x16x32_bf16 v[12:15], v[168:171], v[204:207], v[12:15]
	v_mfma_f32_16x16x32_bf16 v[12:15], v[172:175], v[208:211], v[12:15]
	v_mfma_f32_16x16x32_bf16 v[8:11], v[176:179], v[204:207], v[8:11]
	v_mfma_f32_16x16x32_bf16 v[8:11], v[184:187], v[208:211], v[8:11]
	v_mfma_f32_16x16x32_bf16 v[4:7], v[168:171], v[212:215], v[4:7]
	v_mfma_f32_16x16x32_bf16 v[4:7], v[172:175], v[216:219], v[4:7]
	s_barrier
	v_mfma_f32_16x16x32_bf16 v[0:3], v[176:179], v[212:215], v[0:3]
	v_mfma_f32_16x16x32_bf16 v[0:3], v[184:187], v[216:219], v[0:3]
	s_setprio 0
	s_add_i32 s87, s87, 2
	s_add_u32 s60, s60, 0x100
	s_addc_u32 s61, s61, 0
	s_add_u32 s85, s85, 0x100
	s_addc_u32 s86, s86, 0
	s_cmp_gt_u32 s87, 13
	s_cbranch_scc0 .LBB0_935
	s_and_b64 vcc, exec, s[16:17]
	s_cbranch_vccz .LBB0_938
	s_barrier
	s_setprio 1
.LBB0_938:
	s_lshl_b32 s49, s59, 8
	s_or_b32 s49, s49, s74
	v_lshl_add_u32 v152, s58, 8, v146
	s_ashr_i32 s58, s49, 6
	s_ashr_i32 s59, s58, 31
	s_lshl_b64 s[60:61], s[58:59], 22
	v_ashrrev_i32_e32 v153, 31, v152
	v_lshl_add_u64 v[154:155], v[136:137], 0, s[60:61]
	v_cvt_pk_bf16_f32 v124, v124, v125
	v_cvt_pk_bf16_f32 v125, v126, v127
	v_cvt_pk_bf16_f32 v126, v120, v121
	v_lshlrev_b64 v[120:121], 7, v[152:153]
	v_cvt_pk_bf16_f32 v127, v122, v123
	v_lshl_add_u64 v[122:123], v[154:155], 0, v[120:121]
	global_store_dwordx4 v[122:123], v[124:127], off
	v_cvt_pk_bf16_f32 v116, v116, v117
	v_cvt_pk_bf16_f32 v117, v118, v119
	v_cvt_pk_bf16_f32 v118, v112, v113
	v_or_b32_e32 v112, 16, v152
	v_ashrrev_i32_e32 v113, 31, v112
	v_lshlrev_b64 v[112:113], 7, v[112:113]
	v_cvt_pk_bf16_f32 v119, v114, v115
	v_lshl_add_u64 v[114:115], v[154:155], 0, v[112:113]
	global_store_dwordx4 v[114:115], v[116:119], off
	v_cvt_pk_bf16_f32 v108, v108, v109
	v_cvt_pk_bf16_f32 v109, v110, v111
	v_cvt_pk_bf16_f32 v110, v104, v105
	v_or_b32_e32 v104, 32, v152
	v_ashrrev_i32_e32 v105, 31, v104
	v_lshlrev_b64 v[104:105], 7, v[104:105]
	v_cvt_pk_bf16_f32 v111, v106, v107
	v_lshl_add_u64 v[106:107], v[154:155], 0, v[104:105]
	global_store_dwordx4 v[106:107], v[108:111], off
	v_cvt_pk_bf16_f32 v100, v100, v101
	v_cvt_pk_bf16_f32 v101, v102, v103
	v_cvt_pk_bf16_f32 v102, v96, v97
	v_or_b32_e32 v96, 48, v152
	v_ashrrev_i32_e32 v97, 31, v96
	v_lshlrev_b64 v[96:97], 7, v[96:97]
	v_cvt_pk_bf16_f32 v103, v98, v99
	v_lshl_add_u64 v[98:99], v[154:155], 0, v[96:97]
	global_store_dwordx4 v[98:99], v[100:103], off
	v_cvt_pk_bf16_f32 v92, v92, v93
	v_cvt_pk_bf16_f32 v93, v94, v95
	v_cvt_pk_bf16_f32 v94, v88, v89
	v_lshl_add_u64 v[88:89], v[120:121], 0, s[18:19]
	v_cvt_pk_bf16_f32 v95, v90, v91
	v_lshl_add_u64 v[90:91], v[154:155], 0, v[88:89]
	global_store_dwordx4 v[90:91], v[92:95], off
	v_cvt_pk_bf16_f32 v84, v84, v85
	v_cvt_pk_bf16_f32 v85, v86, v87
	v_cvt_pk_bf16_f32 v86, v80, v81
	v_lshl_add_u64 v[80:81], v[120:121], 0, s[36:37]
	v_cvt_pk_bf16_f32 v87, v82, v83
	v_lshl_add_u64 v[82:83], v[154:155], 0, v[80:81]
	global_store_dwordx4 v[82:83], v[84:87], off
	v_cvt_pk_bf16_f32 v72, v72, v73
	v_cvt_pk_bf16_f32 v73, v74, v75
	v_cvt_pk_bf16_f32 v74, v64, v65
	v_lshl_add_u64 v[64:65], v[120:121], 0, s[44:45]
	v_cvt_pk_bf16_f32 v75, v66, v67
	v_lshl_add_u64 v[66:67], v[154:155], 0, v[64:65]
	s_or_b32 s58, s58, 2
	global_store_dwordx4 v[66:67], v[72:75], off
	v_lshl_add_u64 v[66:67], v[120:121], 0, s[46:47]
	s_ashr_i32 s59, s58, 31
	v_cvt_pk_bf16_f32 v56, v56, v57
	v_cvt_pk_bf16_f32 v57, v58, v59
	v_cvt_pk_bf16_f32 v58, v48, v49
	v_lshl_add_u64 v[48:49], v[154:155], 0, v[66:67]
	s_lshl_b64 s[58:59], s[58:59], 22
	v_cvt_pk_bf16_f32 v59, v50, v51
	global_store_dwordx4 v[48:49], v[56:59], off
	v_cvt_pk_bf16_f32 v48, v76, v77
	v_cvt_pk_bf16_f32 v49, v78, v79
	v_cvt_pk_bf16_f32 v50, v68, v69
	v_cvt_pk_bf16_f32 v51, v70, v71
	s_andn2_b64 vcc, exec, s[10:11]
	s_nop 0
	v_lshl_add_u64 v[56:57], v[136:137], 0, s[58:59]
	v_lshl_add_u64 v[58:59], v[56:57], 0, v[120:121]
	global_store_dwordx4 v[58:59], v[48:51], off
	s_mov_b64 s[10:11], -1
	s_nop 0
	v_cvt_pk_bf16_f32 v48, v60, v61
	v_cvt_pk_bf16_f32 v49, v62, v63
	v_cvt_pk_bf16_f32 v50, v52, v53
	v_lshl_add_u64 v[52:53], v[56:57], 0, v[112:113]
	v_cvt_pk_bf16_f32 v51, v54, v55
	global_store_dwordx4 v[52:53], v[48:51], off
	v_cvt_pk_bf16_f32 v44, v44, v45
	v_cvt_pk_bf16_f32 v45, v46, v47
	v_cvt_pk_bf16_f32 v46, v40, v41
	v_lshl_add_u64 v[40:41], v[56:57], 0, v[104:105]
	v_cvt_pk_bf16_f32 v47, v42, v43
	global_store_dwordx4 v[40:41], v[44:47], off
	v_cvt_pk_bf16_f32 v36, v36, v37
	v_cvt_pk_bf16_f32 v37, v38, v39
	v_cvt_pk_bf16_f32 v38, v32, v33
	v_lshl_add_u64 v[32:33], v[56:57], 0, v[96:97]
	v_cvt_pk_bf16_f32 v39, v34, v35
	global_store_dwordx4 v[32:33], v[36:39], off
	v_cvt_pk_bf16_f32 v28, v28, v29
	v_cvt_pk_bf16_f32 v29, v30, v31
	v_cvt_pk_bf16_f32 v30, v24, v25
	v_lshl_add_u64 v[24:25], v[56:57], 0, v[88:89]
	v_cvt_pk_bf16_f32 v31, v26, v27
	global_store_dwordx4 v[24:25], v[28:31], off
	v_cvt_pk_bf16_f32 v20, v20, v21
	v_cvt_pk_bf16_f32 v21, v22, v23
	v_cvt_pk_bf16_f32 v22, v16, v17
	v_lshl_add_u64 v[16:17], v[56:57], 0, v[80:81]
	v_cvt_pk_bf16_f32 v23, v18, v19
	global_store_dwordx4 v[16:17], v[20:23], off
	v_cvt_pk_bf16_f32 v12, v12, v13
	v_cvt_pk_bf16_f32 v13, v14, v15
	v_cvt_pk_bf16_f32 v14, v8, v9
	v_lshl_add_u64 v[8:9], v[56:57], 0, v[64:65]
	v_cvt_pk_bf16_f32 v15, v10, v11
	global_store_dwordx4 v[8:9], v[12:15], off
	v_cvt_pk_bf16_f32 v4, v4, v5
	v_cvt_pk_bf16_f32 v5, v6, v7
	v_cvt_pk_bf16_f32 v6, v0, v1
	v_lshl_add_u64 v[0:1], v[56:57], 0, v[66:67]
	v_cvt_pk_bf16_f32 v7, v2, v3
	global_store_dwordx4 v[0:1], v[4:7], off
	s_setprio 0
	s_cbranch_vccnz .LBB0_927
	s_andn2_b64 vcc, exec, s[0:1]
	s_cbranch_vccnz .LBB0_926
	s_barrier
	s_branch .LBB0_926

.Lmid_gemm7:
	s_add_i32 s77, 0, 0x18000
	s_add_i32 s79, 0, 0x1c000
	v_add_u32_e32 v158, s77, v145
	v_add_u32_e32 v174, s79, v145
	ds_read_b128 v[140:143], v158
	ds_read_b128 v[150:153], v158 offset:1024
	ds_read_b128 v[154:157], v158 offset:2048
	ds_read_b128 v[158:161], v158 offset:3072
	ds_read_b128 v[162:165], v174
	ds_read_b128 v[166:169], v174 offset:1024
	ds_read_b128 v[170:173], v174 offset:2048
	ds_read_b128 v[174:177], v174 offset:3072
	s_add_u32 s56, s56, 0x40000
	s_addc_u32 s57, s57, 0
	s_mov_b32 m0, s63
	v_lshl_add_u64 v[222:223], s[56:57], 0, v[130:131]
	ds_read_b128 v[184:187], v149 offset:32768
	ds_read_b128 v[188:191], v149 offset:33792
	ds_read_b128 v[192:195], v149 offset:34816
	ds_read_b128 v[196:199], v149 offset:35840
	ds_read_b128 v[200:203], v149 offset:36864
	ds_read_b128 v[204:207], v149 offset:37888
	ds_read_b128 v[208:211], v149 offset:38912
	ds_read_b128 v[212:215], v149 offset:39936
	global_load_lds_dwordx4 v[222:223], off
	v_lshl_add_u64 v[222:223], s[56:57], 0, v[128:129]
	s_mov_b32 m0, s64
	s_nop 0
	global_load_lds_dwordx4 v[222:223], off
	s_waitcnt vmcnt(8)
	s_waitcnt lgkmcnt(0)
	s_barrier
	s_waitcnt lgkmcnt(0)
	v_mfma_f32_16x16x32_bf16 v[124:127], v[140:143], v[184:187], v[124:127]
	v_mfma_f32_16x16x32_bf16 v[124:127], v[150:153], v[188:191], v[124:127]
	s_setprio 1
	v_mfma_f32_16x16x32_bf16 v[120:123], v[154:157], v[184:187], v[120:123]
	v_mfma_f32_16x16x32_bf16 v[120:123], v[158:161], v[188:191], v[120:123]
	v_mfma_f32_16x16x32_bf16 v[108:111], v[140:143], v[192:195], v[108:111]
	v_mfma_f32_16x16x32_bf16 v[108:111], v[150:153], v[196:199], v[108:111]
	v_mfma_f32_16x16x32_bf16 v[104:107], v[154:157], v[192:195], v[104:107]
	v_mfma_f32_16x16x32_bf16 v[104:107], v[158:161], v[196:199], v[104:107]
	v_mfma_f32_16x16x32_bf16 v[92:95], v[140:143], v[200:203], v[92:95]
	v_mfma_f32_16x16x32_bf16 v[92:95], v[150:153], v[204:207], v[92:95]
	v_mfma_f32_16x16x32_bf16 v[88:91], v[154:157], v[200:203], v[88:91]
	v_mfma_f32_16x16x32_bf16 v[88:91], v[158:161], v[204:207], v[88:91]
	v_mfma_f32_16x16x32_bf16 v[76:79], v[140:143], v[208:211], v[76:79]
	v_mfma_f32_16x16x32_bf16 v[76:79], v[150:153], v[212:215], v[76:79]
	v_mfma_f32_16x16x32_bf16 v[72:75], v[154:157], v[208:211], v[72:75]
	v_mfma_f32_16x16x32_bf16 v[72:75], v[158:161], v[212:215], v[72:75]
	v_mfma_f32_16x16x32_bf16 v[116:119], v[162:165], v[184:187], v[116:119]
	v_mfma_f32_16x16x32_bf16 v[116:119], v[166:169], v[188:191], v[116:119]
	v_mfma_f32_16x16x32_bf16 v[112:115], v[170:173], v[184:187], v[112:115]
	v_mfma_f32_16x16x32_bf16 v[112:115], v[174:177], v[188:191], v[112:115]
	v_mfma_f32_16x16x32_bf16 v[100:103], v[162:165], v[192:195], v[100:103]
	v_mfma_f32_16x16x32_bf16 v[100:103], v[166:169], v[196:199], v[100:103]
	v_mfma_f32_16x16x32_bf16 v[96:99], v[170:173], v[192:195], v[96:99]
	v_mfma_f32_16x16x32_bf16 v[96:99], v[174:177], v[196:199], v[96:99]
	v_mfma_f32_16x16x32_bf16 v[84:87], v[162:165], v[200:203], v[84:87]
	v_mfma_f32_16x16x32_bf16 v[84:87], v[166:169], v[204:207], v[84:87]
	v_mfma_f32_16x16x32_bf16 v[80:83], v[170:173], v[200:203], v[80:83]
	v_mfma_f32_16x16x32_bf16 v[80:83], v[174:177], v[204:207], v[80:83]
	v_mfma_f32_16x16x32_bf16 v[68:71], v[162:165], v[208:211], v[68:71]
	v_mfma_f32_16x16x32_bf16 v[68:71], v[166:169], v[212:215], v[68:71]
	s_barrier
	v_mfma_f32_16x16x32_bf16 v[64:67], v[170:173], v[208:211], v[64:67]
	v_mfma_f32_16x16x32_bf16 v[64:67], v[174:177], v[212:215], v[64:67]
	s_setprio 0
	s_add_i32 s56, s77, s60
	v_lshl_add_u64 v[178:179], v[178:179], 0, s[12:13]
	s_mov_b32 m0, s56
	ds_read_b128 v[184:187], v149 offset:49152
	ds_read_b128 v[188:191], v149 offset:50176
	ds_read_b128 v[192:195], v149 offset:51200
	ds_read_b128 v[196:199], v149 offset:52224
	ds_read_b128 v[200:203], v149 offset:53248
	ds_read_b128 v[204:207], v149 offset:54272
	ds_read_b128 v[208:211], v149 offset:55296
	ds_read_b128 v[212:215], v149 offset:56320
	global_load_lds_dwordx4 v[178:179], off
	s_add_i32 m0, s56, 0x2000
	s_add_u32 s54, s54, 0x40080
	v_lshl_add_u64 v[178:179], v[216:217], 0, s[12:13]
	s_addc_u32 s55, s55, 0
	s_add_i32 s56, s79, s60
	global_load_lds_dwordx4 v[178:179], off
	v_lshl_add_u64 v[178:179], s[54:55], 0, v[130:131]
	s_mov_b32 m0, s56
	s_nop 0
	global_load_lds_dwordx4 v[178:179], off
	v_lshl_add_u64 v[178:179], s[54:55], 0, v[128:129]
	s_add_i32 m0, s56, 0x2000
	s_nop 0
	global_load_lds_dwordx4 v[178:179], off
	v_lshl_add_u64 v[178:179], v[218:219], 0, s[12:13]
	s_mov_b32 m0, s66
	s_nop 0
	global_load_lds_dwordx4 v[178:179], off
	v_lshl_add_u64 v[178:179], v[220:221], 0, s[12:13]
	s_mov_b32 m0, s67
	s_nop 0
	global_load_lds_dwordx4 v[178:179], off
	s_waitcnt vmcnt(8)
	s_waitcnt lgkmcnt(0)
	s_barrier
	s_waitcnt lgkmcnt(0)
	v_mfma_f32_16x16x32_bf16 v[60:63], v[140:143], v[184:187], v[60:63]
	v_mfma_f32_16x16x32_bf16 v[60:63], v[150:153], v[188:191], v[60:63]
	s_setprio 1
	v_mfma_f32_16x16x32_bf16 v[56:59], v[154:157], v[184:187], v[56:59]
	v_mfma_f32_16x16x32_bf16 v[56:59], v[158:161], v[188:191], v[56:59]
	v_mfma_f32_16x16x32_bf16 v[44:47], v[140:143], v[192:195], v[44:47]
	v_mfma_f32_16x16x32_bf16 v[44:47], v[150:153], v[196:199], v[44:47]
	v_mfma_f32_16x16x32_bf16 v[40:43], v[154:157], v[192:195], v[40:43]
	v_mfma_f32_16x16x32_bf16 v[40:43], v[158:161], v[196:199], v[40:43]
	v_mfma_f32_16x16x32_bf16 v[28:31], v[140:143], v[200:203], v[28:31]
	v_mfma_f32_16x16x32_bf16 v[28:31], v[150:153], v[204:207], v[28:31]
	v_mfma_f32_16x16x32_bf16 v[24:27], v[154:157], v[200:203], v[24:27]
	v_mfma_f32_16x16x32_bf16 v[24:27], v[158:161], v[204:207], v[24:27]
	v_mfma_f32_16x16x32_bf16 v[12:15], v[140:143], v[208:211], v[12:15]
	v_mfma_f32_16x16x32_bf16 v[12:15], v[150:153], v[212:215], v[12:15]
	v_mfma_f32_16x16x32_bf16 v[8:11], v[154:157], v[208:211], v[8:11]
	v_mfma_f32_16x16x32_bf16 v[8:11], v[158:161], v[212:215], v[8:11]
	v_mfma_f32_16x16x32_bf16 v[52:55], v[162:165], v[184:187], v[52:55]
	v_mfma_f32_16x16x32_bf16 v[52:55], v[166:169], v[188:191], v[52:55]
	v_mfma_f32_16x16x32_bf16 v[48:51], v[170:173], v[184:187], v[48:51]
	v_mfma_f32_16x16x32_bf16 v[48:51], v[174:177], v[188:191], v[48:51]
	v_mfma_f32_16x16x32_bf16 v[36:39], v[162:165], v[192:195], v[36:39]
	v_mfma_f32_16x16x32_bf16 v[36:39], v[166:169], v[196:199], v[36:39]
	v_mfma_f32_16x16x32_bf16 v[32:35], v[170:173], v[192:195], v[32:35]
	v_mfma_f32_16x16x32_bf16 v[32:35], v[174:177], v[196:199], v[32:35]
	v_mfma_f32_16x16x32_bf16 v[20:23], v[162:165], v[200:203], v[20:23]
	v_mfma_f32_16x16x32_bf16 v[20:23], v[166:169], v[204:207], v[20:23]
	v_mfma_f32_16x16x32_bf16 v[16:19], v[170:173], v[200:203], v[16:19]
	v_mfma_f32_16x16x32_bf16 v[16:19], v[174:177], v[204:207], v[16:19]
	v_mfma_f32_16x16x32_bf16 v[4:7], v[162:165], v[208:211], v[4:7]
	v_mfma_f32_16x16x32_bf16 v[4:7], v[166:169], v[212:215], v[4:7]
	s_barrier
	v_mfma_f32_16x16x32_bf16 v[0:3], v[170:173], v[208:211], v[0:3]
	v_mfma_f32_16x16x32_bf16 v[0:3], v[174:177], v[212:215], v[0:3]
	s_setprio 0
	s_add_i32 s76, s76, 2
	s_add_u32 s52, s52, 0x100
	s_addc_u32 s53, s53, 0
	s_add_u32 s74, s74, 0x100
	s_addc_u32 s75, s75, 0
	s_cmp_gt_u32 s76, 13
	s_cbranch_scc0 .LBB0_951
	s_and_b64 vcc, exec, s[16:17]
	s_cbranch_vccz .LBB0_954
	s_barrier
	s_setprio 1
.LBB0_954:
	v_mul_f32_e32 v151, 0xbfb8aa3b, v124
	v_exp_f32_e32 v151, v151
	v_mul_f32_e32 v154, 0xbfb8aa3b, v125
	v_exp_f32_e32 v154, v154
	v_lshl_or_b32 v142, s71, 7, v146
	v_add_f32_e32 v151, 1.0, v151
	v_rcp_f32_e32 v151, v151
	v_lshl_add_u32 v150, s48, 8, v144
	v_ashrrev_i32_e32 v143, 31, v142
	v_mov_b64_e32 v[140:141], s[22:23]
	v_mul_f32_e32 v124, v124, v151
	v_mul_f32_e32 v120, v120, v124
	v_add_f32_e32 v124, 1.0, v154
	v_mul_f32_e32 v151, 0xbfb8aa3b, v126
	v_rcp_f32_e32 v124, v124
	v_exp_f32_e32 v151, v151
	v_mul_f32_e32 v154, 0xbfb8aa3b, v127
	v_exp_f32_e32 v154, v154
	v_mul_f32_e32 v124, v125, v124
	v_add_f32_e32 v125, 1.0, v151
	v_rcp_f32_e32 v125, v125
	v_add_f32_e32 v151, 1.0, v154
	v_rcp_f32_e32 v151, v151
	v_mul_f32_e32 v121, v121, v124
	v_mul_f32_e32 v124, v126, v125
	v_mul_f32_e32 v125, 0xbfb8aa3b, v116
	v_exp_f32_e32 v125, v125
	v_mul_f32_e32 v122, v122, v124
	v_mul_f32_e32 v124, v127, v151
	v_mul_f32_e32 v123, v123, v124
	v_cvt_pk_bf16_f32 v120, v120, v121
	v_cvt_pk_bf16_f32 v121, v122, v123
	v_add_f32_e32 v122, 1.0, v125
	v_rcp_f32_e32 v122, v122
	v_mul_f32_e32 v123, 0xbfb8aa3b, v117
	v_exp_f32_e32 v123, v123
	v_mad_i64_i32 v[152:153], s[52:53], v150, s70, v[140:141]
	v_lshlrev_b64 v[142:143], 1, v[142:143]
	v_lshl_add_u64 v[152:153], v[152:153], 0, v[142:143]
	v_mul_f32_e32 v116, v116, v122
	global_store_dwordx2 v[152:153], v[120:121], off
	v_mul_f32_e32 v112, v112, v116
	v_add_f32_e32 v116, 1.0, v123
	v_mul_f32_e32 v120, 0xbfb8aa3b, v118
	v_rcp_f32_e32 v116, v116
	v_exp_f32_e32 v120, v120
	v_mul_f32_e32 v121, 0xbfb8aa3b, v119
	v_exp_f32_e32 v121, v121
	v_mul_f32_e32 v116, v117, v116
	v_add_f32_e32 v117, 1.0, v120
	v_rcp_f32_e32 v117, v117
	v_add_f32_e32 v120, 1.0, v121
	v_rcp_f32_e32 v120, v120
	v_mul_f32_e32 v113, v113, v116
	v_mul_f32_e32 v116, v118, v117
	v_mul_f32_e32 v114, v114, v116
	v_mul_f32_e32 v116, v119, v120
	v_cvt_pk_bf16_f32 v112, v112, v113
	v_mul_f32_e32 v115, v115, v116
	v_cvt_pk_bf16_f32 v113, v114, v115
	global_store_dwordx2 v[152:153], v[112:113], off offset:128
	v_mul_f32_e32 v112, 0xbfb8aa3b, v108
	v_exp_f32_e32 v114, v112
	v_mul_f32_e32 v115, 0xbfb8aa3b, v109
	v_exp_f32_e32 v115, v115
	v_or_b32_e32 v112, 16, v150
	v_add_f32_e32 v114, 1.0, v114
	v_rcp_f32_e32 v114, v114
	v_mad_i64_i32 v[112:113], s[52:53], v112, s70, v[140:141]
	v_lshl_add_u64 v[112:113], v[112:113], 0, v[142:143]
	v_mul_f32_e32 v108, v108, v114
	v_mul_f32_e32 v104, v104, v108
	v_add_f32_e32 v108, 1.0, v115
	v_mul_f32_e32 v114, 0xbfb8aa3b, v110
	v_rcp_f32_e32 v108, v108
	v_exp_f32_e32 v114, v114
	v_mul_f32_e32 v115, 0xbfb8aa3b, v111
	v_exp_f32_e32 v115, v115
	v_mul_f32_e32 v108, v109, v108
	v_add_f32_e32 v109, 1.0, v114
	v_rcp_f32_e32 v109, v109
	v_add_f32_e32 v114, 1.0, v115
	v_rcp_f32_e32 v114, v114
	v_mul_f32_e32 v105, v105, v108
	v_mul_f32_e32 v108, v110, v109
	v_mul_f32_e32 v109, 0xbfb8aa3b, v100
	v_exp_f32_e32 v109, v109
	v_mul_f32_e32 v106, v106, v108
	v_mul_f32_e32 v108, v111, v114
	v_mul_f32_e32 v107, v107, v108
	v_cvt_pk_bf16_f32 v104, v104, v105
	v_cvt_pk_bf16_f32 v105, v106, v107
	v_add_f32_e32 v106, 1.0, v109
	v_rcp_f32_e32 v106, v106
	v_mul_f32_e32 v107, 0xbfb8aa3b, v101
	v_exp_f32_e32 v107, v107
	global_store_dwordx2 v[112:113], v[104:105], off
	v_mul_f32_e32 v100, v100, v106
	v_mul_f32_e32 v96, v96, v100
	v_add_f32_e32 v100, 1.0, v107
	v_mul_f32_e32 v104, 0xbfb8aa3b, v102
	v_rcp_f32_e32 v100, v100
	v_exp_f32_e32 v104, v104
	v_mul_f32_e32 v105, 0xbfb8aa3b, v103
	v_exp_f32_e32 v105, v105
	v_mul_f32_e32 v100, v101, v100
	v_add_f32_e32 v101, 1.0, v104
	v_rcp_f32_e32 v101, v101
	v_add_f32_e32 v104, 1.0, v105
	v_rcp_f32_e32 v104, v104
	v_mul_f32_e32 v97, v97, v100
	v_mul_f32_e32 v100, v102, v101
	v_mul_f32_e32 v98, v98, v100
	v_mul_f32_e32 v100, v103, v104
	v_cvt_pk_bf16_f32 v96, v96, v97
	v_mul_f32_e32 v99, v99, v100
	v_cvt_pk_bf16_f32 v97, v98, v99
	global_store_dwordx2 v[112:113], v[96:97], off offset:128
	v_mul_f32_e32 v96, 0xbfb8aa3b, v92
	v_exp_f32_e32 v98, v96
	v_mul_f32_e32 v99, 0xbfb8aa3b, v93
	v_exp_f32_e32 v99, v99
	v_or_b32_e32 v96, 32, v150
	v_add_f32_e32 v98, 1.0, v98
	v_rcp_f32_e32 v98, v98
	v_mad_i64_i32 v[96:97], s[52:53], v96, s70, v[140:141]
	v_lshl_add_u64 v[96:97], v[96:97], 0, v[142:143]
	v_mul_f32_e32 v92, v92, v98
	v_mul_f32_e32 v88, v88, v92
	v_add_f32_e32 v92, 1.0, v99
	v_mul_f32_e32 v98, 0xbfb8aa3b, v94
	v_rcp_f32_e32 v92, v92
	v_exp_f32_e32 v98, v98
	v_mul_f32_e32 v99, 0xbfb8aa3b, v95
	v_exp_f32_e32 v99, v99
	v_mul_f32_e32 v92, v93, v92
	v_add_f32_e32 v93, 1.0, v98
	v_rcp_f32_e32 v93, v93
	v_add_f32_e32 v98, 1.0, v99
	v_rcp_f32_e32 v98, v98
	v_mul_f32_e32 v89, v89, v92
	v_mul_f32_e32 v92, v94, v93
	v_mul_f32_e32 v93, 0xbfb8aa3b, v84
	v_exp_f32_e32 v93, v93
	v_mul_f32_e32 v90, v90, v92
	v_mul_f32_e32 v92, v95, v98
	v_mul_f32_e32 v91, v91, v92
	v_cvt_pk_bf16_f32 v88, v88, v89
	v_cvt_pk_bf16_f32 v89, v90, v91
	v_add_f32_e32 v90, 1.0, v93
	v_rcp_f32_e32 v90, v90
	v_mul_f32_e32 v91, 0xbfb8aa3b, v85
	v_exp_f32_e32 v91, v91
	global_store_dwordx2 v[96:97], v[88:89], off
	v_mul_f32_e32 v84, v84, v90
	v_mul_f32_e32 v80, v80, v84
	v_add_f32_e32 v84, 1.0, v91
	v_mul_f32_e32 v88, 0xbfb8aa3b, v86
	v_rcp_f32_e32 v84, v84
	v_exp_f32_e32 v88, v88
	v_mul_f32_e32 v89, 0xbfb8aa3b, v87
	v_exp_f32_e32 v89, v89
	v_mul_f32_e32 v84, v85, v84
	v_add_f32_e32 v85, 1.0, v88
	v_rcp_f32_e32 v85, v85
	v_add_f32_e32 v88, 1.0, v89
	v_rcp_f32_e32 v88, v88
	v_mul_f32_e32 v81, v81, v84
	v_mul_f32_e32 v84, v86, v85
	v_mul_f32_e32 v82, v82, v84
	v_mul_f32_e32 v84, v87, v88
	v_cvt_pk_bf16_f32 v80, v80, v81
	v_mul_f32_e32 v83, v83, v84
	v_cvt_pk_bf16_f32 v81, v82, v83
	global_store_dwordx2 v[96:97], v[80:81], off offset:128
	v_mul_f32_e32 v80, 0xbfb8aa3b, v76
	v_exp_f32_e32 v82, v80
	v_mul_f32_e32 v83, 0xbfb8aa3b, v77
	v_exp_f32_e32 v83, v83
	v_or_b32_e32 v80, 48, v150
	v_add_f32_e32 v82, 1.0, v82
	v_rcp_f32_e32 v82, v82
	v_mad_i64_i32 v[80:81], s[52:53], v80, s70, v[140:141]
	v_lshl_add_u64 v[80:81], v[80:81], 0, v[142:143]
	v_mul_f32_e32 v76, v76, v82
	v_mul_f32_e32 v72, v72, v76
	v_add_f32_e32 v76, 1.0, v83
	v_mul_f32_e32 v82, 0xbfb8aa3b, v78
	v_rcp_f32_e32 v76, v76
	v_exp_f32_e32 v82, v82
	v_mul_f32_e32 v83, 0xbfb8aa3b, v79
	v_exp_f32_e32 v83, v83
	v_mul_f32_e32 v76, v77, v76
	v_add_f32_e32 v77, 1.0, v82
	v_rcp_f32_e32 v77, v77
	v_add_f32_e32 v82, 1.0, v83
	v_rcp_f32_e32 v82, v82
	v_mul_f32_e32 v73, v73, v76
	v_mul_f32_e32 v76, v78, v77
	v_mul_f32_e32 v77, 0xbfb8aa3b, v68
	v_exp_f32_e32 v77, v77
	v_mul_f32_e32 v74, v74, v76
	v_mul_f32_e32 v76, v79, v82
	v_mul_f32_e32 v75, v75, v76
	v_cvt_pk_bf16_f32 v72, v72, v73
	v_cvt_pk_bf16_f32 v73, v74, v75
	v_add_f32_e32 v74, 1.0, v77
	v_rcp_f32_e32 v74, v74
	v_mul_f32_e32 v75, 0xbfb8aa3b, v69
	v_exp_f32_e32 v75, v75
	global_store_dwordx2 v[80:81], v[72:73], off
	v_mul_f32_e32 v68, v68, v74
	v_mul_f32_e32 v64, v64, v68
	v_add_f32_e32 v68, 1.0, v75
	v_mul_f32_e32 v72, 0xbfb8aa3b, v70
	v_rcp_f32_e32 v68, v68
	v_exp_f32_e32 v72, v72
	v_mul_f32_e32 v73, 0xbfb8aa3b, v71
	v_exp_f32_e32 v73, v73
	v_mul_f32_e32 v68, v69, v68
	v_add_f32_e32 v69, 1.0, v72
	v_rcp_f32_e32 v69, v69
	v_add_f32_e32 v72, 1.0, v73
	v_rcp_f32_e32 v72, v72
	v_mul_f32_e32 v65, v65, v68
	v_mul_f32_e32 v68, v70, v69
	v_mul_f32_e32 v66, v66, v68
	v_mul_f32_e32 v68, v71, v72
	v_cvt_pk_bf16_f32 v64, v64, v65
	v_mul_f32_e32 v67, v67, v68
	v_cvt_pk_bf16_f32 v65, v66, v67
	global_store_dwordx2 v[80:81], v[64:65], off offset:128
	v_mul_f32_e32 v64, 0xbfb8aa3b, v60
	v_exp_f32_e32 v66, v64
	v_mul_f32_e32 v67, 0xbfb8aa3b, v61
	v_exp_f32_e32 v67, v67
	v_add_u32_e32 v64, 0x80, v150
	v_add_f32_e32 v66, 1.0, v66
	v_rcp_f32_e32 v66, v66
	v_mad_i64_i32 v[64:65], s[52:53], v64, s70, v[140:141]
	v_lshl_add_u64 v[64:65], v[64:65], 0, v[142:143]
	v_mul_f32_e32 v60, v60, v66
	v_mul_f32_e32 v56, v56, v60
	v_add_f32_e32 v60, 1.0, v67
	v_mul_f32_e32 v66, 0xbfb8aa3b, v62
	v_rcp_f32_e32 v60, v60
	v_exp_f32_e32 v66, v66
	v_mul_f32_e32 v67, 0xbfb8aa3b, v63
	v_exp_f32_e32 v67, v67
	v_mul_f32_e32 v60, v61, v60
	v_add_f32_e32 v61, 1.0, v66
	v_rcp_f32_e32 v61, v61
	v_add_f32_e32 v66, 1.0, v67
	v_rcp_f32_e32 v66, v66
	v_mul_f32_e32 v57, v57, v60
	v_mul_f32_e32 v60, v62, v61
	v_mul_f32_e32 v61, 0xbfb8aa3b, v52
	v_exp_f32_e32 v61, v61
	v_mul_f32_e32 v58, v58, v60
	v_mul_f32_e32 v60, v63, v66
	v_mul_f32_e32 v59, v59, v60
	v_cvt_pk_bf16_f32 v56, v56, v57
	v_cvt_pk_bf16_f32 v57, v58, v59
	v_add_f32_e32 v58, 1.0, v61
	v_rcp_f32_e32 v58, v58
	v_mul_f32_e32 v59, 0xbfb8aa3b, v53
	v_exp_f32_e32 v59, v59
	global_store_dwordx2 v[64:65], v[56:57], off
	v_mul_f32_e32 v52, v52, v58
	v_mul_f32_e32 v48, v48, v52
	v_add_f32_e32 v52, 1.0, v59
	v_mul_f32_e32 v56, 0xbfb8aa3b, v54
	v_rcp_f32_e32 v52, v52
	v_exp_f32_e32 v56, v56
	v_mul_f32_e32 v57, 0xbfb8aa3b, v55
	v_exp_f32_e32 v57, v57
	v_mul_f32_e32 v52, v53, v52
	v_add_f32_e32 v53, 1.0, v56
	v_rcp_f32_e32 v53, v53
	v_add_f32_e32 v56, 1.0, v57
	v_rcp_f32_e32 v56, v56
	v_mul_f32_e32 v49, v49, v52
	v_mul_f32_e32 v52, v54, v53
	v_mul_f32_e32 v50, v50, v52
	v_mul_f32_e32 v52, v55, v56
	v_cvt_pk_bf16_f32 v48, v48, v49
	v_mul_f32_e32 v51, v51, v52
	v_cvt_pk_bf16_f32 v49, v50, v51
	global_store_dwordx2 v[64:65], v[48:49], off offset:128
	v_mul_f32_e32 v48, 0xbfb8aa3b, v44
	v_exp_f32_e32 v50, v48
	v_mul_f32_e32 v51, 0xbfb8aa3b, v45
	v_exp_f32_e32 v51, v51
	v_add_u32_e32 v48, 0x90, v150
	v_add_f32_e32 v50, 1.0, v50
	v_rcp_f32_e32 v50, v50
	v_mad_i64_i32 v[48:49], s[52:53], v48, s70, v[140:141]
	v_lshl_add_u64 v[48:49], v[48:49], 0, v[142:143]
	v_mul_f32_e32 v44, v44, v50
	v_mul_f32_e32 v40, v40, v44
	v_add_f32_e32 v44, 1.0, v51
	v_mul_f32_e32 v50, 0xbfb8aa3b, v46
	v_rcp_f32_e32 v44, v44
	v_exp_f32_e32 v50, v50
	v_mul_f32_e32 v51, 0xbfb8aa3b, v47
	v_exp_f32_e32 v51, v51
	v_mul_f32_e32 v44, v45, v44
	v_add_f32_e32 v45, 1.0, v50
	v_rcp_f32_e32 v45, v45
	v_add_f32_e32 v50, 1.0, v51
	v_rcp_f32_e32 v50, v50
	v_mul_f32_e32 v41, v41, v44
	v_mul_f32_e32 v44, v46, v45
	v_mul_f32_e32 v45, 0xbfb8aa3b, v36
	v_exp_f32_e32 v45, v45
	v_mul_f32_e32 v42, v42, v44
	v_mul_f32_e32 v44, v47, v50
	v_mul_f32_e32 v43, v43, v44
	v_cvt_pk_bf16_f32 v40, v40, v41
	v_cvt_pk_bf16_f32 v41, v42, v43
	v_add_f32_e32 v42, 1.0, v45
	v_rcp_f32_e32 v42, v42
	v_mul_f32_e32 v43, 0xbfb8aa3b, v37
	v_exp_f32_e32 v43, v43
	global_store_dwordx2 v[48:49], v[40:41], off
	v_mul_f32_e32 v36, v36, v42
	v_mul_f32_e32 v32, v32, v36
	v_add_f32_e32 v36, 1.0, v43
	v_mul_f32_e32 v40, 0xbfb8aa3b, v38
	v_rcp_f32_e32 v36, v36
	v_exp_f32_e32 v40, v40
	v_mul_f32_e32 v41, 0xbfb8aa3b, v39
	v_exp_f32_e32 v41, v41
	v_mul_f32_e32 v36, v37, v36
	v_add_f32_e32 v37, 1.0, v40
	v_rcp_f32_e32 v37, v37
	v_add_f32_e32 v40, 1.0, v41
	v_rcp_f32_e32 v40, v40
	v_mul_f32_e32 v33, v33, v36
	v_mul_f32_e32 v36, v38, v37
	v_mul_f32_e32 v34, v34, v36
	v_mul_f32_e32 v36, v39, v40
	v_cvt_pk_bf16_f32 v32, v32, v33
	v_mul_f32_e32 v35, v35, v36
	v_cvt_pk_bf16_f32 v33, v34, v35
	global_store_dwordx2 v[48:49], v[32:33], off offset:128
	v_mul_f32_e32 v32, 0xbfb8aa3b, v28
	v_exp_f32_e32 v34, v32
	v_mul_f32_e32 v35, 0xbfb8aa3b, v29
	v_exp_f32_e32 v35, v35
	v_add_u32_e32 v32, 0xa0, v150
	v_add_f32_e32 v34, 1.0, v34
	v_rcp_f32_e32 v34, v34
	v_mad_i64_i32 v[32:33], s[52:53], v32, s70, v[140:141]
	v_lshl_add_u64 v[32:33], v[32:33], 0, v[142:143]
	v_mul_f32_e32 v28, v28, v34
	v_mul_f32_e32 v24, v24, v28
	v_add_f32_e32 v28, 1.0, v35
	v_mul_f32_e32 v34, 0xbfb8aa3b, v30
	v_rcp_f32_e32 v28, v28
	v_exp_f32_e32 v34, v34
	v_mul_f32_e32 v35, 0xbfb8aa3b, v31
	v_exp_f32_e32 v35, v35
	v_mul_f32_e32 v28, v29, v28
	v_add_f32_e32 v29, 1.0, v34
	v_rcp_f32_e32 v29, v29
	v_add_f32_e32 v34, 1.0, v35
	v_rcp_f32_e32 v34, v34
	v_mul_f32_e32 v25, v25, v28
	v_mul_f32_e32 v28, v30, v29
	v_mul_f32_e32 v29, 0xbfb8aa3b, v20
	v_exp_f32_e32 v29, v29
	v_mul_f32_e32 v26, v26, v28
	v_mul_f32_e32 v28, v31, v34
	v_mul_f32_e32 v27, v27, v28
	v_cvt_pk_bf16_f32 v24, v24, v25
	v_cvt_pk_bf16_f32 v25, v26, v27
	v_add_f32_e32 v26, 1.0, v29
	v_rcp_f32_e32 v26, v26
	v_mul_f32_e32 v27, 0xbfb8aa3b, v21
	v_exp_f32_e32 v27, v27
	global_store_dwordx2 v[32:33], v[24:25], off
	v_mul_f32_e32 v20, v20, v26
	v_mul_f32_e32 v16, v16, v20
	v_add_f32_e32 v20, 1.0, v27
	v_mul_f32_e32 v24, 0xbfb8aa3b, v22
	v_rcp_f32_e32 v20, v20
	v_exp_f32_e32 v24, v24
	v_mul_f32_e32 v25, 0xbfb8aa3b, v23
	v_exp_f32_e32 v25, v25
	v_mul_f32_e32 v20, v21, v20
	v_add_f32_e32 v21, 1.0, v24
	v_rcp_f32_e32 v21, v21
	v_add_f32_e32 v24, 1.0, v25
	v_rcp_f32_e32 v24, v24
	v_mul_f32_e32 v17, v17, v20
	v_mul_f32_e32 v20, v22, v21
	v_mul_f32_e32 v18, v18, v20
	v_mul_f32_e32 v20, v23, v24
	v_cvt_pk_bf16_f32 v16, v16, v17
	v_mul_f32_e32 v19, v19, v20
	v_cvt_pk_bf16_f32 v17, v18, v19
	global_store_dwordx2 v[32:33], v[16:17], off offset:128
	v_mul_f32_e32 v16, 0xbfb8aa3b, v12
	v_exp_f32_e32 v18, v16
	v_mul_f32_e32 v19, 0xbfb8aa3b, v13
	v_exp_f32_e32 v19, v19
	v_add_u32_e32 v16, 0xb0, v150
	v_add_f32_e32 v18, 1.0, v18
	v_rcp_f32_e32 v18, v18
	v_mad_i64_i32 v[16:17], s[52:53], v16, s70, v[140:141]
	v_lshl_add_u64 v[16:17], v[16:17], 0, v[142:143]
	v_mul_f32_e32 v12, v12, v18
	v_mul_f32_e32 v8, v8, v12
	v_add_f32_e32 v12, 1.0, v19
	v_mul_f32_e32 v18, 0xbfb8aa3b, v14
	v_rcp_f32_e32 v12, v12
	v_exp_f32_e32 v18, v18
	v_mul_f32_e32 v19, 0xbfb8aa3b, v15
	v_exp_f32_e32 v19, v19
	v_mul_f32_e32 v12, v13, v12
	v_add_f32_e32 v13, 1.0, v18
	v_rcp_f32_e32 v13, v13
	v_add_f32_e32 v18, 1.0, v19
	v_rcp_f32_e32 v18, v18
	v_mul_f32_e32 v9, v9, v12
	v_mul_f32_e32 v12, v14, v13
	v_mul_f32_e32 v13, 0xbfb8aa3b, v4
	v_exp_f32_e32 v13, v13
	v_mul_f32_e32 v10, v10, v12
	v_mul_f32_e32 v12, v15, v18
	v_mul_f32_e32 v11, v11, v12
	v_cvt_pk_bf16_f32 v8, v8, v9
	v_cvt_pk_bf16_f32 v9, v10, v11
	v_add_f32_e32 v10, 1.0, v13
	v_rcp_f32_e32 v10, v10
	v_mul_f32_e32 v11, 0xbfb8aa3b, v5
	v_exp_f32_e32 v11, v11
	global_store_dwordx2 v[16:17], v[8:9], off
	v_mul_f32_e32 v4, v4, v10
	v_mul_f32_e32 v0, v0, v4
	v_add_f32_e32 v4, 1.0, v11
	v_mul_f32_e32 v8, 0xbfb8aa3b, v6
	v_rcp_f32_e32 v4, v4
	v_exp_f32_e32 v8, v8
	v_mul_f32_e32 v9, 0xbfb8aa3b, v7
	v_exp_f32_e32 v9, v9
	v_mul_f32_e32 v4, v5, v4
	v_add_f32_e32 v5, 1.0, v8
	v_rcp_f32_e32 v5, v5
	v_add_f32_e32 v8, 1.0, v9
	v_rcp_f32_e32 v8, v8
	v_mul_f32_e32 v1, v1, v4
	v_mul_f32_e32 v4, v6, v5
	v_mul_f32_e32 v2, v2, v4
	v_mul_f32_e32 v4, v7, v8
	s_andn2_b64 vcc, exec, s[10:11]
	s_mov_b64 s[10:11], -1
	v_mul_f32_e32 v3, v3, v4
	v_cvt_pk_bf16_f32 v0, v0, v1
	v_cvt_pk_bf16_f32 v1, v2, v3
	global_store_dwordx2 v[16:17], v[0:1], off offset:128
	s_setprio 0
	s_cbranch_vccnz .LBB0_947
	s_andn2_b64 vcc, exec, s[0:1]
	s_cbranch_vccnz .LBB0_946
	s_barrier
	s_branch .LBB0_946

.Lmid_gemm8:
	s_add_i32 s79, 0, 0x18000
	s_add_i32 s89, 0, 0x1c000
	v_add_u32_e32 v164, s79, v147
	v_add_u32_e32 v181, s89, v147
	ds_read_b128 v[152:155], v164
	ds_read_b128 v[156:159], v164 offset:1024
	ds_read_b128 v[160:163], v164 offset:2048
	ds_read_b128 v[164:167], v164 offset:3072
	ds_read_b128 v[168:171], v181
	ds_read_b128 v[172:175], v181 offset:1024
	ds_read_b128 v[176:179], v181 offset:2048
	ds_read_b128 v[184:187], v181 offset:3072
	s_add_u32 s54, s60, 0xb0000
	s_addc_u32 s55, s61, 0
	s_mov_b32 m0, s67
	v_lshl_add_u64 v[226:227], s[54:55], 0, v[128:129]
	ds_read_b128 v[188:191], v151 offset:32768
	ds_read_b128 v[192:195], v151 offset:33792
	ds_read_b128 v[196:199], v151 offset:34816
	ds_read_b128 v[200:203], v151 offset:35840
	ds_read_b128 v[204:207], v151 offset:36864
	ds_read_b128 v[208:211], v151 offset:37888
	ds_read_b128 v[212:215], v151 offset:38912
	ds_read_b128 v[216:219], v151 offset:39936
	global_load_lds_dwordx4 v[226:227], off
	v_lshl_add_u64 v[226:227], s[54:55], 0, v[132:133]
	s_mov_b32 m0, s68
	s_nop 0
	global_load_lds_dwordx4 v[226:227], off
	s_waitcnt vmcnt(8)
	s_waitcnt lgkmcnt(0)
	s_barrier
	s_waitcnt lgkmcnt(0)
	v_mfma_f32_16x16x32_bf16 v[124:127], v[152:155], v[188:191], v[124:127]
	v_mfma_f32_16x16x32_bf16 v[124:127], v[156:159], v[192:195], v[124:127]
	s_setprio 1
	v_mfma_f32_16x16x32_bf16 v[120:123], v[160:163], v[188:191], v[120:123]
	v_mfma_f32_16x16x32_bf16 v[120:123], v[164:167], v[192:195], v[120:123]
	v_mfma_f32_16x16x32_bf16 v[116:119], v[152:155], v[196:199], v[116:119]
	v_mfma_f32_16x16x32_bf16 v[116:119], v[156:159], v[200:203], v[116:119]
	v_mfma_f32_16x16x32_bf16 v[108:111], v[160:163], v[196:199], v[108:111]
	v_mfma_f32_16x16x32_bf16 v[108:111], v[164:167], v[200:203], v[108:111]
	v_mfma_f32_16x16x32_bf16 v[100:103], v[152:155], v[204:207], v[100:103]
	v_mfma_f32_16x16x32_bf16 v[100:103], v[156:159], v[208:211], v[100:103]
	v_mfma_f32_16x16x32_bf16 v[92:95], v[160:163], v[204:207], v[92:95]
	v_mfma_f32_16x16x32_bf16 v[92:95], v[164:167], v[208:211], v[92:95]
	v_mfma_f32_16x16x32_bf16 v[84:87], v[152:155], v[212:215], v[84:87]
	v_mfma_f32_16x16x32_bf16 v[84:87], v[156:159], v[216:219], v[84:87]
	v_mfma_f32_16x16x32_bf16 v[76:79], v[160:163], v[212:215], v[76:79]
	v_mfma_f32_16x16x32_bf16 v[76:79], v[164:167], v[216:219], v[76:79]
	v_mfma_f32_16x16x32_bf16 v[112:115], v[168:171], v[188:191], v[112:115]
	v_mfma_f32_16x16x32_bf16 v[112:115], v[172:175], v[192:195], v[112:115]
	v_mfma_f32_16x16x32_bf16 v[104:107], v[176:179], v[188:191], v[104:107]
	v_mfma_f32_16x16x32_bf16 v[104:107], v[184:187], v[192:195], v[104:107]
	v_mfma_f32_16x16x32_bf16 v[96:99], v[168:171], v[196:199], v[96:99]
	v_mfma_f32_16x16x32_bf16 v[96:99], v[172:175], v[200:203], v[96:99]
	v_mfma_f32_16x16x32_bf16 v[88:91], v[176:179], v[196:199], v[88:91]
	v_mfma_f32_16x16x32_bf16 v[88:91], v[184:187], v[200:203], v[88:91]
	v_mfma_f32_16x16x32_bf16 v[80:83], v[168:171], v[204:207], v[80:83]
	v_mfma_f32_16x16x32_bf16 v[80:83], v[172:175], v[208:211], v[80:83]
	v_mfma_f32_16x16x32_bf16 v[72:75], v[176:179], v[204:207], v[72:75]
	v_mfma_f32_16x16x32_bf16 v[72:75], v[184:187], v[208:211], v[72:75]
	v_mfma_f32_16x16x32_bf16 v[68:71], v[168:171], v[212:215], v[68:71]
	v_mfma_f32_16x16x32_bf16 v[68:71], v[172:175], v[216:219], v[68:71]
	s_barrier
	v_mfma_f32_16x16x32_bf16 v[64:67], v[176:179], v[212:215], v[64:67]
	v_mfma_f32_16x16x32_bf16 v[64:67], v[184:187], v[216:219], v[64:67]
	s_setprio 0
	s_add_i32 s54, s79, s64
	v_lshl_add_u64 v[144:145], v[144:145], 0, s[16:17]
	s_mov_b32 m0, s54
	ds_read_b128 v[188:191], v151 offset:49152
	ds_read_b128 v[192:195], v151 offset:50176
	ds_read_b128 v[196:199], v151 offset:51200
	ds_read_b128 v[200:203], v151 offset:52224
	ds_read_b128 v[204:207], v151 offset:53248
	ds_read_b128 v[208:211], v151 offset:54272
	ds_read_b128 v[212:215], v151 offset:55296
	ds_read_b128 v[216:219], v151 offset:56320
	global_load_lds_dwordx4 v[144:145], off
	s_add_i32 m0, s54, 0x2000
	s_add_u32 s54, s58, 0xb0080
	v_lshl_add_u64 v[144:145], v[220:221], 0, s[16:17]
	s_addc_u32 s55, s59, 0
	s_add_i32 s58, s89, s64
	global_load_lds_dwordx4 v[144:145], off
	v_lshl_add_u64 v[144:145], s[54:55], 0, v[130:131]
	s_mov_b32 m0, s58
	s_nop 0
	global_load_lds_dwordx4 v[144:145], off
	v_lshl_add_u64 v[144:145], s[54:55], 0, v[134:135]
	s_add_i32 m0, s58, 0x2000
	s_nop 0
	global_load_lds_dwordx4 v[144:145], off
	v_lshl_add_u64 v[144:145], v[222:223], 0, s[16:17]
	s_mov_b32 m0, s70
	s_nop 0
	global_load_lds_dwordx4 v[144:145], off
	v_lshl_add_u64 v[144:145], v[224:225], 0, s[16:17]
	s_mov_b32 m0, s71
	s_nop 0
	global_load_lds_dwordx4 v[144:145], off
	s_waitcnt vmcnt(8)
	s_waitcnt lgkmcnt(0)
	s_barrier
	s_waitcnt lgkmcnt(0)
	v_mfma_f32_16x16x32_bf16 v[60:63], v[152:155], v[188:191], v[60:63]
	v_mfma_f32_16x16x32_bf16 v[60:63], v[156:159], v[192:195], v[60:63]
	s_setprio 1
	v_mfma_f32_16x16x32_bf16 v[56:59], v[160:163], v[188:191], v[56:59]
	v_mfma_f32_16x16x32_bf16 v[56:59], v[164:167], v[192:195], v[56:59]
	v_mfma_f32_16x16x32_bf16 v[52:55], v[152:155], v[196:199], v[52:55]
	v_mfma_f32_16x16x32_bf16 v[52:55], v[156:159], v[200:203], v[52:55]
	v_mfma_f32_16x16x32_bf16 v[44:47], v[160:163], v[196:199], v[44:47]
	v_mfma_f32_16x16x32_bf16 v[44:47], v[164:167], v[200:203], v[44:47]
	v_mfma_f32_16x16x32_bf16 v[36:39], v[152:155], v[204:207], v[36:39]
	v_mfma_f32_16x16x32_bf16 v[36:39], v[156:159], v[208:211], v[36:39]
	v_mfma_f32_16x16x32_bf16 v[28:31], v[160:163], v[204:207], v[28:31]
	v_mfma_f32_16x16x32_bf16 v[28:31], v[164:167], v[208:211], v[28:31]
	v_mfma_f32_16x16x32_bf16 v[20:23], v[152:155], v[212:215], v[20:23]
	v_mfma_f32_16x16x32_bf16 v[20:23], v[156:159], v[216:219], v[20:23]
	v_mfma_f32_16x16x32_bf16 v[12:15], v[160:163], v[212:215], v[12:15]
	v_mfma_f32_16x16x32_bf16 v[12:15], v[164:167], v[216:219], v[12:15]
	v_mfma_f32_16x16x32_bf16 v[48:51], v[168:171], v[188:191], v[48:51]
	v_mfma_f32_16x16x32_bf16 v[48:51], v[172:175], v[192:195], v[48:51]
	v_mfma_f32_16x16x32_bf16 v[40:43], v[176:179], v[188:191], v[40:43]
	v_mfma_f32_16x16x32_bf16 v[40:43], v[184:187], v[192:195], v[40:43]
	v_mfma_f32_16x16x32_bf16 v[32:35], v[168:171], v[196:199], v[32:35]
	v_mfma_f32_16x16x32_bf16 v[32:35], v[172:175], v[200:203], v[32:35]
	v_mfma_f32_16x16x32_bf16 v[24:27], v[176:179], v[196:199], v[24:27]
	v_mfma_f32_16x16x32_bf16 v[24:27], v[184:187], v[200:203], v[24:27]
	v_mfma_f32_16x16x32_bf16 v[16:19], v[168:171], v[204:207], v[16:19]
	v_mfma_f32_16x16x32_bf16 v[16:19], v[172:175], v[208:211], v[16:19]
	v_mfma_f32_16x16x32_bf16 v[8:11], v[176:179], v[204:207], v[8:11]
	v_mfma_f32_16x16x32_bf16 v[8:11], v[184:187], v[208:211], v[8:11]
	v_mfma_f32_16x16x32_bf16 v[4:7], v[168:171], v[212:215], v[4:7]
	v_mfma_f32_16x16x32_bf16 v[4:7], v[172:175], v[216:219], v[4:7]
	s_barrier
	v_mfma_f32_16x16x32_bf16 v[0:3], v[176:179], v[212:215], v[0:3]
	v_mfma_f32_16x16x32_bf16 v[0:3], v[184:187], v[216:219], v[0:3]
	s_setprio 0
	s_add_i32 s88, s88, 2
	s_add_u32 s86, s86, 0x100
	s_addc_u32 s87, s87, 0
	s_cmp_gt_u32 s88, 41
	s_mov_b64 s[54:55], s[56:57]
	s_cbranch_scc0 .LBB0_1031
	s_and_b64 vcc, exec, s[18:19]
	s_cbranch_vccz .LBB0_1034
	s_barrier
	s_setprio 1
.LBB0_1034:
	v_lshl_add_u32 v152, s84, 8, v146
	v_lshl_or_b32 v144, s85, 8, v148
	v_ashrrev_i32_e32 v145, 31, v144
	v_ashrrev_i32_e32 v153, 31, v152
	v_lshl_add_u64 v[154:155], v[144:145], 1, s[24:25]
	v_lshlrev_b64 v[144:145], 11, v[152:153]
	v_lshl_add_u64 v[144:145], v[154:155], 0, v[144:145]
	s_nop 15
	s_nop 7
	v_cvt_pk_bf16_f32 v124, v124, v125
	v_cvt_pk_bf16_f32 v125, v126, v127
	v_cvt_pk_bf16_f32 v126, v120, v121
	v_cvt_pk_bf16_f32 v127, v122, v123
	global_store_dwordx4 v[144:145], v[124:127], off
	v_cvt_pk_bf16_f32 v112, v112, v113
	v_cvt_pk_bf16_f32 v113, v114, v115
	v_cvt_pk_bf16_f32 v114, v104, v105
	v_or_b32_e32 v104, 16, v152
	v_ashrrev_i32_e32 v105, 31, v104
	v_lshlrev_b64 v[104:105], 11, v[104:105]
	v_cvt_pk_bf16_f32 v115, v106, v107
	global_store_dwordx4 v[144:145], v[112:115], off offset:256
	s_nop 1
	v_lshl_add_u64 v[112:113], v[154:155], 0, v[104:105]
	v_cvt_pk_bf16_f32 v104, v116, v117
	v_cvt_pk_bf16_f32 v105, v118, v119
	v_cvt_pk_bf16_f32 v106, v108, v109
	v_cvt_pk_bf16_f32 v107, v110, v111
	global_store_dwordx4 v[112:113], v[104:107], off
	v_cvt_pk_bf16_f32 v96, v96, v97
	v_cvt_pk_bf16_f32 v97, v98, v99
	v_cvt_pk_bf16_f32 v98, v88, v89
	v_or_b32_e32 v88, 32, v152
	v_ashrrev_i32_e32 v89, 31, v88
	v_lshlrev_b64 v[88:89], 11, v[88:89]
	v_cvt_pk_bf16_f32 v99, v90, v91
	global_store_dwordx4 v[112:113], v[96:99], off offset:256
	s_nop 1
	v_lshl_add_u64 v[96:97], v[154:155], 0, v[88:89]
	v_cvt_pk_bf16_f32 v88, v100, v101
	v_cvt_pk_bf16_f32 v89, v102, v103
	v_cvt_pk_bf16_f32 v90, v92, v93
	v_cvt_pk_bf16_f32 v91, v94, v95
	global_store_dwordx4 v[96:97], v[88:91], off
	v_cvt_pk_bf16_f32 v80, v80, v81
	v_cvt_pk_bf16_f32 v81, v82, v83
	v_cvt_pk_bf16_f32 v82, v72, v73
	v_or_b32_e32 v72, 48, v152
	v_ashrrev_i32_e32 v73, 31, v72
	v_lshlrev_b64 v[72:73], 11, v[72:73]
	v_cvt_pk_bf16_f32 v83, v74, v75
	global_store_dwordx4 v[96:97], v[80:83], off offset:256
	s_nop 1
	v_lshl_add_u64 v[80:81], v[154:155], 0, v[72:73]
	v_cvt_pk_bf16_f32 v72, v84, v85
	v_cvt_pk_bf16_f32 v73, v86, v87
	v_cvt_pk_bf16_f32 v74, v76, v77
	v_cvt_pk_bf16_f32 v75, v78, v79
	global_store_dwordx4 v[80:81], v[72:75], off
	v_cvt_pk_bf16_f32 v68, v68, v69
	v_cvt_pk_bf16_f32 v69, v70, v71
	v_cvt_pk_bf16_f32 v70, v64, v65
	v_cvt_pk_bf16_f32 v71, v66, v67
	global_store_dwordx4 v[80:81], v[68:71], off offset:256
	v_cvt_pk_bf16_f32 v60, v60, v61
	v_cvt_pk_bf16_f32 v61, v62, v63
	v_cvt_pk_bf16_f32 v62, v56, v57
	v_add_co_u32_e32 v56, vcc, s74, v144
	v_lshl_add_u64 v[64:65], v[144:145], 0, s[36:37]
	s_nop 0
	v_addc_co_u32_e32 v57, vcc, 0, v145, vcc
	v_cvt_pk_bf16_f32 v63, v58, v59
	global_store_dwordx4 v[56:57], v[60:63], off
	v_cvt_pk_bf16_f32 v48, v48, v49
	v_cvt_pk_bf16_f32 v49, v50, v51
	v_cvt_pk_bf16_f32 v50, v40, v41
	v_cvt_pk_bf16_f32 v51, v42, v43
	global_store_dwordx4 v[64:65], v[48:51], off offset:256
	v_cvt_pk_bf16_f32 v40, v52, v53
	v_cvt_pk_bf16_f32 v41, v54, v55
	v_cvt_pk_bf16_f32 v42, v44, v45
	v_add_co_u32_e32 v44, vcc, s75, v144
	s_nop 0
	v_lshl_add_u64 v[48:49], v[144:145], 0, s[44:45]
	v_addc_co_u32_e32 v45, vcc, 0, v145, vcc
	v_cvt_pk_bf16_f32 v43, v46, v47
	global_store_dwordx4 v[44:45], v[40:43], off
	v_cvt_pk_bf16_f32 v32, v32, v33
	v_cvt_pk_bf16_f32 v33, v34, v35
	v_cvt_pk_bf16_f32 v34, v24, v25
	v_cvt_pk_bf16_f32 v35, v26, v27
	global_store_dwordx4 v[48:49], v[32:35], off offset:256
	v_cvt_pk_bf16_f32 v24, v36, v37
	v_cvt_pk_bf16_f32 v25, v38, v39
	v_cvt_pk_bf16_f32 v26, v28, v29
	v_add_co_u32_e32 v28, vcc, s76, v144
	s_nop 0
	v_lshl_add_u64 v[32:33], v[144:145], 0, s[46:47]
	v_addc_co_u32_e32 v29, vcc, 0, v145, vcc
	v_cvt_pk_bf16_f32 v27, v30, v31
	global_store_dwordx4 v[28:29], v[24:27], off
	v_cvt_pk_bf16_f32 v16, v16, v17
	v_cvt_pk_bf16_f32 v17, v18, v19
	v_cvt_pk_bf16_f32 v18, v8, v9
	v_cvt_pk_bf16_f32 v19, v10, v11
	global_store_dwordx4 v[32:33], v[16:19], off offset:256
	v_cvt_pk_bf16_f32 v8, v20, v21
	v_cvt_pk_bf16_f32 v9, v22, v23
	v_cvt_pk_bf16_f32 v10, v12, v13
	v_add_co_u32_e32 v12, vcc, s77, v144
	s_nop 0
	v_lshl_add_u64 v[16:17], v[144:145], 0, s[48:49]
	v_addc_co_u32_e32 v13, vcc, 0, v145, vcc
	s_and_b64 vcc, exec, s[10:11]
	s_mov_b64 s[10:11], -1
	v_cvt_pk_bf16_f32 v11, v14, v15
	global_store_dwordx4 v[12:13], v[8:11], off
	v_cvt_pk_bf16_f32 v4, v4, v5
	v_cvt_pk_bf16_f32 v5, v6, v7
	v_cvt_pk_bf16_f32 v6, v0, v1
	v_cvt_pk_bf16_f32 v7, v2, v3
	global_store_dwordx4 v[16:17], v[4:7], off offset:256
	s_setprio 0
	s_cbranch_vccnz .LBB0_1019
	s_andn2_b64 vcc, exec, s[0:1]
	s_cbranch_vccnz .LBB0_1018
	s_barrier
	s_branch .LBB0_1018

.Lmid_gemm9:
	s_add_i32 s79, 0, 0x18000
	s_add_i32 s88, 0, 0x1c000
	v_add_u32_e32 v164, s79, v147
	v_add_u32_e32 v181, s88, v147
	ds_read_b128 v[152:155], v164
	ds_read_b128 v[156:159], v164 offset:1024
	ds_read_b128 v[160:163], v164 offset:2048
	ds_read_b128 v[164:167], v164 offset:3072
	ds_read_b128 v[168:171], v181
	ds_read_b128 v[172:175], v181 offset:1024
	ds_read_b128 v[176:179], v181 offset:2048
	ds_read_b128 v[184:187], v181 offset:3072
	s_add_u32 s64, s64, 0x40000
	s_addc_u32 s65, s65, 0
	s_mov_b32 m0, s71
	v_lshl_add_u64 v[228:229], s[64:65], 0, v[128:129]
	ds_read_b128 v[188:191], v150 offset:32768
	ds_read_b128 v[192:195], v150 offset:33792
	ds_read_b128 v[196:199], v150 offset:34816
	ds_read_b128 v[200:203], v150 offset:35840
	ds_read_b128 v[204:207], v150 offset:36864
	ds_read_b128 v[208:211], v150 offset:37888
	ds_read_b128 v[212:215], v150 offset:38912
	ds_read_b128 v[216:219], v150 offset:39936
	global_load_lds_dwordx4 v[228:229], off
	v_lshl_add_u64 v[228:229], s[64:65], 0, v[132:133]
	s_mov_b32 m0, s72
	s_nop 0
	global_load_lds_dwordx4 v[228:229], off
	s_waitcnt vmcnt(8)
	s_waitcnt lgkmcnt(0)
	s_barrier
	s_waitcnt lgkmcnt(0)
	v_mfma_f32_16x16x32_bf16 v[124:127], v[152:155], v[188:191], v[124:127]
	v_mfma_f32_16x16x32_bf16 v[124:127], v[156:159], v[192:195], v[124:127]
	s_setprio 1
	v_mfma_f32_16x16x32_bf16 v[120:123], v[160:163], v[188:191], v[120:123]
	v_mfma_f32_16x16x32_bf16 v[120:123], v[164:167], v[192:195], v[120:123]
	v_mfma_f32_16x16x32_bf16 v[116:119], v[152:155], v[196:199], v[116:119]
	v_mfma_f32_16x16x32_bf16 v[116:119], v[156:159], v[200:203], v[116:119]
	v_mfma_f32_16x16x32_bf16 v[112:115], v[160:163], v[196:199], v[112:115]
	v_mfma_f32_16x16x32_bf16 v[112:115], v[164:167], v[200:203], v[112:115]
	v_mfma_f32_16x16x32_bf16 v[108:111], v[152:155], v[204:207], v[108:111]
	v_mfma_f32_16x16x32_bf16 v[108:111], v[156:159], v[208:211], v[108:111]
	v_mfma_f32_16x16x32_bf16 v[104:107], v[160:163], v[204:207], v[104:107]
	v_mfma_f32_16x16x32_bf16 v[104:107], v[164:167], v[208:211], v[104:107]
	v_mfma_f32_16x16x32_bf16 v[100:103], v[152:155], v[212:215], v[100:103]
	v_mfma_f32_16x16x32_bf16 v[100:103], v[156:159], v[216:219], v[100:103]
	v_mfma_f32_16x16x32_bf16 v[96:99], v[160:163], v[212:215], v[96:99]
	v_mfma_f32_16x16x32_bf16 v[96:99], v[164:167], v[216:219], v[96:99]
	v_mfma_f32_16x16x32_bf16 v[68:71], v[168:171], v[188:191], v[68:71]
	v_mfma_f32_16x16x32_bf16 v[68:71], v[172:175], v[192:195], v[68:71]
	v_mfma_f32_16x16x32_bf16 v[64:67], v[176:179], v[188:191], v[64:67]
	v_mfma_f32_16x16x32_bf16 v[64:67], v[184:187], v[192:195], v[64:67]
	v_mfma_f32_16x16x32_bf16 v[52:55], v[168:171], v[196:199], v[52:55]
	v_mfma_f32_16x16x32_bf16 v[52:55], v[172:175], v[200:203], v[52:55]
	v_mfma_f32_16x16x32_bf16 v[48:51], v[176:179], v[196:199], v[48:51]
	v_mfma_f32_16x16x32_bf16 v[48:51], v[184:187], v[200:203], v[48:51]
	v_mfma_f32_16x16x32_bf16 v[44:47], v[168:171], v[204:207], v[44:47]
	v_mfma_f32_16x16x32_bf16 v[44:47], v[172:175], v[208:211], v[44:47]
	v_mfma_f32_16x16x32_bf16 v[40:43], v[176:179], v[204:207], v[40:43]
	v_mfma_f32_16x16x32_bf16 v[40:43], v[184:187], v[208:211], v[40:43]
	v_mfma_f32_16x16x32_bf16 v[36:39], v[168:171], v[212:215], v[36:39]
	v_mfma_f32_16x16x32_bf16 v[36:39], v[172:175], v[216:219], v[36:39]
	s_barrier
	v_mfma_f32_16x16x32_bf16 v[32:35], v[176:179], v[212:215], v[32:35]
	v_mfma_f32_16x16x32_bf16 v[32:35], v[184:187], v[216:219], v[32:35]
	s_setprio 0
	s_add_i32 s64, s79, s68
	v_lshl_add_u64 v[220:221], v[220:221], 0, s[12:13]
	s_mov_b32 m0, s64
	ds_read_b128 v[188:191], v150 offset:49152
	ds_read_b128 v[192:195], v150 offset:50176
	ds_read_b128 v[196:199], v150 offset:51200
	ds_read_b128 v[200:203], v150 offset:52224
	ds_read_b128 v[204:207], v150 offset:53248
	ds_read_b128 v[208:211], v150 offset:54272
	ds_read_b128 v[212:215], v150 offset:55296
	ds_read_b128 v[216:219], v150 offset:56320
	global_load_lds_dwordx4 v[220:221], off
	s_add_i32 m0, s64, 0x2000
	s_add_u32 s62, s62, 0x40080
	v_lshl_add_u64 v[220:221], v[222:223], 0, s[12:13]
	s_addc_u32 s63, s63, 0
	s_add_i32 s64, s88, s68
	global_load_lds_dwordx4 v[220:221], off
	v_lshl_add_u64 v[220:221], s[62:63], 0, v[130:131]
	s_mov_b32 m0, s64
	s_nop 0
	global_load_lds_dwordx4 v[220:221], off
	v_lshl_add_u64 v[220:221], s[62:63], 0, v[134:135]
	s_add_i32 m0, s64, 0x2000
	s_nop 0
	global_load_lds_dwordx4 v[220:221], off
	v_lshl_add_u64 v[220:221], v[224:225], 0, s[12:13]
	s_mov_b32 m0, s75
	s_nop 0
	global_load_lds_dwordx4 v[220:221], off
	v_lshl_add_u64 v[220:221], v[226:227], 0, s[12:13]
	s_mov_b32 m0, s76
	s_nop 0
	global_load_lds_dwordx4 v[220:221], off
	s_waitcnt vmcnt(8)
	s_waitcnt lgkmcnt(0)
	s_barrier
	s_waitcnt lgkmcnt(0)
	v_mfma_f32_16x16x32_bf16 v[92:95], v[152:155], v[188:191], v[92:95]
	v_mfma_f32_16x16x32_bf16 v[92:95], v[156:159], v[192:195], v[92:95]
	s_setprio 1
	v_mfma_f32_16x16x32_bf16 v[88:91], v[160:163], v[188:191], v[88:91]
	v_mfma_f32_16x16x32_bf16 v[88:91], v[164:167], v[192:195], v[88:91]
	v_mfma_f32_16x16x32_bf16 v[84:87], v[152:155], v[196:199], v[84:87]
	v_mfma_f32_16x16x32_bf16 v[84:87], v[156:159], v[200:203], v[84:87]
	v_mfma_f32_16x16x32_bf16 v[80:83], v[160:163], v[196:199], v[80:83]
	v_mfma_f32_16x16x32_bf16 v[80:83], v[164:167], v[200:203], v[80:83]
	v_mfma_f32_16x16x32_bf16 v[76:79], v[152:155], v[204:207], v[76:79]
	v_mfma_f32_16x16x32_bf16 v[76:79], v[156:159], v[208:211], v[76:79]
	v_mfma_f32_16x16x32_bf16 v[72:75], v[160:163], v[204:207], v[72:75]
	v_mfma_f32_16x16x32_bf16 v[72:75], v[164:167], v[208:211], v[72:75]
	v_mfma_f32_16x16x32_bf16 v[60:63], v[152:155], v[212:215], v[60:63]
	v_mfma_f32_16x16x32_bf16 v[60:63], v[156:159], v[216:219], v[60:63]
	v_mfma_f32_16x16x32_bf16 v[56:59], v[160:163], v[212:215], v[56:59]
	v_mfma_f32_16x16x32_bf16 v[56:59], v[164:167], v[216:219], v[56:59]
	v_mfma_f32_16x16x32_bf16 v[28:31], v[168:171], v[188:191], v[28:31]
	v_mfma_f32_16x16x32_bf16 v[28:31], v[172:175], v[192:195], v[28:31]
	v_mfma_f32_16x16x32_bf16 v[24:27], v[176:179], v[188:191], v[24:27]
	v_mfma_f32_16x16x32_bf16 v[24:27], v[184:187], v[192:195], v[24:27]
	v_mfma_f32_16x16x32_bf16 v[20:23], v[168:171], v[196:199], v[20:23]
	v_mfma_f32_16x16x32_bf16 v[20:23], v[172:175], v[200:203], v[20:23]
	v_mfma_f32_16x16x32_bf16 v[16:19], v[176:179], v[196:199], v[16:19]
	v_mfma_f32_16x16x32_bf16 v[16:19], v[184:187], v[200:203], v[16:19]
	v_mfma_f32_16x16x32_bf16 v[12:15], v[168:171], v[204:207], v[12:15]
	v_mfma_f32_16x16x32_bf16 v[12:15], v[172:175], v[208:211], v[12:15]
	v_mfma_f32_16x16x32_bf16 v[8:11], v[176:179], v[204:207], v[8:11]
	v_mfma_f32_16x16x32_bf16 v[8:11], v[184:187], v[208:211], v[8:11]
	v_mfma_f32_16x16x32_bf16 v[4:7], v[168:171], v[212:215], v[4:7]
	v_mfma_f32_16x16x32_bf16 v[4:7], v[172:175], v[216:219], v[4:7]
	s_barrier
	v_mfma_f32_16x16x32_bf16 v[0:3], v[176:179], v[212:215], v[0:3]
	v_mfma_f32_16x16x32_bf16 v[0:3], v[184:187], v[216:219], v[0:3]
	s_setprio 0
	s_add_i32 s87, s87, 2
	s_add_u32 s60, s60, 0x100
	s_addc_u32 s61, s61, 0
	s_add_u32 s85, s85, 0x100
	s_addc_u32 s86, s86, 0
	s_cmp_gt_u32 s87, 13
	s_cbranch_scc0 .LBB0_1162
	s_and_b64 vcc, exec, s[16:17]
	s_cbranch_vccz .LBB0_1165
	s_barrier
	s_setprio 1
.LBB0_1165:
	s_lshl_b32 s49, s59, 8
	s_or_b32 s49, s49, s74
	v_lshl_add_u32 v152, s58, 8, v146
	s_ashr_i32 s58, s49, 6
	s_ashr_i32 s59, s58, 31
	s_lshl_b64 s[60:61], s[58:59], 22
	s_cmp_lt_i32 s58, 16
	s_cselect_b64 vcc, -1, 0
	v_cndmask_b32_e32 v156, 1.0, v151, vcc
	v_pk_mul_f32 v[124:125], v[156:157], v[124:125] op_sel_hi:[0,1]
	v_ashrrev_i32_e32 v153, 31, v152
	v_lshl_add_u64 v[154:155], v[136:137], 0, s[60:61]
	v_pk_mul_f32 v[126:127], v[156:157], v[126:127] op_sel_hi:[0,1]
	v_pk_mul_f32 v[158:159], v[156:157], v[122:123] op_sel_hi:[0,1]
	v_pk_mul_f32 v[122:123], v[156:157], v[120:121] op_sel_hi:[0,1]
	v_cvt_pk_bf16_f32 v120, v124, v125
	v_lshlrev_b64 v[124:125], 7, v[152:153]
	v_cvt_pk_bf16_f32 v121, v126, v127
	v_lshl_add_u64 v[126:127], v[154:155], 0, v[124:125]
	v_pk_mul_f32 v[116:117], v[156:157], v[116:117] op_sel_hi:[0,1]
	v_cvt_pk_bf16_f32 v122, v122, v123
	v_cvt_pk_bf16_f32 v123, v158, v159
	global_store_dwordx4 v[126:127], v[120:123], off
	v_pk_mul_f32 v[118:119], v[156:157], v[118:119] op_sel_hi:[0,1]
	v_pk_mul_f32 v[108:109], v[156:157], v[108:109] op_sel_hi:[0,1]
	v_pk_mul_f32 v[120:121], v[156:157], v[114:115] op_sel_hi:[0,1]
	v_pk_mul_f32 v[114:115], v[156:157], v[112:113] op_sel_hi:[0,1]
	v_cvt_pk_bf16_f32 v112, v116, v117
	v_or_b32_e32 v116, 16, v152
	v_ashrrev_i32_e32 v117, 31, v116
	v_lshlrev_b64 v[116:117], 7, v[116:117]
	v_cvt_pk_bf16_f32 v113, v118, v119
	v_lshl_add_u64 v[118:119], v[154:155], 0, v[116:117]
	v_cvt_pk_bf16_f32 v114, v114, v115
	v_cvt_pk_bf16_f32 v115, v120, v121
	global_store_dwordx4 v[118:119], v[112:115], off
	v_pk_mul_f32 v[110:111], v[156:157], v[110:111] op_sel_hi:[0,1]
	v_pk_mul_f32 v[100:101], v[156:157], v[100:101] op_sel_hi:[0,1]
	v_pk_mul_f32 v[112:113], v[156:157], v[106:107] op_sel_hi:[0,1]
	v_pk_mul_f32 v[106:107], v[156:157], v[104:105] op_sel_hi:[0,1]
	v_cvt_pk_bf16_f32 v104, v108, v109
	v_or_b32_e32 v108, 32, v152
	v_ashrrev_i32_e32 v109, 31, v108
	v_lshlrev_b64 v[108:109], 7, v[108:109]
	v_cvt_pk_bf16_f32 v105, v110, v111
	v_lshl_add_u64 v[110:111], v[154:155], 0, v[108:109]
	v_cvt_pk_bf16_f32 v106, v106, v107
	v_cvt_pk_bf16_f32 v107, v112, v113
	global_store_dwordx4 v[110:111], v[104:107], off
	v_pk_mul_f32 v[102:103], v[156:157], v[102:103] op_sel_hi:[0,1]
	v_pk_mul_f32 v[92:93], v[156:157], v[92:93] op_sel_hi:[0,1]
	v_pk_mul_f32 v[104:105], v[156:157], v[98:99] op_sel_hi:[0,1]
	v_pk_mul_f32 v[98:99], v[156:157], v[96:97] op_sel_hi:[0,1]
	v_cvt_pk_bf16_f32 v96, v100, v101
	v_or_b32_e32 v100, 48, v152
	v_ashrrev_i32_e32 v101, 31, v100
	v_lshlrev_b64 v[100:101], 7, v[100:101]
	v_cvt_pk_bf16_f32 v97, v102, v103
	v_lshl_add_u64 v[102:103], v[154:155], 0, v[100:101]
	v_cvt_pk_bf16_f32 v98, v98, v99
	v_cvt_pk_bf16_f32 v99, v104, v105
	global_store_dwordx4 v[102:103], v[96:99], off
	v_pk_mul_f32 v[94:95], v[156:157], v[94:95] op_sel_hi:[0,1]
	v_pk_mul_f32 v[84:85], v[156:157], v[84:85] op_sel_hi:[0,1]
	v_pk_mul_f32 v[96:97], v[156:157], v[90:91] op_sel_hi:[0,1]
	v_pk_mul_f32 v[90:91], v[156:157], v[88:89] op_sel_hi:[0,1]
	v_cvt_pk_bf16_f32 v88, v92, v93
	v_lshl_add_u64 v[92:93], v[124:125], 0, s[18:19]
	v_cvt_pk_bf16_f32 v89, v94, v95
	v_lshl_add_u64 v[94:95], v[154:155], 0, v[92:93]
	v_cvt_pk_bf16_f32 v90, v90, v91
	v_cvt_pk_bf16_f32 v91, v96, v97
	global_store_dwordx4 v[94:95], v[88:91], off
	v_pk_mul_f32 v[86:87], v[156:157], v[86:87] op_sel_hi:[0,1]
	s_or_b32 s58, s58, 2
	v_pk_mul_f32 v[88:89], v[156:157], v[82:83] op_sel_hi:[0,1]
	v_pk_mul_f32 v[82:83], v[156:157], v[80:81] op_sel_hi:[0,1]
	v_cvt_pk_bf16_f32 v80, v84, v85
	v_lshl_add_u64 v[84:85], v[124:125], 0, s[36:37]
	v_cvt_pk_bf16_f32 v81, v86, v87
	v_lshl_add_u64 v[86:87], v[154:155], 0, v[84:85]
	v_pk_mul_f32 v[76:77], v[156:157], v[76:77] op_sel_hi:[0,1]
	s_ashr_i32 s59, s58, 31
	v_cvt_pk_bf16_f32 v82, v82, v83
	v_cvt_pk_bf16_f32 v83, v88, v89
	global_store_dwordx4 v[86:87], v[80:83], off
	v_pk_mul_f32 v[78:79], v[156:157], v[78:79] op_sel_hi:[0,1]
	s_lshl_b64 s[60:61], s[58:59], 22
	v_pk_mul_f32 v[80:81], v[156:157], v[74:75] op_sel_hi:[0,1]
	v_pk_mul_f32 v[74:75], v[156:157], v[72:73] op_sel_hi:[0,1]
	v_cvt_pk_bf16_f32 v72, v76, v77
	v_lshl_add_u64 v[76:77], v[124:125], 0, s[44:45]
	v_cvt_pk_bf16_f32 v73, v78, v79
	v_lshl_add_u64 v[78:79], v[154:155], 0, v[76:77]
	v_pk_mul_f32 v[60:61], v[156:157], v[60:61] op_sel_hi:[0,1]
	s_cmp_lt_i32 s58, 16
	v_cvt_pk_bf16_f32 v74, v74, v75
	v_cvt_pk_bf16_f32 v75, v80, v81
	global_store_dwordx4 v[78:79], v[72:75], off
	v_pk_mul_f32 v[62:63], v[156:157], v[62:63] op_sel_hi:[0,1]
	s_cselect_b64 vcc, -1, 0
	v_pk_mul_f32 v[72:73], v[156:157], v[58:59] op_sel_hi:[0,1]
	v_pk_mul_f32 v[58:59], v[156:157], v[56:57] op_sel_hi:[0,1]
	v_cvt_pk_bf16_f32 v56, v60, v61
	v_lshl_add_u64 v[60:61], v[124:125], 0, s[46:47]
	v_cvt_pk_bf16_f32 v57, v62, v63
	v_cvt_pk_bf16_f32 v58, v58, v59
	v_cvt_pk_bf16_f32 v59, v72, v73
	v_lshl_add_u64 v[62:63], v[154:155], 0, v[60:61]
	v_cndmask_b32_e32 v72, 1.0, v151, vcc
	global_store_dwordx4 v[62:63], v[56:59], off
	v_lshl_add_u64 v[62:63], v[136:137], 0, s[60:61]
	v_pk_mul_f32 v[64:65], v[72:73], v[64:65] op_sel_hi:[0,1]
	v_pk_mul_f32 v[58:59], v[72:73], v[70:71] op_sel_hi:[0,1]
	v_pk_mul_f32 v[56:57], v[72:73], v[68:69] op_sel_hi:[0,1]
	v_cvt_pk_bf16_f32 v56, v56, v57
	v_cvt_pk_bf16_f32 v57, v58, v59
	v_cvt_pk_bf16_f32 v58, v64, v65
	v_lshl_add_u64 v[64:65], v[62:63], 0, v[124:125]
	v_pk_mul_f32 v[52:53], v[72:73], v[52:53] op_sel_hi:[0,1]
	v_pk_mul_f32 v[66:67], v[72:73], v[66:67] op_sel_hi:[0,1]
	v_cvt_pk_bf16_f32 v59, v66, v67
	global_store_dwordx4 v[64:65], v[56:59], off
	v_pk_mul_f32 v[54:55], v[72:73], v[54:55] op_sel_hi:[0,1]
	v_pk_mul_f32 v[44:45], v[72:73], v[44:45] op_sel_hi:[0,1]
	v_pk_mul_f32 v[56:57], v[72:73], v[50:51] op_sel_hi:[0,1]
	v_pk_mul_f32 v[50:51], v[72:73], v[48:49] op_sel_hi:[0,1]
	v_cvt_pk_bf16_f32 v48, v52, v53
	v_cvt_pk_bf16_f32 v49, v54, v55
	v_lshl_add_u64 v[52:53], v[62:63], 0, v[116:117]
	v_cvt_pk_bf16_f32 v50, v50, v51
	v_cvt_pk_bf16_f32 v51, v56, v57
	global_store_dwordx4 v[52:53], v[48:51], off
	v_pk_mul_f32 v[46:47], v[72:73], v[46:47] op_sel_hi:[0,1]
	v_pk_mul_f32 v[36:37], v[72:73], v[36:37] op_sel_hi:[0,1]
	v_pk_mul_f32 v[48:49], v[72:73], v[42:43] op_sel_hi:[0,1]
	v_pk_mul_f32 v[42:43], v[72:73], v[40:41] op_sel_hi:[0,1]
	v_cvt_pk_bf16_f32 v40, v44, v45
	v_cvt_pk_bf16_f32 v41, v46, v47
	v_lshl_add_u64 v[44:45], v[62:63], 0, v[108:109]
	v_cvt_pk_bf16_f32 v42, v42, v43
	v_cvt_pk_bf16_f32 v43, v48, v49
	global_store_dwordx4 v[44:45], v[40:43], off
	v_pk_mul_f32 v[38:39], v[72:73], v[38:39] op_sel_hi:[0,1]
	v_pk_mul_f32 v[28:29], v[72:73], v[28:29] op_sel_hi:[0,1]
	v_pk_mul_f32 v[40:41], v[72:73], v[34:35] op_sel_hi:[0,1]
	v_pk_mul_f32 v[34:35], v[72:73], v[32:33] op_sel_hi:[0,1]
	v_cvt_pk_bf16_f32 v32, v36, v37
	v_cvt_pk_bf16_f32 v33, v38, v39
	v_lshl_add_u64 v[36:37], v[62:63], 0, v[100:101]
	v_cvt_pk_bf16_f32 v34, v34, v35
	v_cvt_pk_bf16_f32 v35, v40, v41
	global_store_dwordx4 v[36:37], v[32:35], off
	v_pk_mul_f32 v[30:31], v[72:73], v[30:31] op_sel_hi:[0,1]
	v_pk_mul_f32 v[20:21], v[72:73], v[20:21] op_sel_hi:[0,1]
	v_pk_mul_f32 v[32:33], v[72:73], v[26:27] op_sel_hi:[0,1]
	v_pk_mul_f32 v[26:27], v[72:73], v[24:25] op_sel_hi:[0,1]
	v_cvt_pk_bf16_f32 v24, v28, v29
	v_cvt_pk_bf16_f32 v25, v30, v31
	v_lshl_add_u64 v[28:29], v[62:63], 0, v[92:93]
	v_cvt_pk_bf16_f32 v26, v26, v27
	v_cvt_pk_bf16_f32 v27, v32, v33
	global_store_dwordx4 v[28:29], v[24:27], off
	v_pk_mul_f32 v[22:23], v[72:73], v[22:23] op_sel_hi:[0,1]
	v_pk_mul_f32 v[12:13], v[72:73], v[12:13] op_sel_hi:[0,1]
	v_pk_mul_f32 v[24:25], v[72:73], v[18:19] op_sel_hi:[0,1]
	v_pk_mul_f32 v[18:19], v[72:73], v[16:17] op_sel_hi:[0,1]
	v_cvt_pk_bf16_f32 v16, v20, v21
	v_cvt_pk_bf16_f32 v17, v22, v23
	v_lshl_add_u64 v[20:21], v[62:63], 0, v[84:85]
	v_cvt_pk_bf16_f32 v18, v18, v19
	v_cvt_pk_bf16_f32 v19, v24, v25
	global_store_dwordx4 v[20:21], v[16:19], off
	v_pk_mul_f32 v[14:15], v[72:73], v[14:15] op_sel_hi:[0,1]
	v_pk_mul_f32 v[4:5], v[72:73], v[4:5] op_sel_hi:[0,1]
	v_pk_mul_f32 v[16:17], v[72:73], v[10:11] op_sel_hi:[0,1]
	v_pk_mul_f32 v[10:11], v[72:73], v[8:9] op_sel_hi:[0,1]
	v_cvt_pk_bf16_f32 v8, v12, v13
	v_cvt_pk_bf16_f32 v9, v14, v15
	v_lshl_add_u64 v[12:13], v[62:63], 0, v[76:77]
	v_cvt_pk_bf16_f32 v10, v10, v11
	v_cvt_pk_bf16_f32 v11, v16, v17
	global_store_dwordx4 v[12:13], v[8:11], off
	s_andn2_b64 vcc, exec, s[10:11]
	s_mov_b64 s[10:11], -1
	v_pk_mul_f32 v[8:9], v[72:73], v[2:3] op_sel_hi:[0,1]
	v_pk_mul_f32 v[2:3], v[72:73], v[0:1] op_sel_hi:[0,1]
	v_cvt_pk_bf16_f32 v0, v4, v5
	v_lshl_add_u64 v[4:5], v[62:63], 0, v[60:61]
	v_pk_mul_f32 v[6:7], v[72:73], v[6:7] op_sel_hi:[0,1]
	v_cvt_pk_bf16_f32 v1, v6, v7
	v_cvt_pk_bf16_f32 v2, v2, v3
	v_cvt_pk_bf16_f32 v3, v8, v9
	global_store_dwordx4 v[4:5], v[0:3], off
	s_setprio 0
	s_cbranch_vccnz .LBB0_1154
	s_andn2_b64 vcc, exec, s[0:1]
	s_cbranch_vccnz .LBB0_1153
	s_barrier
	s_branch .LBB0_1153

.Lmid_gemm10:
	s_add_i32 s79, 0, 0x18000
	s_add_i32 s87, 0, 0x1c000
	v_add_u32_e32 v164, s79, v147
	v_add_u32_e32 v181, s87, v147
	ds_read_b128 v[152:155], v164
	ds_read_b128 v[156:159], v164 offset:1024
	ds_read_b128 v[160:163], v164 offset:2048
	ds_read_b128 v[164:167], v164 offset:3072
	ds_read_b128 v[168:171], v181
	ds_read_b128 v[172:175], v181 offset:1024
	ds_read_b128 v[176:179], v181 offset:2048
	ds_read_b128 v[184:187], v181 offset:3072
	s_add_u32 s60, s60, 0x40000
	s_addc_u32 s61, s61, 0
	s_mov_b32 m0, s66
	v_lshl_add_u64 v[226:227], s[60:61], 0, v[128:129]
	ds_read_b128 v[188:191], v151 offset:32768
	ds_read_b128 v[192:195], v151 offset:33792
	ds_read_b128 v[196:199], v151 offset:34816
	ds_read_b128 v[200:203], v151 offset:35840
	ds_read_b128 v[204:207], v151 offset:36864
	ds_read_b128 v[208:211], v151 offset:37888
	ds_read_b128 v[212:215], v151 offset:38912
	ds_read_b128 v[216:219], v151 offset:39936
	global_load_lds_dwordx4 v[226:227], off
	v_lshl_add_u64 v[226:227], s[60:61], 0, v[132:133]
	s_mov_b32 m0, s67
	s_nop 0
	global_load_lds_dwordx4 v[226:227], off
	s_waitcnt vmcnt(8)
	s_waitcnt lgkmcnt(0)
	s_barrier
	s_waitcnt lgkmcnt(0)
	v_mfma_f32_16x16x32_bf16 v[124:127], v[152:155], v[188:191], v[124:127]
	v_mfma_f32_16x16x32_bf16 v[124:127], v[156:159], v[192:195], v[124:127]
	s_setprio 1
	v_mfma_f32_16x16x32_bf16 v[120:123], v[160:163], v[188:191], v[120:123]
	v_mfma_f32_16x16x32_bf16 v[120:123], v[164:167], v[192:195], v[120:123]
	v_mfma_f32_16x16x32_bf16 v[116:119], v[152:155], v[196:199], v[116:119]
	v_mfma_f32_16x16x32_bf16 v[116:119], v[156:159], v[200:203], v[116:119]
	v_mfma_f32_16x16x32_bf16 v[108:111], v[160:163], v[196:199], v[108:111]
	v_mfma_f32_16x16x32_bf16 v[108:111], v[164:167], v[200:203], v[108:111]
	v_mfma_f32_16x16x32_bf16 v[100:103], v[152:155], v[204:207], v[100:103]
	v_mfma_f32_16x16x32_bf16 v[100:103], v[156:159], v[208:211], v[100:103]
	v_mfma_f32_16x16x32_bf16 v[92:95], v[160:163], v[204:207], v[92:95]
	v_mfma_f32_16x16x32_bf16 v[92:95], v[164:167], v[208:211], v[92:95]
	v_mfma_f32_16x16x32_bf16 v[84:87], v[152:155], v[212:215], v[84:87]
	v_mfma_f32_16x16x32_bf16 v[84:87], v[156:159], v[216:219], v[84:87]
	v_mfma_f32_16x16x32_bf16 v[76:79], v[160:163], v[212:215], v[76:79]
	v_mfma_f32_16x16x32_bf16 v[76:79], v[164:167], v[216:219], v[76:79]
	v_mfma_f32_16x16x32_bf16 v[112:115], v[168:171], v[188:191], v[112:115]
	v_mfma_f32_16x16x32_bf16 v[112:115], v[172:175], v[192:195], v[112:115]
	v_mfma_f32_16x16x32_bf16 v[104:107], v[176:179], v[188:191], v[104:107]
	v_mfma_f32_16x16x32_bf16 v[104:107], v[184:187], v[192:195], v[104:107]
	v_mfma_f32_16x16x32_bf16 v[96:99], v[168:171], v[196:199], v[96:99]
	v_mfma_f32_16x16x32_bf16 v[96:99], v[172:175], v[200:203], v[96:99]
	v_mfma_f32_16x16x32_bf16 v[88:91], v[176:179], v[196:199], v[88:91]
	v_mfma_f32_16x16x32_bf16 v[88:91], v[184:187], v[200:203], v[88:91]
	v_mfma_f32_16x16x32_bf16 v[80:83], v[168:171], v[204:207], v[80:83]
	v_mfma_f32_16x16x32_bf16 v[80:83], v[172:175], v[208:211], v[80:83]
	v_mfma_f32_16x16x32_bf16 v[72:75], v[176:179], v[204:207], v[72:75]
	v_mfma_f32_16x16x32_bf16 v[72:75], v[184:187], v[208:211], v[72:75]
	v_mfma_f32_16x16x32_bf16 v[68:71], v[168:171], v[212:215], v[68:71]
	v_mfma_f32_16x16x32_bf16 v[68:71], v[172:175], v[216:219], v[68:71]
	s_barrier
	v_mfma_f32_16x16x32_bf16 v[64:67], v[176:179], v[212:215], v[64:67]
	v_mfma_f32_16x16x32_bf16 v[64:67], v[184:187], v[216:219], v[64:67]
	s_setprio 0
	s_add_i32 s60, s79, s64
	v_lshl_add_u64 v[144:145], v[144:145], 0, s[16:17]
	s_mov_b32 m0, s60
	ds_read_b128 v[188:191], v151 offset:49152
	ds_read_b128 v[192:195], v151 offset:50176
	ds_read_b128 v[196:199], v151 offset:51200
	ds_read_b128 v[200:203], v151 offset:52224
	ds_read_b128 v[204:207], v151 offset:53248
	ds_read_b128 v[208:211], v151 offset:54272
	ds_read_b128 v[212:215], v151 offset:55296
	ds_read_b128 v[216:219], v151 offset:56320
	global_load_lds_dwordx4 v[144:145], off
	s_add_i32 m0, s60, 0x2000
	s_add_u32 s58, s58, 0x40080
	v_lshl_add_u64 v[144:145], v[220:221], 0, s[16:17]
	s_addc_u32 s59, s59, 0
	s_add_i32 s60, s87, s64
	global_load_lds_dwordx4 v[144:145], off
	v_lshl_add_u64 v[144:145], s[58:59], 0, v[130:131]
	s_mov_b32 m0, s60
	s_nop 0
	global_load_lds_dwordx4 v[144:145], off
	v_lshl_add_u64 v[144:145], s[58:59], 0, v[134:135]
	s_add_i32 m0, s60, 0x2000
	s_nop 0
	global_load_lds_dwordx4 v[144:145], off
	v_lshl_add_u64 v[144:145], v[222:223], 0, s[16:17]
	s_mov_b32 m0, s69
	s_nop 0
	global_load_lds_dwordx4 v[144:145], off
	v_lshl_add_u64 v[144:145], v[224:225], 0, s[16:17]
	s_mov_b32 m0, s70
	s_nop 0
	global_load_lds_dwordx4 v[144:145], off
	s_waitcnt vmcnt(8)
	s_waitcnt lgkmcnt(0)
	s_barrier
	s_waitcnt lgkmcnt(0)
	v_mfma_f32_16x16x32_bf16 v[60:63], v[152:155], v[188:191], v[60:63]
	v_mfma_f32_16x16x32_bf16 v[60:63], v[156:159], v[192:195], v[60:63]
	s_setprio 1
	v_mfma_f32_16x16x32_bf16 v[56:59], v[160:163], v[188:191], v[56:59]
	v_mfma_f32_16x16x32_bf16 v[56:59], v[164:167], v[192:195], v[56:59]
	v_mfma_f32_16x16x32_bf16 v[52:55], v[152:155], v[196:199], v[52:55]
	v_mfma_f32_16x16x32_bf16 v[52:55], v[156:159], v[200:203], v[52:55]
	v_mfma_f32_16x16x32_bf16 v[44:47], v[160:163], v[196:199], v[44:47]
	v_mfma_f32_16x16x32_bf16 v[44:47], v[164:167], v[200:203], v[44:47]
	v_mfma_f32_16x16x32_bf16 v[36:39], v[152:155], v[204:207], v[36:39]
	v_mfma_f32_16x16x32_bf16 v[36:39], v[156:159], v[208:211], v[36:39]
	v_mfma_f32_16x16x32_bf16 v[28:31], v[160:163], v[204:207], v[28:31]
	v_mfma_f32_16x16x32_bf16 v[28:31], v[164:167], v[208:211], v[28:31]
	v_mfma_f32_16x16x32_bf16 v[20:23], v[152:155], v[212:215], v[20:23]
	v_mfma_f32_16x16x32_bf16 v[20:23], v[156:159], v[216:219], v[20:23]
	v_mfma_f32_16x16x32_bf16 v[12:15], v[160:163], v[212:215], v[12:15]
	v_mfma_f32_16x16x32_bf16 v[12:15], v[164:167], v[216:219], v[12:15]
	v_mfma_f32_16x16x32_bf16 v[48:51], v[168:171], v[188:191], v[48:51]
	v_mfma_f32_16x16x32_bf16 v[48:51], v[172:175], v[192:195], v[48:51]
	v_mfma_f32_16x16x32_bf16 v[40:43], v[176:179], v[188:191], v[40:43]
	v_mfma_f32_16x16x32_bf16 v[40:43], v[184:187], v[192:195], v[40:43]
	v_mfma_f32_16x16x32_bf16 v[32:35], v[168:171], v[196:199], v[32:35]
	v_mfma_f32_16x16x32_bf16 v[32:35], v[172:175], v[200:203], v[32:35]
	v_mfma_f32_16x16x32_bf16 v[24:27], v[176:179], v[196:199], v[24:27]
	v_mfma_f32_16x16x32_bf16 v[24:27], v[184:187], v[200:203], v[24:27]
	v_mfma_f32_16x16x32_bf16 v[16:19], v[168:171], v[204:207], v[16:19]
	v_mfma_f32_16x16x32_bf16 v[16:19], v[172:175], v[208:211], v[16:19]
	v_mfma_f32_16x16x32_bf16 v[8:11], v[176:179], v[204:207], v[8:11]
	v_mfma_f32_16x16x32_bf16 v[8:11], v[184:187], v[208:211], v[8:11]
	v_mfma_f32_16x16x32_bf16 v[4:7], v[168:171], v[212:215], v[4:7]
	v_mfma_f32_16x16x32_bf16 v[4:7], v[172:175], v[216:219], v[4:7]
	s_barrier
	v_mfma_f32_16x16x32_bf16 v[0:3], v[176:179], v[212:215], v[0:3]
	v_mfma_f32_16x16x32_bf16 v[0:3], v[184:187], v[216:219], v[0:3]
	s_setprio 0
	s_add_i32 s86, s86, 2
	s_add_u32 s56, s56, 0x100
	s_addc_u32 s57, s57, 0
	s_add_u32 s84, s84, 0x100
	s_addc_u32 s85, s85, 0
	s_cmp_gt_u32 s86, 13
	s_cbranch_scc0 .LBB0_1311
	s_and_b64 vcc, exec, s[18:19]
	s_cbranch_vccz .LBB0_1314
	s_barrier
	s_setprio 1
.LBB0_1314:
	v_lshl_add_u32 v152, s54, 8, v146
	v_lshl_or_b32 v144, s77, 8, v148
	v_ashrrev_i32_e32 v145, 31, v144
	v_ashrrev_i32_e32 v153, 31, v152
	v_lshl_add_u64 v[154:155], v[144:145], 1, s[24:25]
	v_lshlrev_b64 v[144:145], 11, v[152:153]
	v_lshl_add_u64 v[144:145], v[154:155], 0, v[144:145]
	s_nop 15
	s_nop 7
	v_cvt_pk_bf16_f32 v124, v124, v125
	v_cvt_pk_bf16_f32 v125, v126, v127
	v_cvt_pk_bf16_f32 v126, v120, v121
	v_cvt_pk_bf16_f32 v127, v122, v123
	global_store_dwordx4 v[144:145], v[124:127], off
	v_cvt_pk_bf16_f32 v112, v112, v113
	v_cvt_pk_bf16_f32 v113, v114, v115
	v_cvt_pk_bf16_f32 v114, v104, v105
	v_or_b32_e32 v104, 16, v152
	v_ashrrev_i32_e32 v105, 31, v104
	v_lshlrev_b64 v[104:105], 11, v[104:105]
	v_cvt_pk_bf16_f32 v115, v106, v107
	global_store_dwordx4 v[144:145], v[112:115], off offset:256
	s_nop 1
	v_lshl_add_u64 v[112:113], v[154:155], 0, v[104:105]
	v_cvt_pk_bf16_f32 v104, v116, v117
	v_cvt_pk_bf16_f32 v105, v118, v119
	v_cvt_pk_bf16_f32 v106, v108, v109
	v_cvt_pk_bf16_f32 v107, v110, v111
	global_store_dwordx4 v[112:113], v[104:107], off
	v_cvt_pk_bf16_f32 v96, v96, v97
	v_cvt_pk_bf16_f32 v97, v98, v99
	v_cvt_pk_bf16_f32 v98, v88, v89
	v_or_b32_e32 v88, 32, v152
	v_ashrrev_i32_e32 v89, 31, v88
	v_lshlrev_b64 v[88:89], 11, v[88:89]
	v_cvt_pk_bf16_f32 v99, v90, v91
	global_store_dwordx4 v[112:113], v[96:99], off offset:256
	s_nop 1
	v_lshl_add_u64 v[96:97], v[154:155], 0, v[88:89]
	v_cvt_pk_bf16_f32 v88, v100, v101
	v_cvt_pk_bf16_f32 v89, v102, v103
	v_cvt_pk_bf16_f32 v90, v92, v93
	v_cvt_pk_bf16_f32 v91, v94, v95
	global_store_dwordx4 v[96:97], v[88:91], off
	v_cvt_pk_bf16_f32 v80, v80, v81
	v_cvt_pk_bf16_f32 v81, v82, v83
	v_cvt_pk_bf16_f32 v82, v72, v73
	v_or_b32_e32 v72, 48, v152
	v_ashrrev_i32_e32 v73, 31, v72
	v_lshlrev_b64 v[72:73], 11, v[72:73]
	v_cvt_pk_bf16_f32 v83, v74, v75
	global_store_dwordx4 v[96:97], v[80:83], off offset:256
	s_nop 1
	v_lshl_add_u64 v[80:81], v[154:155], 0, v[72:73]
	v_cvt_pk_bf16_f32 v72, v84, v85
	v_cvt_pk_bf16_f32 v73, v86, v87
	v_cvt_pk_bf16_f32 v74, v76, v77
	v_cvt_pk_bf16_f32 v75, v78, v79
	global_store_dwordx4 v[80:81], v[72:75], off
	v_cvt_pk_bf16_f32 v68, v68, v69
	v_cvt_pk_bf16_f32 v69, v70, v71
	v_cvt_pk_bf16_f32 v70, v64, v65
	v_cvt_pk_bf16_f32 v71, v66, v67
	global_store_dwordx4 v[80:81], v[68:71], off offset:256
	v_cvt_pk_bf16_f32 v60, v60, v61
	v_cvt_pk_bf16_f32 v61, v62, v63
	v_cvt_pk_bf16_f32 v62, v56, v57
	v_add_co_u32_e32 v56, vcc, s73, v144
	v_lshl_add_u64 v[64:65], v[144:145], 0, s[0:1]
	s_nop 0
	v_addc_co_u32_e32 v57, vcc, 0, v145, vcc
	v_cvt_pk_bf16_f32 v63, v58, v59
	global_store_dwordx4 v[56:57], v[60:63], off
	v_cvt_pk_bf16_f32 v48, v48, v49
	v_cvt_pk_bf16_f32 v49, v50, v51
	v_cvt_pk_bf16_f32 v50, v40, v41
	v_cvt_pk_bf16_f32 v51, v42, v43
	global_store_dwordx4 v[64:65], v[48:51], off offset:256
	v_cvt_pk_bf16_f32 v40, v52, v53
	v_cvt_pk_bf16_f32 v41, v54, v55
	v_cvt_pk_bf16_f32 v42, v44, v45
	v_add_co_u32_e32 v44, vcc, s74, v144
	s_nop 0
	v_lshl_add_u64 v[48:49], v[144:145], 0, s[30:31]
	v_addc_co_u32_e32 v45, vcc, 0, v145, vcc
	v_cvt_pk_bf16_f32 v43, v46, v47
	global_store_dwordx4 v[44:45], v[40:43], off
	v_cvt_pk_bf16_f32 v32, v32, v33
	v_cvt_pk_bf16_f32 v33, v34, v35
	v_cvt_pk_bf16_f32 v34, v24, v25
	v_cvt_pk_bf16_f32 v35, v26, v27
	global_store_dwordx4 v[48:49], v[32:35], off offset:256
	v_cvt_pk_bf16_f32 v24, v36, v37
	v_cvt_pk_bf16_f32 v25, v38, v39
	v_cvt_pk_bf16_f32 v26, v28, v29
	v_add_co_u32_e32 v28, vcc, s75, v144
	s_nop 0
	v_lshl_add_u64 v[32:33], v[144:145], 0, s[36:37]
	v_addc_co_u32_e32 v29, vcc, 0, v145, vcc
	v_cvt_pk_bf16_f32 v27, v30, v31
	global_store_dwordx4 v[28:29], v[24:27], off
	v_cvt_pk_bf16_f32 v16, v16, v17
	v_cvt_pk_bf16_f32 v17, v18, v19
	v_cvt_pk_bf16_f32 v18, v8, v9
	v_cvt_pk_bf16_f32 v19, v10, v11
	global_store_dwordx4 v[32:33], v[16:19], off offset:256
	v_cvt_pk_bf16_f32 v8, v20, v21
	v_cvt_pk_bf16_f32 v9, v22, v23
	v_cvt_pk_bf16_f32 v10, v12, v13
	v_add_co_u32_e32 v12, vcc, s76, v144
	s_nop 0
	v_lshl_add_u64 v[16:17], v[144:145], 0, s[44:45]
	v_addc_co_u32_e32 v13, vcc, 0, v145, vcc
	s_andn2_b64 vcc, exec, s[10:11]
	s_mov_b64 s[10:11], -1
	v_cvt_pk_bf16_f32 v11, v14, v15
	global_store_dwordx4 v[12:13], v[8:11], off
	v_cvt_pk_bf16_f32 v4, v4, v5
	v_cvt_pk_bf16_f32 v5, v6, v7
	v_cvt_pk_bf16_f32 v6, v0, v1
	v_cvt_pk_bf16_f32 v7, v2, v3
	global_store_dwordx4 v[16:17], v[4:7], off offset:256
	s_setprio 0
	s_cbranch_vccnz .LBB0_1303
	s_andn2_b64 vcc, exec, s[12:13]
	s_cbranch_vccnz .LBB0_1302
	s_barrier
	s_branch .LBB0_1302

.Lmid_gemm11:
	s_add_i32 s71, 0, 0x18000
	s_add_i32 s72, 0, 0x1c000
	v_add_u32_e32 v158, s71, v145
	v_add_u32_e32 v174, s72, v145
	ds_read_b128 v[140:143], v158
	ds_read_b128 v[150:153], v158 offset:1024
	ds_read_b128 v[154:157], v158 offset:2048
	ds_read_b128 v[158:161], v158 offset:3072
	ds_read_b128 v[162:165], v174
	ds_read_b128 v[166:169], v174 offset:1024
	ds_read_b128 v[170:173], v174 offset:2048
	ds_read_b128 v[174:177], v174 offset:3072
	s_add_u32 s50, s50, 0x40000
	s_addc_u32 s51, s51, 0
	s_mov_b32 m0, s57
	v_lshl_add_u64 v[222:223], s[50:51], 0, v[130:131]
	ds_read_b128 v[184:187], v149 offset:32768
	ds_read_b128 v[188:191], v149 offset:33792
	ds_read_b128 v[192:195], v149 offset:34816
	ds_read_b128 v[196:199], v149 offset:35840
	ds_read_b128 v[200:203], v149 offset:36864
	ds_read_b128 v[204:207], v149 offset:37888
	ds_read_b128 v[208:211], v149 offset:38912
	ds_read_b128 v[212:215], v149 offset:39936
	global_load_lds_dwordx4 v[222:223], off
	v_lshl_add_u64 v[222:223], s[50:51], 0, v[128:129]
	s_mov_b32 m0, s58
	s_nop 0
	global_load_lds_dwordx4 v[222:223], off
	s_waitcnt vmcnt(8)
	s_waitcnt lgkmcnt(0)
	s_barrier
	s_waitcnt lgkmcnt(0)
	v_mfma_f32_16x16x32_bf16 v[124:127], v[140:143], v[184:187], v[124:127]
	v_mfma_f32_16x16x32_bf16 v[124:127], v[150:153], v[188:191], v[124:127]
	s_setprio 1
	v_mfma_f32_16x16x32_bf16 v[120:123], v[154:157], v[184:187], v[120:123]
	v_mfma_f32_16x16x32_bf16 v[120:123], v[158:161], v[188:191], v[120:123]
	v_mfma_f32_16x16x32_bf16 v[108:111], v[140:143], v[192:195], v[108:111]
	v_mfma_f32_16x16x32_bf16 v[108:111], v[150:153], v[196:199], v[108:111]
	v_mfma_f32_16x16x32_bf16 v[104:107], v[154:157], v[192:195], v[104:107]
	v_mfma_f32_16x16x32_bf16 v[104:107], v[158:161], v[196:199], v[104:107]
	v_mfma_f32_16x16x32_bf16 v[92:95], v[140:143], v[200:203], v[92:95]
	v_mfma_f32_16x16x32_bf16 v[92:95], v[150:153], v[204:207], v[92:95]
	v_mfma_f32_16x16x32_bf16 v[88:91], v[154:157], v[200:203], v[88:91]
	v_mfma_f32_16x16x32_bf16 v[88:91], v[158:161], v[204:207], v[88:91]
	v_mfma_f32_16x16x32_bf16 v[76:79], v[140:143], v[208:211], v[76:79]
	v_mfma_f32_16x16x32_bf16 v[76:79], v[150:153], v[212:215], v[76:79]
	v_mfma_f32_16x16x32_bf16 v[72:75], v[154:157], v[208:211], v[72:75]
	v_mfma_f32_16x16x32_bf16 v[72:75], v[158:161], v[212:215], v[72:75]
	v_mfma_f32_16x16x32_bf16 v[116:119], v[162:165], v[184:187], v[116:119]
	v_mfma_f32_16x16x32_bf16 v[116:119], v[166:169], v[188:191], v[116:119]
	v_mfma_f32_16x16x32_bf16 v[112:115], v[170:173], v[184:187], v[112:115]
	v_mfma_f32_16x16x32_bf16 v[112:115], v[174:177], v[188:191], v[112:115]
	v_mfma_f32_16x16x32_bf16 v[100:103], v[162:165], v[192:195], v[100:103]
	v_mfma_f32_16x16x32_bf16 v[100:103], v[166:169], v[196:199], v[100:103]
	v_mfma_f32_16x16x32_bf16 v[96:99], v[170:173], v[192:195], v[96:99]
	v_mfma_f32_16x16x32_bf16 v[96:99], v[174:177], v[196:199], v[96:99]
	v_mfma_f32_16x16x32_bf16 v[84:87], v[162:165], v[200:203], v[84:87]
	v_mfma_f32_16x16x32_bf16 v[84:87], v[166:169], v[204:207], v[84:87]
	v_mfma_f32_16x16x32_bf16 v[80:83], v[170:173], v[200:203], v[80:83]
	v_mfma_f32_16x16x32_bf16 v[80:83], v[174:177], v[204:207], v[80:83]
	v_mfma_f32_16x16x32_bf16 v[68:71], v[162:165], v[208:211], v[68:71]
	v_mfma_f32_16x16x32_bf16 v[68:71], v[166:169], v[212:215], v[68:71]
	s_barrier
	v_mfma_f32_16x16x32_bf16 v[64:67], v[170:173], v[208:211], v[64:67]
	v_mfma_f32_16x16x32_bf16 v[64:67], v[174:177], v[212:215], v[64:67]
	s_setprio 0
	s_add_i32 s50, s71, s54
	v_lshl_add_u64 v[178:179], v[178:179], 0, s[10:11]
	s_mov_b32 m0, s50
	ds_read_b128 v[184:187], v149 offset:49152
	ds_read_b128 v[188:191], v149 offset:50176
	ds_read_b128 v[192:195], v149 offset:51200
	ds_read_b128 v[196:199], v149 offset:52224
	ds_read_b128 v[200:203], v149 offset:53248
	ds_read_b128 v[204:207], v149 offset:54272
	ds_read_b128 v[208:211], v149 offset:55296
	ds_read_b128 v[212:215], v149 offset:56320
	global_load_lds_dwordx4 v[178:179], off
	s_add_i32 m0, s50, 0x2000
	s_add_u32 s48, s48, 0x40080
	v_lshl_add_u64 v[178:179], v[216:217], 0, s[10:11]
	s_addc_u32 s49, s49, 0
	s_add_i32 s50, s72, s54
	global_load_lds_dwordx4 v[178:179], off
	v_lshl_add_u64 v[178:179], s[48:49], 0, v[130:131]
	s_mov_b32 m0, s50
	s_nop 0
	global_load_lds_dwordx4 v[178:179], off
	v_lshl_add_u64 v[178:179], s[48:49], 0, v[128:129]
	s_add_i32 m0, s50, 0x2000
	s_nop 0
	global_load_lds_dwordx4 v[178:179], off
	v_lshl_add_u64 v[178:179], v[218:219], 0, s[10:11]
	s_mov_b32 m0, s60
	s_nop 0
	global_load_lds_dwordx4 v[178:179], off
	v_lshl_add_u64 v[178:179], v[220:221], 0, s[10:11]
	s_mov_b32 m0, s61
	s_nop 0
	global_load_lds_dwordx4 v[178:179], off
	s_waitcnt vmcnt(8)
	s_waitcnt lgkmcnt(0)
	s_barrier
	s_waitcnt lgkmcnt(0)
	v_mfma_f32_16x16x32_bf16 v[60:63], v[140:143], v[184:187], v[60:63]
	v_mfma_f32_16x16x32_bf16 v[60:63], v[150:153], v[188:191], v[60:63]
	s_setprio 1
	v_mfma_f32_16x16x32_bf16 v[56:59], v[154:157], v[184:187], v[56:59]
	v_mfma_f32_16x16x32_bf16 v[56:59], v[158:161], v[188:191], v[56:59]
	v_mfma_f32_16x16x32_bf16 v[44:47], v[140:143], v[192:195], v[44:47]
	v_mfma_f32_16x16x32_bf16 v[44:47], v[150:153], v[196:199], v[44:47]
	v_mfma_f32_16x16x32_bf16 v[40:43], v[154:157], v[192:195], v[40:43]
	v_mfma_f32_16x16x32_bf16 v[40:43], v[158:161], v[196:199], v[40:43]
	v_mfma_f32_16x16x32_bf16 v[28:31], v[140:143], v[200:203], v[28:31]
	v_mfma_f32_16x16x32_bf16 v[28:31], v[150:153], v[204:207], v[28:31]
	v_mfma_f32_16x16x32_bf16 v[24:27], v[154:157], v[200:203], v[24:27]
	v_mfma_f32_16x16x32_bf16 v[24:27], v[158:161], v[204:207], v[24:27]
	v_mfma_f32_16x16x32_bf16 v[12:15], v[140:143], v[208:211], v[12:15]
	v_mfma_f32_16x16x32_bf16 v[12:15], v[150:153], v[212:215], v[12:15]
	v_mfma_f32_16x16x32_bf16 v[8:11], v[154:157], v[208:211], v[8:11]
	v_mfma_f32_16x16x32_bf16 v[8:11], v[158:161], v[212:215], v[8:11]
	v_mfma_f32_16x16x32_bf16 v[52:55], v[162:165], v[184:187], v[52:55]
	v_mfma_f32_16x16x32_bf16 v[52:55], v[166:169], v[188:191], v[52:55]
	v_mfma_f32_16x16x32_bf16 v[48:51], v[170:173], v[184:187], v[48:51]
	v_mfma_f32_16x16x32_bf16 v[48:51], v[174:177], v[188:191], v[48:51]
	v_mfma_f32_16x16x32_bf16 v[36:39], v[162:165], v[192:195], v[36:39]
	v_mfma_f32_16x16x32_bf16 v[36:39], v[166:169], v[196:199], v[36:39]
	v_mfma_f32_16x16x32_bf16 v[32:35], v[170:173], v[192:195], v[32:35]
	v_mfma_f32_16x16x32_bf16 v[32:35], v[174:177], v[196:199], v[32:35]
	v_mfma_f32_16x16x32_bf16 v[20:23], v[162:165], v[200:203], v[20:23]
	v_mfma_f32_16x16x32_bf16 v[20:23], v[166:169], v[204:207], v[20:23]
	v_mfma_f32_16x16x32_bf16 v[16:19], v[170:173], v[200:203], v[16:19]
	v_mfma_f32_16x16x32_bf16 v[16:19], v[174:177], v[204:207], v[16:19]
	v_mfma_f32_16x16x32_bf16 v[4:7], v[162:165], v[208:211], v[4:7]
	v_mfma_f32_16x16x32_bf16 v[4:7], v[166:169], v[212:215], v[4:7]
	s_barrier
	v_mfma_f32_16x16x32_bf16 v[0:3], v[170:173], v[208:211], v[0:3]
	v_mfma_f32_16x16x32_bf16 v[0:3], v[174:177], v[212:215], v[0:3]
	s_setprio 0
	s_add_i32 s70, s70, 2
	s_add_u32 s46, s46, 0x100
	s_addc_u32 s47, s47, 0
	s_add_u32 s68, s68, 0x100
	s_addc_u32 s69, s69, 0
	s_cmp_gt_u32 s70, 13
	s_cbranch_scc0 .LBB0_1434
	s_and_b64 vcc, exec, s[12:13]
	s_cbranch_vccz .LBB0_1437
	s_barrier
	s_setprio 1
.LBB0_1437:
	v_mul_f32_e32 v151, 0xbfb8aa3b, v124
	v_exp_f32_e32 v151, v151
	v_mul_f32_e32 v154, 0xbfb8aa3b, v125
	v_exp_f32_e32 v154, v154
	v_lshl_or_b32 v142, s65, 7, v146
	v_add_f32_e32 v151, 1.0, v151
	v_rcp_f32_e32 v151, v151
	v_lshl_add_u32 v150, s44, 8, v144
	v_ashrrev_i32_e32 v143, 31, v142
	v_mov_b64_e32 v[140:141], s[22:23]
	v_mul_f32_e32 v124, v124, v151
	v_mul_f32_e32 v120, v120, v124
	v_add_f32_e32 v124, 1.0, v154
	v_mul_f32_e32 v151, 0xbfb8aa3b, v126
	v_rcp_f32_e32 v124, v124
	v_exp_f32_e32 v151, v151
	v_mul_f32_e32 v154, 0xbfb8aa3b, v127
	v_exp_f32_e32 v154, v154
	v_mul_f32_e32 v124, v125, v124
	v_add_f32_e32 v125, 1.0, v151
	v_rcp_f32_e32 v125, v125
	v_add_f32_e32 v151, 1.0, v154
	v_rcp_f32_e32 v151, v151
	v_mul_f32_e32 v121, v121, v124
	v_mul_f32_e32 v124, v126, v125
	v_mul_f32_e32 v125, 0xbfb8aa3b, v116
	v_exp_f32_e32 v125, v125
	v_mul_f32_e32 v122, v122, v124
	v_mul_f32_e32 v124, v127, v151
	v_mul_f32_e32 v123, v123, v124
	v_cvt_pk_bf16_f32 v120, v120, v121
	v_cvt_pk_bf16_f32 v121, v122, v123
	v_add_f32_e32 v122, 1.0, v125
	v_rcp_f32_e32 v122, v122
	v_mul_f32_e32 v123, 0xbfb8aa3b, v117
	v_exp_f32_e32 v123, v123
	v_mad_i64_i32 v[152:153], s[46:47], v150, s64, v[140:141]
	v_lshlrev_b64 v[142:143], 1, v[142:143]
	v_lshl_add_u64 v[152:153], v[152:153], 0, v[142:143]
	v_mul_f32_e32 v116, v116, v122
	global_store_dwordx2 v[152:153], v[120:121], off
	v_mul_f32_e32 v112, v112, v116
	v_add_f32_e32 v116, 1.0, v123
	v_mul_f32_e32 v120, 0xbfb8aa3b, v118
	v_rcp_f32_e32 v116, v116
	v_exp_f32_e32 v120, v120
	v_mul_f32_e32 v121, 0xbfb8aa3b, v119
	v_exp_f32_e32 v121, v121
	v_mul_f32_e32 v116, v117, v116
	v_add_f32_e32 v117, 1.0, v120
	v_rcp_f32_e32 v117, v117
	v_add_f32_e32 v120, 1.0, v121
	v_rcp_f32_e32 v120, v120
	v_mul_f32_e32 v113, v113, v116
	v_mul_f32_e32 v116, v118, v117
	v_mul_f32_e32 v114, v114, v116
	v_mul_f32_e32 v116, v119, v120
	v_cvt_pk_bf16_f32 v112, v112, v113
	v_mul_f32_e32 v115, v115, v116
	v_cvt_pk_bf16_f32 v113, v114, v115
	global_store_dwordx2 v[152:153], v[112:113], off offset:128
	v_mul_f32_e32 v112, 0xbfb8aa3b, v108
	v_exp_f32_e32 v114, v112
	v_mul_f32_e32 v115, 0xbfb8aa3b, v109
	v_exp_f32_e32 v115, v115
	v_or_b32_e32 v112, 16, v150
	v_add_f32_e32 v114, 1.0, v114
	v_rcp_f32_e32 v114, v114
	v_mad_i64_i32 v[112:113], s[46:47], v112, s64, v[140:141]
	v_lshl_add_u64 v[112:113], v[112:113], 0, v[142:143]
	v_mul_f32_e32 v108, v108, v114
	v_mul_f32_e32 v104, v104, v108
	v_add_f32_e32 v108, 1.0, v115
	v_mul_f32_e32 v114, 0xbfb8aa3b, v110
	v_rcp_f32_e32 v108, v108
	v_exp_f32_e32 v114, v114
	v_mul_f32_e32 v115, 0xbfb8aa3b, v111
	v_exp_f32_e32 v115, v115
	v_mul_f32_e32 v108, v109, v108
	v_add_f32_e32 v109, 1.0, v114
	v_rcp_f32_e32 v109, v109
	v_add_f32_e32 v114, 1.0, v115
	v_rcp_f32_e32 v114, v114
	v_mul_f32_e32 v105, v105, v108
	v_mul_f32_e32 v108, v110, v109
	v_mul_f32_e32 v109, 0xbfb8aa3b, v100
	v_exp_f32_e32 v109, v109
	v_mul_f32_e32 v106, v106, v108
	v_mul_f32_e32 v108, v111, v114
	v_mul_f32_e32 v107, v107, v108
	v_cvt_pk_bf16_f32 v104, v104, v105
	v_cvt_pk_bf16_f32 v105, v106, v107
	v_add_f32_e32 v106, 1.0, v109
	v_rcp_f32_e32 v106, v106
	v_mul_f32_e32 v107, 0xbfb8aa3b, v101
	v_exp_f32_e32 v107, v107
	global_store_dwordx2 v[112:113], v[104:105], off
	v_mul_f32_e32 v100, v100, v106
	v_mul_f32_e32 v96, v96, v100
	v_add_f32_e32 v100, 1.0, v107
	v_mul_f32_e32 v104, 0xbfb8aa3b, v102
	v_rcp_f32_e32 v100, v100
	v_exp_f32_e32 v104, v104
	v_mul_f32_e32 v105, 0xbfb8aa3b, v103
	v_exp_f32_e32 v105, v105
	v_mul_f32_e32 v100, v101, v100
	v_add_f32_e32 v101, 1.0, v104
	v_rcp_f32_e32 v101, v101
	v_add_f32_e32 v104, 1.0, v105
	v_rcp_f32_e32 v104, v104
	v_mul_f32_e32 v97, v97, v100
	v_mul_f32_e32 v100, v102, v101
	v_mul_f32_e32 v98, v98, v100
	v_mul_f32_e32 v100, v103, v104
	v_cvt_pk_bf16_f32 v96, v96, v97
	v_mul_f32_e32 v99, v99, v100
	v_cvt_pk_bf16_f32 v97, v98, v99
	global_store_dwordx2 v[112:113], v[96:97], off offset:128
	v_mul_f32_e32 v96, 0xbfb8aa3b, v92
	v_exp_f32_e32 v98, v96
	v_mul_f32_e32 v99, 0xbfb8aa3b, v93
	v_exp_f32_e32 v99, v99
	v_or_b32_e32 v96, 32, v150
	v_add_f32_e32 v98, 1.0, v98
	v_rcp_f32_e32 v98, v98
	v_mad_i64_i32 v[96:97], s[46:47], v96, s64, v[140:141]
	v_lshl_add_u64 v[96:97], v[96:97], 0, v[142:143]
	v_mul_f32_e32 v92, v92, v98
	v_mul_f32_e32 v88, v88, v92
	v_add_f32_e32 v92, 1.0, v99
	v_mul_f32_e32 v98, 0xbfb8aa3b, v94
	v_rcp_f32_e32 v92, v92
	v_exp_f32_e32 v98, v98
	v_mul_f32_e32 v99, 0xbfb8aa3b, v95
	v_exp_f32_e32 v99, v99
	v_mul_f32_e32 v92, v93, v92
	v_add_f32_e32 v93, 1.0, v98
	v_rcp_f32_e32 v93, v93
	v_add_f32_e32 v98, 1.0, v99
	v_rcp_f32_e32 v98, v98
	v_mul_f32_e32 v89, v89, v92
	v_mul_f32_e32 v92, v94, v93
	v_mul_f32_e32 v93, 0xbfb8aa3b, v84
	v_exp_f32_e32 v93, v93
	v_mul_f32_e32 v90, v90, v92
	v_mul_f32_e32 v92, v95, v98
	v_mul_f32_e32 v91, v91, v92
	v_cvt_pk_bf16_f32 v88, v88, v89
	v_cvt_pk_bf16_f32 v89, v90, v91
	v_add_f32_e32 v90, 1.0, v93
	v_rcp_f32_e32 v90, v90
	v_mul_f32_e32 v91, 0xbfb8aa3b, v85
	v_exp_f32_e32 v91, v91
	global_store_dwordx2 v[96:97], v[88:89], off
	v_mul_f32_e32 v84, v84, v90
	v_mul_f32_e32 v80, v80, v84
	v_add_f32_e32 v84, 1.0, v91
	v_mul_f32_e32 v88, 0xbfb8aa3b, v86
	v_rcp_f32_e32 v84, v84
	v_exp_f32_e32 v88, v88
	v_mul_f32_e32 v89, 0xbfb8aa3b, v87
	v_exp_f32_e32 v89, v89
	v_mul_f32_e32 v84, v85, v84
	v_add_f32_e32 v85, 1.0, v88
	v_rcp_f32_e32 v85, v85
	v_add_f32_e32 v88, 1.0, v89
	v_rcp_f32_e32 v88, v88
	v_mul_f32_e32 v81, v81, v84
	v_mul_f32_e32 v84, v86, v85
	v_mul_f32_e32 v82, v82, v84
	v_mul_f32_e32 v84, v87, v88
	v_cvt_pk_bf16_f32 v80, v80, v81
	v_mul_f32_e32 v83, v83, v84
	v_cvt_pk_bf16_f32 v81, v82, v83
	global_store_dwordx2 v[96:97], v[80:81], off offset:128
	v_mul_f32_e32 v80, 0xbfb8aa3b, v76
	v_exp_f32_e32 v82, v80
	v_mul_f32_e32 v83, 0xbfb8aa3b, v77
	v_exp_f32_e32 v83, v83
	v_or_b32_e32 v80, 48, v150
	v_add_f32_e32 v82, 1.0, v82
	v_rcp_f32_e32 v82, v82
	v_mad_i64_i32 v[80:81], s[46:47], v80, s64, v[140:141]
	v_lshl_add_u64 v[80:81], v[80:81], 0, v[142:143]
	v_mul_f32_e32 v76, v76, v82
	v_mul_f32_e32 v72, v72, v76
	v_add_f32_e32 v76, 1.0, v83
	v_mul_f32_e32 v82, 0xbfb8aa3b, v78
	v_rcp_f32_e32 v76, v76
	v_exp_f32_e32 v82, v82
	v_mul_f32_e32 v83, 0xbfb8aa3b, v79
	v_exp_f32_e32 v83, v83
	v_mul_f32_e32 v76, v77, v76
	v_add_f32_e32 v77, 1.0, v82
	v_rcp_f32_e32 v77, v77
	v_add_f32_e32 v82, 1.0, v83
	v_rcp_f32_e32 v82, v82
	v_mul_f32_e32 v73, v73, v76
	v_mul_f32_e32 v76, v78, v77
	v_mul_f32_e32 v77, 0xbfb8aa3b, v68
	v_exp_f32_e32 v77, v77
	v_mul_f32_e32 v74, v74, v76
	v_mul_f32_e32 v76, v79, v82
	v_mul_f32_e32 v75, v75, v76
	v_cvt_pk_bf16_f32 v72, v72, v73
	v_cvt_pk_bf16_f32 v73, v74, v75
	v_add_f32_e32 v74, 1.0, v77
	v_rcp_f32_e32 v74, v74
	v_mul_f32_e32 v75, 0xbfb8aa3b, v69
	v_exp_f32_e32 v75, v75
	global_store_dwordx2 v[80:81], v[72:73], off
	v_mul_f32_e32 v68, v68, v74
	v_mul_f32_e32 v64, v64, v68
	v_add_f32_e32 v68, 1.0, v75
	v_mul_f32_e32 v72, 0xbfb8aa3b, v70
	v_rcp_f32_e32 v68, v68
	v_exp_f32_e32 v72, v72
	v_mul_f32_e32 v73, 0xbfb8aa3b, v71
	v_exp_f32_e32 v73, v73
	v_mul_f32_e32 v68, v69, v68
	v_add_f32_e32 v69, 1.0, v72
	v_rcp_f32_e32 v69, v69
	v_add_f32_e32 v72, 1.0, v73
	v_rcp_f32_e32 v72, v72
	v_mul_f32_e32 v65, v65, v68
	v_mul_f32_e32 v68, v70, v69
	v_mul_f32_e32 v66, v66, v68
	v_mul_f32_e32 v68, v71, v72
	v_cvt_pk_bf16_f32 v64, v64, v65
	v_mul_f32_e32 v67, v67, v68
	v_cvt_pk_bf16_f32 v65, v66, v67
	global_store_dwordx2 v[80:81], v[64:65], off offset:128
	v_mul_f32_e32 v64, 0xbfb8aa3b, v60
	v_exp_f32_e32 v66, v64
	v_mul_f32_e32 v67, 0xbfb8aa3b, v61
	v_exp_f32_e32 v67, v67
	v_add_u32_e32 v64, 0x80, v150
	v_add_f32_e32 v66, 1.0, v66
	v_rcp_f32_e32 v66, v66
	v_mad_i64_i32 v[64:65], s[46:47], v64, s64, v[140:141]
	v_lshl_add_u64 v[64:65], v[64:65], 0, v[142:143]
	v_mul_f32_e32 v60, v60, v66
	v_mul_f32_e32 v56, v56, v60
	v_add_f32_e32 v60, 1.0, v67
	v_mul_f32_e32 v66, 0xbfb8aa3b, v62
	v_rcp_f32_e32 v60, v60
	v_exp_f32_e32 v66, v66
	v_mul_f32_e32 v67, 0xbfb8aa3b, v63
	v_exp_f32_e32 v67, v67
	v_mul_f32_e32 v60, v61, v60
	v_add_f32_e32 v61, 1.0, v66
	v_rcp_f32_e32 v61, v61
	v_add_f32_e32 v66, 1.0, v67
	v_rcp_f32_e32 v66, v66
	v_mul_f32_e32 v57, v57, v60
	v_mul_f32_e32 v60, v62, v61
	v_mul_f32_e32 v61, 0xbfb8aa3b, v52
	v_exp_f32_e32 v61, v61
	v_mul_f32_e32 v58, v58, v60
	v_mul_f32_e32 v60, v63, v66
	v_mul_f32_e32 v59, v59, v60
	v_cvt_pk_bf16_f32 v56, v56, v57
	v_cvt_pk_bf16_f32 v57, v58, v59
	v_add_f32_e32 v58, 1.0, v61
	v_rcp_f32_e32 v58, v58
	v_mul_f32_e32 v59, 0xbfb8aa3b, v53
	v_exp_f32_e32 v59, v59
	global_store_dwordx2 v[64:65], v[56:57], off
	v_mul_f32_e32 v52, v52, v58
	v_mul_f32_e32 v48, v48, v52
	v_add_f32_e32 v52, 1.0, v59
	v_mul_f32_e32 v56, 0xbfb8aa3b, v54
	v_rcp_f32_e32 v52, v52
	v_exp_f32_e32 v56, v56
	v_mul_f32_e32 v57, 0xbfb8aa3b, v55
	v_exp_f32_e32 v57, v57
	v_mul_f32_e32 v52, v53, v52
	v_add_f32_e32 v53, 1.0, v56
	v_rcp_f32_e32 v53, v53
	v_add_f32_e32 v56, 1.0, v57
	v_rcp_f32_e32 v56, v56
	v_mul_f32_e32 v49, v49, v52
	v_mul_f32_e32 v52, v54, v53
	v_mul_f32_e32 v50, v50, v52
	v_mul_f32_e32 v52, v55, v56
	v_cvt_pk_bf16_f32 v48, v48, v49
	v_mul_f32_e32 v51, v51, v52
	v_cvt_pk_bf16_f32 v49, v50, v51
	global_store_dwordx2 v[64:65], v[48:49], off offset:128
	v_mul_f32_e32 v48, 0xbfb8aa3b, v44
	v_exp_f32_e32 v50, v48
	v_mul_f32_e32 v51, 0xbfb8aa3b, v45
	v_exp_f32_e32 v51, v51
	v_add_u32_e32 v48, 0x90, v150
	v_add_f32_e32 v50, 1.0, v50
	v_rcp_f32_e32 v50, v50
	v_mad_i64_i32 v[48:49], s[46:47], v48, s64, v[140:141]
	v_lshl_add_u64 v[48:49], v[48:49], 0, v[142:143]
	v_mul_f32_e32 v44, v44, v50
	v_mul_f32_e32 v40, v40, v44
	v_add_f32_e32 v44, 1.0, v51
	v_mul_f32_e32 v50, 0xbfb8aa3b, v46
	v_rcp_f32_e32 v44, v44
	v_exp_f32_e32 v50, v50
	v_mul_f32_e32 v51, 0xbfb8aa3b, v47
	v_exp_f32_e32 v51, v51
	v_mul_f32_e32 v44, v45, v44
	v_add_f32_e32 v45, 1.0, v50
	v_rcp_f32_e32 v45, v45
	v_add_f32_e32 v50, 1.0, v51
	v_rcp_f32_e32 v50, v50
	v_mul_f32_e32 v41, v41, v44
	v_mul_f32_e32 v44, v46, v45
	v_mul_f32_e32 v45, 0xbfb8aa3b, v36
	v_exp_f32_e32 v45, v45
	v_mul_f32_e32 v42, v42, v44
	v_mul_f32_e32 v44, v47, v50
	v_mul_f32_e32 v43, v43, v44
	v_cvt_pk_bf16_f32 v40, v40, v41
	v_cvt_pk_bf16_f32 v41, v42, v43
	v_add_f32_e32 v42, 1.0, v45
	v_rcp_f32_e32 v42, v42
	v_mul_f32_e32 v43, 0xbfb8aa3b, v37
	v_exp_f32_e32 v43, v43
	global_store_dwordx2 v[48:49], v[40:41], off
	v_mul_f32_e32 v36, v36, v42
	v_mul_f32_e32 v32, v32, v36
	v_add_f32_e32 v36, 1.0, v43
	v_mul_f32_e32 v40, 0xbfb8aa3b, v38
	v_rcp_f32_e32 v36, v36
	v_exp_f32_e32 v40, v40
	v_mul_f32_e32 v41, 0xbfb8aa3b, v39
	v_exp_f32_e32 v41, v41
	v_mul_f32_e32 v36, v37, v36
	v_add_f32_e32 v37, 1.0, v40
	v_rcp_f32_e32 v37, v37
	v_add_f32_e32 v40, 1.0, v41
	v_rcp_f32_e32 v40, v40
	v_mul_f32_e32 v33, v33, v36
	v_mul_f32_e32 v36, v38, v37
	v_mul_f32_e32 v34, v34, v36
	v_mul_f32_e32 v36, v39, v40
	v_cvt_pk_bf16_f32 v32, v32, v33
	v_mul_f32_e32 v35, v35, v36
	v_cvt_pk_bf16_f32 v33, v34, v35
	global_store_dwordx2 v[48:49], v[32:33], off offset:128
	v_mul_f32_e32 v32, 0xbfb8aa3b, v28
	v_exp_f32_e32 v34, v32
	v_mul_f32_e32 v35, 0xbfb8aa3b, v29
	v_exp_f32_e32 v35, v35
	v_add_u32_e32 v32, 0xa0, v150
	v_add_f32_e32 v34, 1.0, v34
	v_rcp_f32_e32 v34, v34
	v_mad_i64_i32 v[32:33], s[46:47], v32, s64, v[140:141]
	v_lshl_add_u64 v[32:33], v[32:33], 0, v[142:143]
	v_mul_f32_e32 v28, v28, v34
	v_mul_f32_e32 v24, v24, v28
	v_add_f32_e32 v28, 1.0, v35
	v_mul_f32_e32 v34, 0xbfb8aa3b, v30
	v_rcp_f32_e32 v28, v28
	v_exp_f32_e32 v34, v34
	v_mul_f32_e32 v35, 0xbfb8aa3b, v31
	v_exp_f32_e32 v35, v35
	v_mul_f32_e32 v28, v29, v28
	v_add_f32_e32 v29, 1.0, v34
	v_rcp_f32_e32 v29, v29
	v_add_f32_e32 v34, 1.0, v35
	v_rcp_f32_e32 v34, v34
	v_mul_f32_e32 v25, v25, v28
	v_mul_f32_e32 v28, v30, v29
	v_mul_f32_e32 v29, 0xbfb8aa3b, v20
	v_exp_f32_e32 v29, v29
	v_mul_f32_e32 v26, v26, v28
	v_mul_f32_e32 v28, v31, v34
	v_mul_f32_e32 v27, v27, v28
	v_cvt_pk_bf16_f32 v24, v24, v25
	v_cvt_pk_bf16_f32 v25, v26, v27
	v_add_f32_e32 v26, 1.0, v29
	v_rcp_f32_e32 v26, v26
	v_mul_f32_e32 v27, 0xbfb8aa3b, v21
	v_exp_f32_e32 v27, v27
	global_store_dwordx2 v[32:33], v[24:25], off
	v_mul_f32_e32 v20, v20, v26
	v_mul_f32_e32 v16, v16, v20
	v_add_f32_e32 v20, 1.0, v27
	v_mul_f32_e32 v24, 0xbfb8aa3b, v22
	v_rcp_f32_e32 v20, v20
	v_exp_f32_e32 v24, v24
	v_mul_f32_e32 v25, 0xbfb8aa3b, v23
	v_exp_f32_e32 v25, v25
	v_mul_f32_e32 v20, v21, v20
	v_add_f32_e32 v21, 1.0, v24
	v_rcp_f32_e32 v21, v21
	v_add_f32_e32 v24, 1.0, v25
	v_rcp_f32_e32 v24, v24
	v_mul_f32_e32 v17, v17, v20
	v_mul_f32_e32 v20, v22, v21
	v_mul_f32_e32 v18, v18, v20
	v_mul_f32_e32 v20, v23, v24
	v_cvt_pk_bf16_f32 v16, v16, v17
	v_mul_f32_e32 v19, v19, v20
	v_cvt_pk_bf16_f32 v17, v18, v19
	global_store_dwordx2 v[32:33], v[16:17], off offset:128
	v_mul_f32_e32 v16, 0xbfb8aa3b, v12
	v_exp_f32_e32 v18, v16
	v_mul_f32_e32 v19, 0xbfb8aa3b, v13
	v_exp_f32_e32 v19, v19
	v_add_u32_e32 v16, 0xb0, v150
	v_add_f32_e32 v18, 1.0, v18
	v_rcp_f32_e32 v18, v18
	v_mad_i64_i32 v[16:17], s[46:47], v16, s64, v[140:141]
	v_lshl_add_u64 v[16:17], v[16:17], 0, v[142:143]
	v_mul_f32_e32 v12, v12, v18
	v_mul_f32_e32 v8, v8, v12
	v_add_f32_e32 v12, 1.0, v19
	v_mul_f32_e32 v18, 0xbfb8aa3b, v14
	v_rcp_f32_e32 v12, v12
	v_exp_f32_e32 v18, v18
	v_mul_f32_e32 v19, 0xbfb8aa3b, v15
	v_exp_f32_e32 v19, v19
	v_mul_f32_e32 v12, v13, v12
	v_add_f32_e32 v13, 1.0, v18
	v_rcp_f32_e32 v13, v13
	v_add_f32_e32 v18, 1.0, v19
	v_rcp_f32_e32 v18, v18
	v_mul_f32_e32 v9, v9, v12
	v_mul_f32_e32 v12, v14, v13
	v_mul_f32_e32 v13, 0xbfb8aa3b, v4
	v_exp_f32_e32 v13, v13
	v_mul_f32_e32 v10, v10, v12
	v_mul_f32_e32 v12, v15, v18
	v_mul_f32_e32 v11, v11, v12
	v_cvt_pk_bf16_f32 v8, v8, v9
	v_cvt_pk_bf16_f32 v9, v10, v11
	v_add_f32_e32 v10, 1.0, v13
	v_rcp_f32_e32 v10, v10
	v_mul_f32_e32 v11, 0xbfb8aa3b, v5
	v_exp_f32_e32 v11, v11
	global_store_dwordx2 v[16:17], v[8:9], off
	v_mul_f32_e32 v4, v4, v10
	v_mul_f32_e32 v0, v0, v4
	v_add_f32_e32 v4, 1.0, v11
	v_mul_f32_e32 v8, 0xbfb8aa3b, v6
	v_rcp_f32_e32 v4, v4
	v_exp_f32_e32 v8, v8
	v_mul_f32_e32 v9, 0xbfb8aa3b, v7
	v_exp_f32_e32 v9, v9
	v_mul_f32_e32 v4, v5, v4
	v_add_f32_e32 v5, 1.0, v8
	v_rcp_f32_e32 v5, v5
	v_add_f32_e32 v8, 1.0, v9
	v_rcp_f32_e32 v8, v8
	v_mul_f32_e32 v1, v1, v4
	v_mul_f32_e32 v4, v6, v5
	v_mul_f32_e32 v2, v2, v4
	v_mul_f32_e32 v4, v7, v8
	s_andn2_b64 vcc, exec, s[8:9]
	s_mov_b64 s[8:9], -1
	v_mul_f32_e32 v3, v3, v4
	v_cvt_pk_bf16_f32 v0, v0, v1
	v_cvt_pk_bf16_f32 v1, v2, v3
	global_store_dwordx2 v[16:17], v[0:1], off offset:128
	s_setprio 0
	s_cbranch_vccnz .LBB0_1430
	s_andn2_b64 vcc, exec, s[0:1]
	s_cbranch_vccnz .LBB0_1429
	s_barrier
	s_branch .LBB0_1429

.Lmid_gemm12:
	s_add_i32 s77, 0, 0x18000
	s_add_i32 s79, 0, 0x1c000
	v_add_u32_e32 v164, s77, v147
	v_add_u32_e32 v181, s79, v147
	ds_read_b128 v[152:155], v164
	ds_read_b128 v[156:159], v164 offset:1024
	ds_read_b128 v[160:163], v164 offset:2048
	ds_read_b128 v[164:167], v164 offset:3072
	ds_read_b128 v[168:171], v181
	ds_read_b128 v[172:175], v181 offset:1024
	ds_read_b128 v[176:179], v181 offset:2048
	ds_read_b128 v[184:187], v181 offset:3072
	s_add_u32 s46, s52, 0xb0000
	s_addc_u32 s47, s53, 0
	s_mov_b32 m0, s59
	v_lshl_add_u64 v[226:227], s[46:47], 0, v[128:129]
	ds_read_b128 v[188:191], v151 offset:32768
	ds_read_b128 v[192:195], v151 offset:33792
	ds_read_b128 v[196:199], v151 offset:34816
	ds_read_b128 v[200:203], v151 offset:35840
	ds_read_b128 v[204:207], v151 offset:36864
	ds_read_b128 v[208:211], v151 offset:37888
	ds_read_b128 v[212:215], v151 offset:38912
	ds_read_b128 v[216:219], v151 offset:39936
	global_load_lds_dwordx4 v[226:227], off
	v_lshl_add_u64 v[226:227], s[46:47], 0, v[132:133]
	s_mov_b32 m0, s60
	s_nop 0
	global_load_lds_dwordx4 v[226:227], off
	s_waitcnt vmcnt(8)
	s_waitcnt lgkmcnt(0)
	s_barrier
	s_waitcnt lgkmcnt(0)
	v_mfma_f32_16x16x32_bf16 v[124:127], v[152:155], v[188:191], v[124:127]
	v_mfma_f32_16x16x32_bf16 v[124:127], v[156:159], v[192:195], v[124:127]
	s_setprio 1
	v_mfma_f32_16x16x32_bf16 v[120:123], v[160:163], v[188:191], v[120:123]
	v_mfma_f32_16x16x32_bf16 v[120:123], v[164:167], v[192:195], v[120:123]
	v_mfma_f32_16x16x32_bf16 v[116:119], v[152:155], v[196:199], v[116:119]
	v_mfma_f32_16x16x32_bf16 v[116:119], v[156:159], v[200:203], v[116:119]
	v_mfma_f32_16x16x32_bf16 v[108:111], v[160:163], v[196:199], v[108:111]
	v_mfma_f32_16x16x32_bf16 v[108:111], v[164:167], v[200:203], v[108:111]
	v_mfma_f32_16x16x32_bf16 v[100:103], v[152:155], v[204:207], v[100:103]
	v_mfma_f32_16x16x32_bf16 v[100:103], v[156:159], v[208:211], v[100:103]
	v_mfma_f32_16x16x32_bf16 v[92:95], v[160:163], v[204:207], v[92:95]
	v_mfma_f32_16x16x32_bf16 v[92:95], v[164:167], v[208:211], v[92:95]
	v_mfma_f32_16x16x32_bf16 v[84:87], v[152:155], v[212:215], v[84:87]
	v_mfma_f32_16x16x32_bf16 v[84:87], v[156:159], v[216:219], v[84:87]
	v_mfma_f32_16x16x32_bf16 v[76:79], v[160:163], v[212:215], v[76:79]
	v_mfma_f32_16x16x32_bf16 v[76:79], v[164:167], v[216:219], v[76:79]
	v_mfma_f32_16x16x32_bf16 v[112:115], v[168:171], v[188:191], v[112:115]
	v_mfma_f32_16x16x32_bf16 v[112:115], v[172:175], v[192:195], v[112:115]
	v_mfma_f32_16x16x32_bf16 v[104:107], v[176:179], v[188:191], v[104:107]
	v_mfma_f32_16x16x32_bf16 v[104:107], v[184:187], v[192:195], v[104:107]
	v_mfma_f32_16x16x32_bf16 v[96:99], v[168:171], v[196:199], v[96:99]
	v_mfma_f32_16x16x32_bf16 v[96:99], v[172:175], v[200:203], v[96:99]
	v_mfma_f32_16x16x32_bf16 v[88:91], v[176:179], v[196:199], v[88:91]
	v_mfma_f32_16x16x32_bf16 v[88:91], v[184:187], v[200:203], v[88:91]
	v_mfma_f32_16x16x32_bf16 v[80:83], v[168:171], v[204:207], v[80:83]
	v_mfma_f32_16x16x32_bf16 v[80:83], v[172:175], v[208:211], v[80:83]
	v_mfma_f32_16x16x32_bf16 v[72:75], v[176:179], v[204:207], v[72:75]
	v_mfma_f32_16x16x32_bf16 v[72:75], v[184:187], v[208:211], v[72:75]
	v_mfma_f32_16x16x32_bf16 v[68:71], v[168:171], v[212:215], v[68:71]
	v_mfma_f32_16x16x32_bf16 v[68:71], v[172:175], v[216:219], v[68:71]
	s_barrier
	v_mfma_f32_16x16x32_bf16 v[64:67], v[176:179], v[212:215], v[64:67]
	v_mfma_f32_16x16x32_bf16 v[64:67], v[184:187], v[216:219], v[64:67]
	s_setprio 0
	s_add_i32 s46, s77, s56
	v_lshl_add_u64 v[144:145], v[144:145], 0, s[10:11]
	s_mov_b32 m0, s46
	ds_read_b128 v[188:191], v151 offset:49152
	ds_read_b128 v[192:195], v151 offset:50176
	ds_read_b128 v[196:199], v151 offset:51200
	ds_read_b128 v[200:203], v151 offset:52224
	ds_read_b128 v[204:207], v151 offset:53248
	ds_read_b128 v[208:211], v151 offset:54272
	ds_read_b128 v[212:215], v151 offset:55296
	ds_read_b128 v[216:219], v151 offset:56320
	global_load_lds_dwordx4 v[144:145], off
	s_add_i32 m0, s46, 0x2000
	s_add_u32 s46, s50, 0xb0080
	v_lshl_add_u64 v[144:145], v[220:221], 0, s[10:11]
	s_addc_u32 s47, s51, 0
	s_add_i32 s50, s79, s56
	global_load_lds_dwordx4 v[144:145], off
	v_lshl_add_u64 v[144:145], s[46:47], 0, v[130:131]
	s_mov_b32 m0, s50
	s_nop 0
	global_load_lds_dwordx4 v[144:145], off
	v_lshl_add_u64 v[144:145], s[46:47], 0, v[134:135]
	s_add_i32 m0, s50, 0x2000
	s_nop 0
	global_load_lds_dwordx4 v[144:145], off
	v_lshl_add_u64 v[144:145], v[222:223], 0, s[10:11]
	s_mov_b32 m0, s62
	s_nop 0
	global_load_lds_dwordx4 v[144:145], off
	v_lshl_add_u64 v[144:145], v[224:225], 0, s[10:11]
	s_mov_b32 m0, s63
	s_nop 0
	global_load_lds_dwordx4 v[144:145], off
	s_waitcnt vmcnt(8)
	s_waitcnt lgkmcnt(0)
	s_barrier
	s_waitcnt lgkmcnt(0)
	v_mfma_f32_16x16x32_bf16 v[60:63], v[152:155], v[188:191], v[60:63]
	v_mfma_f32_16x16x32_bf16 v[60:63], v[156:159], v[192:195], v[60:63]
	s_setprio 1
	v_mfma_f32_16x16x32_bf16 v[56:59], v[160:163], v[188:191], v[56:59]
	v_mfma_f32_16x16x32_bf16 v[56:59], v[164:167], v[192:195], v[56:59]
	v_mfma_f32_16x16x32_bf16 v[52:55], v[152:155], v[196:199], v[52:55]
	v_mfma_f32_16x16x32_bf16 v[52:55], v[156:159], v[200:203], v[52:55]
	v_mfma_f32_16x16x32_bf16 v[44:47], v[160:163], v[196:199], v[44:47]
	v_mfma_f32_16x16x32_bf16 v[44:47], v[164:167], v[200:203], v[44:47]
	v_mfma_f32_16x16x32_bf16 v[36:39], v[152:155], v[204:207], v[36:39]
	v_mfma_f32_16x16x32_bf16 v[36:39], v[156:159], v[208:211], v[36:39]
	v_mfma_f32_16x16x32_bf16 v[28:31], v[160:163], v[204:207], v[28:31]
	v_mfma_f32_16x16x32_bf16 v[28:31], v[164:167], v[208:211], v[28:31]
	v_mfma_f32_16x16x32_bf16 v[20:23], v[152:155], v[212:215], v[20:23]
	v_mfma_f32_16x16x32_bf16 v[20:23], v[156:159], v[216:219], v[20:23]
	v_mfma_f32_16x16x32_bf16 v[12:15], v[160:163], v[212:215], v[12:15]
	v_mfma_f32_16x16x32_bf16 v[12:15], v[164:167], v[216:219], v[12:15]
	v_mfma_f32_16x16x32_bf16 v[48:51], v[168:171], v[188:191], v[48:51]
	v_mfma_f32_16x16x32_bf16 v[48:51], v[172:175], v[192:195], v[48:51]
	v_mfma_f32_16x16x32_bf16 v[40:43], v[176:179], v[188:191], v[40:43]
	v_mfma_f32_16x16x32_bf16 v[40:43], v[184:187], v[192:195], v[40:43]
	v_mfma_f32_16x16x32_bf16 v[32:35], v[168:171], v[196:199], v[32:35]
	v_mfma_f32_16x16x32_bf16 v[32:35], v[172:175], v[200:203], v[32:35]
	v_mfma_f32_16x16x32_bf16 v[24:27], v[176:179], v[196:199], v[24:27]
	v_mfma_f32_16x16x32_bf16 v[24:27], v[184:187], v[200:203], v[24:27]
	v_mfma_f32_16x16x32_bf16 v[16:19], v[168:171], v[204:207], v[16:19]
	v_mfma_f32_16x16x32_bf16 v[16:19], v[172:175], v[208:211], v[16:19]
	v_mfma_f32_16x16x32_bf16 v[8:11], v[176:179], v[204:207], v[8:11]
	v_mfma_f32_16x16x32_bf16 v[8:11], v[184:187], v[208:211], v[8:11]
	v_mfma_f32_16x16x32_bf16 v[4:7], v[168:171], v[212:215], v[4:7]
	v_mfma_f32_16x16x32_bf16 v[4:7], v[172:175], v[216:219], v[4:7]
	s_barrier
	v_mfma_f32_16x16x32_bf16 v[0:3], v[176:179], v[212:215], v[0:3]
	v_mfma_f32_16x16x32_bf16 v[0:3], v[184:187], v[216:219], v[0:3]
	s_setprio 0
	s_add_i32 s76, s76, 2
	s_add_u32 s74, s74, 0x100
	s_addc_u32 s75, s75, 0
	s_cmp_gt_u32 s76, 41
	s_mov_b64 s[46:47], s[48:49]
	s_cbranch_scc0 .LBB0_1514
	s_and_b64 vcc, exec, s[12:13]
	s_cbranch_vccz .LBB0_1517
	s_barrier
	s_setprio 1
.LBB0_1517:
	v_lshl_add_u32 v152, s72, 8, v146
	v_lshl_or_b32 v144, s73, 8, v148
	v_ashrrev_i32_e32 v145, 31, v144
	v_ashrrev_i32_e32 v153, 31, v152
	v_lshl_add_u64 v[154:155], v[144:145], 1, s[24:25]
	v_lshlrev_b64 v[144:145], 11, v[152:153]
	v_lshl_add_u64 v[144:145], v[154:155], 0, v[144:145]
	s_nop 15
	s_nop 7
	v_cvt_pk_bf16_f32 v124, v124, v125
	v_cvt_pk_bf16_f32 v125, v126, v127
	v_cvt_pk_bf16_f32 v126, v120, v121
	v_cvt_pk_bf16_f32 v127, v122, v123
	global_store_dwordx4 v[144:145], v[124:127], off
	v_cvt_pk_bf16_f32 v112, v112, v113
	v_cvt_pk_bf16_f32 v113, v114, v115
	v_cvt_pk_bf16_f32 v114, v104, v105
	v_or_b32_e32 v104, 16, v152
	v_ashrrev_i32_e32 v105, 31, v104
	v_lshlrev_b64 v[104:105], 11, v[104:105]
	v_cvt_pk_bf16_f32 v115, v106, v107
	global_store_dwordx4 v[144:145], v[112:115], off offset:256
	s_nop 1
	v_lshl_add_u64 v[112:113], v[154:155], 0, v[104:105]
	v_cvt_pk_bf16_f32 v104, v116, v117
	v_cvt_pk_bf16_f32 v105, v118, v119
	v_cvt_pk_bf16_f32 v106, v108, v109
	v_cvt_pk_bf16_f32 v107, v110, v111
	global_store_dwordx4 v[112:113], v[104:107], off
	v_cvt_pk_bf16_f32 v96, v96, v97
	v_cvt_pk_bf16_f32 v97, v98, v99
	v_cvt_pk_bf16_f32 v98, v88, v89
	v_or_b32_e32 v88, 32, v152
	v_ashrrev_i32_e32 v89, 31, v88
	v_lshlrev_b64 v[88:89], 11, v[88:89]
	v_cvt_pk_bf16_f32 v99, v90, v91
	global_store_dwordx4 v[112:113], v[96:99], off offset:256
	s_nop 1
	v_lshl_add_u64 v[96:97], v[154:155], 0, v[88:89]
	v_cvt_pk_bf16_f32 v88, v100, v101
	v_cvt_pk_bf16_f32 v89, v102, v103
	v_cvt_pk_bf16_f32 v90, v92, v93
	v_cvt_pk_bf16_f32 v91, v94, v95
	global_store_dwordx4 v[96:97], v[88:91], off
	v_cvt_pk_bf16_f32 v80, v80, v81
	v_cvt_pk_bf16_f32 v81, v82, v83
	v_cvt_pk_bf16_f32 v82, v72, v73
	v_or_b32_e32 v72, 48, v152
	v_ashrrev_i32_e32 v73, 31, v72
	v_lshlrev_b64 v[72:73], 11, v[72:73]
	v_cvt_pk_bf16_f32 v83, v74, v75
	global_store_dwordx4 v[96:97], v[80:83], off offset:256
	s_nop 1
	v_lshl_add_u64 v[80:81], v[154:155], 0, v[72:73]
	v_cvt_pk_bf16_f32 v72, v84, v85
	v_cvt_pk_bf16_f32 v73, v86, v87
	v_cvt_pk_bf16_f32 v74, v76, v77
	v_cvt_pk_bf16_f32 v75, v78, v79
	global_store_dwordx4 v[80:81], v[72:75], off
	v_cvt_pk_bf16_f32 v68, v68, v69
	v_cvt_pk_bf16_f32 v69, v70, v71
	v_cvt_pk_bf16_f32 v70, v64, v65
	v_cvt_pk_bf16_f32 v71, v66, v67
	global_store_dwordx4 v[80:81], v[68:71], off offset:256
	v_cvt_pk_bf16_f32 v60, v60, v61
	v_cvt_pk_bf16_f32 v61, v62, v63
	v_cvt_pk_bf16_f32 v62, v56, v57
	v_add_co_u32_e32 v56, vcc, s66, v144
	v_lshl_add_u64 v[64:65], v[144:145], 0, s[16:17]
	s_nop 0
	v_addc_co_u32_e32 v57, vcc, 0, v145, vcc
	v_cvt_pk_bf16_f32 v63, v58, v59
	global_store_dwordx4 v[56:57], v[60:63], off
	v_cvt_pk_bf16_f32 v48, v48, v49
	v_cvt_pk_bf16_f32 v49, v50, v51
	v_cvt_pk_bf16_f32 v50, v40, v41
	v_cvt_pk_bf16_f32 v51, v42, v43
	global_store_dwordx4 v[64:65], v[48:51], off offset:256
	v_cvt_pk_bf16_f32 v40, v52, v53
	v_cvt_pk_bf16_f32 v41, v54, v55
	v_cvt_pk_bf16_f32 v42, v44, v45
	v_add_co_u32_e32 v44, vcc, s67, v144
	s_nop 0
	v_lshl_add_u64 v[48:49], v[144:145], 0, s[18:19]
	v_addc_co_u32_e32 v45, vcc, 0, v145, vcc
	v_cvt_pk_bf16_f32 v43, v46, v47
	global_store_dwordx4 v[44:45], v[40:43], off
	v_cvt_pk_bf16_f32 v32, v32, v33
	v_cvt_pk_bf16_f32 v33, v34, v35
	v_cvt_pk_bf16_f32 v34, v24, v25
	v_cvt_pk_bf16_f32 v35, v26, v27
	global_store_dwordx4 v[48:49], v[32:35], off offset:256
	v_cvt_pk_bf16_f32 v24, v36, v37
	v_cvt_pk_bf16_f32 v25, v38, v39
	v_cvt_pk_bf16_f32 v26, v28, v29
	v_add_co_u32_e32 v28, vcc, s68, v144
	s_nop 0
	v_lshl_add_u64 v[32:33], v[144:145], 0, s[30:31]
	v_addc_co_u32_e32 v29, vcc, 0, v145, vcc
	v_cvt_pk_bf16_f32 v27, v30, v31
	global_store_dwordx4 v[28:29], v[24:27], off
	v_cvt_pk_bf16_f32 v16, v16, v17
	v_cvt_pk_bf16_f32 v17, v18, v19
	v_cvt_pk_bf16_f32 v18, v8, v9
	v_cvt_pk_bf16_f32 v19, v10, v11
	global_store_dwordx4 v[32:33], v[16:19], off offset:256
	v_cvt_pk_bf16_f32 v8, v20, v21
	v_cvt_pk_bf16_f32 v9, v22, v23
	v_cvt_pk_bf16_f32 v10, v12, v13
	v_add_co_u32_e32 v12, vcc, s69, v144
	s_nop 0
	v_lshl_add_u64 v[16:17], v[144:145], 0, s[36:37]
	v_addc_co_u32_e32 v13, vcc, 0, v145, vcc
	s_and_b64 vcc, exec, s[6:7]
	s_mov_b64 s[6:7], -1
	v_cvt_pk_bf16_f32 v11, v14, v15
	global_store_dwordx4 v[12:13], v[8:11], off
	v_cvt_pk_bf16_f32 v4, v4, v5
	v_cvt_pk_bf16_f32 v5, v6, v7
	v_cvt_pk_bf16_f32 v6, v0, v1
	v_cvt_pk_bf16_f32 v7, v2, v3
	global_store_dwordx4 v[16:17], v[4:7], off offset:256
	s_setprio 0
	s_cbranch_vccnz .LBB0_1502
	s_andn2_b64 vcc, exec, s[0:1]
	s_cbranch_vccnz .LBB0_1501
	s_barrier
	s_branch .LBB0_1501
